# row-statistics code of the fused epilogues (7 passes): SLP-packed v_pk_add/mul split into their scalar ops, register copies forwarded and removed, mov+fmac pairs turned into v_fmamk (same arithmetic a
# speedup vs baseline: 1.0107x; 1.0041x over previous
.LBB0_570:
	v_add_f32_e32 v130, v127, v126
	v_add_f32_e32 v131, v128, v129
	v_add_f32_e32 v132, v123, v122
	v_add_f32_e32 v133, v124, v125
	v_add_f32_e32 v130, v130, v131
	v_add_f32_e32 v133, v132, v133
	v_add_f32_e32 v132, v132, v132
	v_add_f32_e32 v131, 0, v130
	v_add_f32_e32 v135, v118, v119
	v_add_f32_e32 v137, v120, v121
	v_mov_b32_e32 v136, v115
	v_add_f32_e32 v134, v114, v115
	v_add_f32_e32 v135, v135, v137
	v_add_f32_e32 v130, v116, v117
	v_add_f32_e32 v131, v133, v131
	v_add_f32_e32 v130, v134, v130
	v_add_f32_e32 v131, v135, v131
	v_add_f32_e32 v130, v130, v131
	v_mov_b32_e32 v131, v130
	s_nop 1
	v_permlane16_swap_b32_e32 v130, v131
	s_lshl_b32 s0, s17, 3
	s_add_i32 s27, s0, 0
	s_barrier
	s_waitcnt lgkmcnt(0)
	v_add_f32_e32 v130, v130, v131
	v_mov_b32_e32 v131, v130
	s_nop 1
	v_permlane32_swap_b32_e32 v130, v131
	s_waitcnt lgkmcnt(0)
	v_add_f32_e32 v131, v130, v131
	v_fmamk_f32 v132, v131, 0xbc800000, v129
	v_fmamk_f32 v134, v131, 0xbc800000, v127
	v_fmamk_f32 v130, v131, 0xbc800000, v128
	v_fmamk_f32 v133, v131, 0xbc800000, v126
	v_mul_f32_e32 v134, v134, v134
	v_mul_f32_e32 v132, v132, v132
	v_fmac_f32_e32 v134, v133, v133
	v_fmac_f32_e32 v132, v130, v130
	v_add_f32_e32 v130, v134, v132
	v_fmamk_f32 v133, v131, 0xbc800000, v125
	v_fmamk_f32 v135, v131, 0xbc800000, v123
	v_fmamk_f32 v132, v131, 0xbc800000, v124
	v_fmamk_f32 v134, v131, 0xbc800000, v122
	v_mul_f32_e32 v135, v135, v135
	v_mul_f32_e32 v133, v133, v133
	v_fmac_f32_e32 v135, v134, v134
	v_fmac_f32_e32 v133, v132, v132
	v_add_f32_e32 v132, v135, v133
	v_fmamk_f32 v133, v131, 0xbc800000, v121
	v_fmamk_f32 v135, v131, 0xbc800000, v119
	v_add_f32_e32 v130, v130, v132
	v_fmamk_f32 v132, v131, 0xbc800000, v120
	v_fmamk_f32 v134, v131, 0xbc800000, v118
	v_mul_f32_e32 v135, v135, v135
	v_mul_f32_e32 v133, v133, v133
	v_fmac_f32_e32 v135, v134, v134
	v_fmac_f32_e32 v133, v132, v132
	v_add_f32_e32 v132, v135, v133
	v_fmamk_f32 v133, v131, 0xbc800000, v117
	v_fmamk_f32 v135, v131, 0xbc800000, v115
	v_add_f32_e32 v130, v132, v130
	v_fmamk_f32 v132, v131, 0xbc800000, v116
	v_fmamk_f32 v134, v131, 0xbc800000, v114
	v_mul_f32_e32 v135, v135, v135
	v_mul_f32_e32 v133, v133, v133
	v_fmac_f32_e32 v135, v134, v134
	v_fmac_f32_e32 v133, v132, v132
	v_add_f32_e32 v132, v135, v133
	v_add_f32_e32 v132, v132, v130
	v_mov_b32_e32 v133, v132
	s_nop 1
	v_permlane16_swap_b32_e32 v132, v133
	v_and_b32_e32 v130, 63, v148
	v_cmp_gt_u32_e64 s[4:5], 16, v130
	s_waitcnt lgkmcnt(0)
	v_add_f32_e32 v132, v132, v133
	v_mov_b32_e32 v133, v132
	s_nop 1
	v_permlane32_swap_b32_e32 v132, v133
	s_and_saveexec_b64 s[0:1], s[4:5]
	s_cbranch_execz .LBB0_572
	s_lshl_b32 s6, s26, 11
	s_add_i32 s6, s27, s6
	v_mul_f32_e32 v134, 0x3c800000, v131
	s_waitcnt lgkmcnt(0)
	v_add_f32_e32 v135, v132, v133
	v_lshl_add_u32 v131, v170, 5, s6
	ds_write_b64 v131, v[134:135]
.LBB0_572:
	s_or_b64 exec, exec, s[0:1]
	s_waitcnt lgkmcnt(0)
	v_add_f32_e32 v132, v111, v110
	v_add_f32_e32 v133, v112, v113
	v_add_f32_e32 v134, v107, v106
	v_add_f32_e32 v135, v108, v109
	v_add_f32_e32 v131, v132, v133
	v_add_f32_e32 v135, v134, v135
	v_add_f32_e32 v134, v134, v134
	v_add_f32_e32 v133, 0, v131
	v_add_f32_e32 v137, v102, v103
	v_add_f32_e32 v139, v104, v105
	v_mov_b32_e32 v138, v99
	v_mov_b32_e32 v134, v100
	v_add_f32_e32 v136, v98, v99
	v_add_f32_e32 v137, v137, v139
	v_add_f32_e32 v132, v100, v101
	v_add_f32_e32 v133, v135, v133
	v_add_f32_e32 v132, v136, v132
	v_add_f32_e32 v133, v137, v133
	v_add_f32_e32 v131, v132, v133
	v_mov_b32_e32 v132, v131
	s_nop 1
	v_permlane16_swap_b32_e32 v131, v132
	s_waitcnt lgkmcnt(0)
	v_add_f32_e32 v131, v131, v132
	v_mov_b32_e32 v132, v131
	s_nop 1
	v_permlane32_swap_b32_e32 v131, v132
	s_waitcnt lgkmcnt(0)
	v_add_f32_e32 v131, v131, v132
	v_fmamk_f32 v133, v131, 0xbc800000, v113
	v_fmamk_f32 v135, v131, 0xbc800000, v111
	v_fmamk_f32 v132, v131, 0xbc800000, v112
	v_fmamk_f32 v134, v131, 0xbc800000, v110
	v_mul_f32_e32 v135, v135, v135
	v_mul_f32_e32 v133, v133, v133
	v_fmac_f32_e32 v135, v134, v134
	v_fmac_f32_e32 v133, v132, v132
	v_add_f32_e32 v132, v135, v133
	v_fmamk_f32 v134, v131, 0xbc800000, v109
	v_fmamk_f32 v136, v131, 0xbc800000, v107
	v_fmamk_f32 v133, v131, 0xbc800000, v108
	v_fmamk_f32 v135, v131, 0xbc800000, v106
	v_mul_f32_e32 v136, v136, v136
	v_mul_f32_e32 v134, v134, v134
	v_fmac_f32_e32 v136, v135, v135
	v_fmac_f32_e32 v134, v133, v133
	v_add_f32_e32 v133, v136, v134
	v_fmamk_f32 v134, v131, 0xbc800000, v105
	v_fmamk_f32 v136, v131, 0xbc800000, v103
	v_add_f32_e32 v132, v132, v133
	v_fmamk_f32 v133, v131, 0xbc800000, v104
	v_fmamk_f32 v135, v131, 0xbc800000, v102
	v_mul_f32_e32 v136, v136, v136
	v_mul_f32_e32 v134, v134, v134
	v_fmac_f32_e32 v136, v135, v135
	v_fmac_f32_e32 v134, v133, v133
	v_add_f32_e32 v133, v136, v134
	v_fmamk_f32 v134, v131, 0xbc800000, v101
	v_fmamk_f32 v136, v131, 0xbc800000, v99
	v_add_f32_e32 v132, v133, v132
	v_fmamk_f32 v133, v131, 0xbc800000, v100
	v_fmamk_f32 v135, v131, 0xbc800000, v98
	v_mul_f32_e32 v136, v136, v136
	v_mul_f32_e32 v134, v134, v134
	v_fmac_f32_e32 v136, v135, v135
	v_fmac_f32_e32 v134, v133, v133
	v_add_f32_e32 v133, v136, v134
	v_add_f32_e32 v132, v133, v132
	v_mov_b32_e32 v133, v132
	s_nop 1
	v_permlane16_swap_b32_e32 v132, v133
	s_waitcnt lgkmcnt(0)
	v_add_f32_e32 v132, v132, v133
	v_mov_b32_e32 v133, v132
	s_nop 1
	v_permlane32_swap_b32_e32 v132, v133
	s_and_saveexec_b64 s[0:1], s[4:5]
	s_cbranch_execz .LBB0_574
	s_lshl_b32 s6, s26, 11
	s_add_i32 s6, s27, s6
	v_mul_f32_e32 v134, 0x3c800000, v131
	s_waitcnt lgkmcnt(0)
	v_add_f32_e32 v135, v132, v133
	v_lshl_add_u32 v131, v170, 5, s6
	ds_write_b64 v131, v[134:135] offset:512
.LBB0_574:
	s_or_b64 exec, exec, s[0:1]
	s_waitcnt lgkmcnt(0)
	v_add_f32_e32 v132, v95, v94
	v_add_f32_e32 v133, v96, v97
	v_add_f32_e32 v134, v91, v90
	v_add_f32_e32 v135, v92, v93
	v_add_f32_e32 v131, v132, v133
	v_add_f32_e32 v135, v134, v135
	v_add_f32_e32 v134, v134, v134
	v_add_f32_e32 v133, 0, v131
	v_add_f32_e32 v137, v86, v87
	v_add_f32_e32 v139, v88, v89
	v_mov_b32_e32 v138, v83
	v_mov_b32_e32 v134, v84
	v_add_f32_e32 v136, v82, v83
	v_add_f32_e32 v137, v137, v139
	v_add_f32_e32 v132, v84, v85
	v_add_f32_e32 v133, v135, v133
	v_add_f32_e32 v132, v136, v132
	v_add_f32_e32 v133, v137, v133
	v_add_f32_e32 v131, v132, v133
	v_mov_b32_e32 v132, v131
	s_nop 1
	v_permlane16_swap_b32_e32 v131, v132
	s_waitcnt lgkmcnt(0)
	v_add_f32_e32 v131, v131, v132
	v_mov_b32_e32 v132, v131
	s_nop 1
	v_permlane32_swap_b32_e32 v131, v132
	s_waitcnt lgkmcnt(0)
	v_add_f32_e32 v131, v131, v132
	v_fmamk_f32 v133, v131, 0xbc800000, v97
	v_fmamk_f32 v135, v131, 0xbc800000, v95
	v_fmamk_f32 v132, v131, 0xbc800000, v96
	v_fmamk_f32 v134, v131, 0xbc800000, v94
	v_mul_f32_e32 v135, v135, v135
	v_mul_f32_e32 v133, v133, v133
	v_fmac_f32_e32 v135, v134, v134
	v_fmac_f32_e32 v133, v132, v132
	v_add_f32_e32 v132, v135, v133
	v_fmamk_f32 v134, v131, 0xbc800000, v93
	v_fmamk_f32 v136, v131, 0xbc800000, v91
	v_fmamk_f32 v133, v131, 0xbc800000, v92
	v_fmamk_f32 v135, v131, 0xbc800000, v90
	v_mul_f32_e32 v136, v136, v136
	v_mul_f32_e32 v134, v134, v134
	v_fmac_f32_e32 v136, v135, v135
	v_fmac_f32_e32 v134, v133, v133
	v_add_f32_e32 v133, v136, v134
	v_fmamk_f32 v134, v131, 0xbc800000, v89
	v_fmamk_f32 v136, v131, 0xbc800000, v87
	v_add_f32_e32 v132, v132, v133
	v_fmamk_f32 v133, v131, 0xbc800000, v88
	v_fmamk_f32 v135, v131, 0xbc800000, v86
	v_mul_f32_e32 v136, v136, v136
	v_mul_f32_e32 v134, v134, v134
	v_fmac_f32_e32 v136, v135, v135
	v_fmac_f32_e32 v134, v133, v133
	v_add_f32_e32 v133, v136, v134
	v_fmamk_f32 v134, v131, 0xbc800000, v85
	v_fmamk_f32 v136, v131, 0xbc800000, v83
	v_add_f32_e32 v132, v133, v132
	v_fmamk_f32 v133, v131, 0xbc800000, v84
	v_fmamk_f32 v135, v131, 0xbc800000, v82
	v_mul_f32_e32 v136, v136, v136
	v_mul_f32_e32 v134, v134, v134
	v_fmac_f32_e32 v136, v135, v135
	v_fmac_f32_e32 v134, v133, v133
	v_add_f32_e32 v133, v136, v134
	v_add_f32_e32 v132, v133, v132
	v_mov_b32_e32 v133, v132
	s_nop 1
	v_permlane16_swap_b32_e32 v132, v133
	s_waitcnt lgkmcnt(0)
	v_add_f32_e32 v132, v132, v133
	v_mov_b32_e32 v133, v132
	s_nop 1
	v_permlane32_swap_b32_e32 v132, v133
	s_and_saveexec_b64 s[0:1], s[4:5]
	s_cbranch_execz .LBB0_576
	s_lshl_b32 s6, s26, 11
	s_add_i32 s6, s27, s6
	v_mul_f32_e32 v134, 0x3c800000, v131
	s_waitcnt lgkmcnt(0)
	v_add_f32_e32 v135, v132, v133
	v_lshl_add_u32 v131, v170, 5, s6
	ds_write_b64 v131, v[134:135] offset:1024
.LBB0_576:
	s_or_b64 exec, exec, s[0:1]
	s_waitcnt lgkmcnt(0)
	v_add_f32_e32 v132, v79, v78
	v_add_f32_e32 v133, v80, v81
	v_add_f32_e32 v134, v75, v74
	v_add_f32_e32 v135, v76, v77
	v_add_f32_e32 v131, v132, v133
	v_add_f32_e32 v135, v134, v135
	v_add_f32_e32 v134, v134, v134
	v_add_f32_e32 v133, 0, v131
	v_add_f32_e32 v137, v70, v71
	v_add_f32_e32 v139, v72, v73
	v_mov_b32_e32 v138, v67
	v_mov_b32_e32 v134, v68
	v_add_f32_e32 v136, v66, v67
	v_add_f32_e32 v137, v137, v139
	v_add_f32_e32 v132, v68, v69
	v_add_f32_e32 v133, v135, v133
	v_add_f32_e32 v132, v136, v132
	v_add_f32_e32 v133, v137, v133
	v_add_f32_e32 v131, v132, v133
	v_mov_b32_e32 v132, v131
	s_nop 1
	v_permlane16_swap_b32_e32 v131, v132
	s_waitcnt lgkmcnt(0)
	v_add_f32_e32 v131, v131, v132
	v_mov_b32_e32 v132, v131
	s_nop 1
	v_permlane32_swap_b32_e32 v131, v132
	s_waitcnt lgkmcnt(0)
	v_add_f32_e32 v131, v131, v132
	v_fmamk_f32 v133, v131, 0xbc800000, v81
	v_fmamk_f32 v135, v131, 0xbc800000, v79
	v_fmamk_f32 v132, v131, 0xbc800000, v80
	v_fmamk_f32 v134, v131, 0xbc800000, v78
	v_mul_f32_e32 v135, v135, v135
	v_mul_f32_e32 v133, v133, v133
	v_fmac_f32_e32 v135, v134, v134
	v_fmac_f32_e32 v133, v132, v132
	v_add_f32_e32 v132, v135, v133
	v_fmamk_f32 v134, v131, 0xbc800000, v77
	v_fmamk_f32 v136, v131, 0xbc800000, v75
	v_fmamk_f32 v133, v131, 0xbc800000, v76
	v_fmamk_f32 v135, v131, 0xbc800000, v74
	v_mul_f32_e32 v136, v136, v136
	v_mul_f32_e32 v134, v134, v134
	v_fmac_f32_e32 v136, v135, v135
	v_fmac_f32_e32 v134, v133, v133
	v_add_f32_e32 v133, v136, v134
	v_fmamk_f32 v134, v131, 0xbc800000, v73
	v_fmamk_f32 v136, v131, 0xbc800000, v71
	v_add_f32_e32 v132, v132, v133
	v_fmamk_f32 v133, v131, 0xbc800000, v72
	v_fmamk_f32 v135, v131, 0xbc800000, v70
	v_mul_f32_e32 v136, v136, v136
	v_mul_f32_e32 v134, v134, v134
	v_fmac_f32_e32 v136, v135, v135
	v_fmac_f32_e32 v134, v133, v133
	v_add_f32_e32 v133, v136, v134
	v_fmamk_f32 v134, v131, 0xbc800000, v69
	v_fmamk_f32 v136, v131, 0xbc800000, v67
	v_add_f32_e32 v132, v133, v132
	v_fmamk_f32 v133, v131, 0xbc800000, v68
	v_fmamk_f32 v135, v131, 0xbc800000, v66
	v_mul_f32_e32 v136, v136, v136
	v_mul_f32_e32 v134, v134, v134
	v_fmac_f32_e32 v136, v135, v135
	v_fmac_f32_e32 v134, v133, v133
	v_add_f32_e32 v133, v136, v134
	v_add_f32_e32 v132, v133, v132
	v_mov_b32_e32 v133, v132
	s_nop 1
	v_permlane16_swap_b32_e32 v132, v133
	s_waitcnt lgkmcnt(0)
	v_add_f32_e32 v132, v132, v133
	v_mov_b32_e32 v133, v132
	s_nop 1
	v_permlane32_swap_b32_e32 v132, v133
	s_and_saveexec_b64 s[0:1], s[4:5]
	s_cbranch_execz .LBB0_578
	s_lshl_b32 s6, s26, 11
	s_add_i32 s6, s27, s6
	v_mul_f32_e32 v134, 0x3c800000, v131
	s_waitcnt lgkmcnt(0)
	v_add_f32_e32 v135, v132, v133
	v_lshl_add_u32 v131, v170, 5, s6
	ds_write_b64 v131, v[134:135] offset:1536
.LBB0_578:
	s_or_b64 exec, exec, s[0:1]
	s_waitcnt lgkmcnt(0)
	v_add_f32_e32 v132, v63, v62
	v_add_f32_e32 v133, v64, v65
	v_add_f32_e32 v134, v59, v58
	v_add_f32_e32 v135, v60, v61
	v_add_f32_e32 v131, v132, v133
	v_add_f32_e32 v135, v134, v135
	v_add_f32_e32 v134, v134, v134
	v_add_f32_e32 v133, 0, v131
	v_add_f32_e32 v137, v54, v55
	v_add_f32_e32 v139, v56, v57
	v_mov_b32_e32 v138, v51
	v_mov_b32_e32 v134, v52
	v_add_f32_e32 v136, v50, v51
	v_add_f32_e32 v137, v137, v139
	v_add_f32_e32 v132, v52, v53
	v_add_f32_e32 v133, v135, v133
	v_add_f32_e32 v132, v136, v132
	v_add_f32_e32 v133, v137, v133
	v_add_f32_e32 v131, v132, v133
	v_mov_b32_e32 v132, v131
	s_nop 1
	v_permlane16_swap_b32_e32 v131, v132
	s_waitcnt lgkmcnt(0)
	v_add_f32_e32 v131, v131, v132
	v_mov_b32_e32 v132, v131
	s_nop 1
	v_permlane32_swap_b32_e32 v131, v132
	s_waitcnt lgkmcnt(0)
	v_add_f32_e32 v131, v131, v132
	v_fmamk_f32 v133, v131, 0xbc800000, v65
	v_fmamk_f32 v135, v131, 0xbc800000, v63
	v_fmamk_f32 v132, v131, 0xbc800000, v64
	v_fmamk_f32 v134, v131, 0xbc800000, v62
	v_mul_f32_e32 v135, v135, v135
	v_mul_f32_e32 v133, v133, v133
	v_fmac_f32_e32 v135, v134, v134
	v_fmac_f32_e32 v133, v132, v132
	v_add_f32_e32 v132, v135, v133
	v_fmamk_f32 v134, v131, 0xbc800000, v61
	v_fmamk_f32 v136, v131, 0xbc800000, v59
	v_fmamk_f32 v133, v131, 0xbc800000, v60
	v_fmamk_f32 v135, v131, 0xbc800000, v58
	v_mul_f32_e32 v136, v136, v136
	v_mul_f32_e32 v134, v134, v134
	v_fmac_f32_e32 v136, v135, v135
	v_fmac_f32_e32 v134, v133, v133
	v_add_f32_e32 v133, v136, v134
	v_fmamk_f32 v134, v131, 0xbc800000, v57
	v_fmamk_f32 v136, v131, 0xbc800000, v55
	v_add_f32_e32 v132, v132, v133
	v_fmamk_f32 v133, v131, 0xbc800000, v56
	v_fmamk_f32 v135, v131, 0xbc800000, v54
	v_mul_f32_e32 v136, v136, v136
	v_mul_f32_e32 v134, v134, v134
	v_fmac_f32_e32 v136, v135, v135
	v_fmac_f32_e32 v134, v133, v133
	v_add_f32_e32 v133, v136, v134
	v_fmamk_f32 v134, v131, 0xbc800000, v53
	v_fmamk_f32 v136, v131, 0xbc800000, v51
	v_add_f32_e32 v132, v133, v132
	v_fmamk_f32 v133, v131, 0xbc800000, v52
	v_fmamk_f32 v135, v131, 0xbc800000, v50
	v_mul_f32_e32 v136, v136, v136
	v_mul_f32_e32 v134, v134, v134
	v_fmac_f32_e32 v136, v135, v135
	v_fmac_f32_e32 v134, v133, v133
	v_add_f32_e32 v133, v136, v134
	v_add_f32_e32 v132, v133, v132
	v_mov_b32_e32 v133, v132
	s_nop 1
	v_permlane16_swap_b32_e32 v132, v133
	s_waitcnt lgkmcnt(0)
	v_add_f32_e32 v132, v132, v133
	v_mov_b32_e32 v133, v132
	s_nop 1
	v_permlane32_swap_b32_e32 v132, v133
	s_and_saveexec_b64 s[0:1], s[4:5]
	s_cbranch_execz .LBB0_580
	s_lshl_b32 s6, s26, 11
	s_add_i32 s6, s27, s6
	v_mul_f32_e32 v134, 0x3c800000, v131
	s_waitcnt lgkmcnt(0)
	v_add_f32_e32 v135, v132, v133
	v_lshl_add_u32 v131, v170, 5, s6
	ds_write_b64 v131, v[134:135] offset:4096
.LBB0_580:
	s_or_b64 exec, exec, s[0:1]
	s_waitcnt lgkmcnt(0)
	v_add_f32_e32 v132, v47, v46
	v_add_f32_e32 v133, v48, v49
	v_add_f32_e32 v134, v43, v42
	v_add_f32_e32 v135, v44, v45
	v_add_f32_e32 v131, v132, v133
	v_add_f32_e32 v135, v134, v135
	v_add_f32_e32 v134, v134, v134
	v_add_f32_e32 v133, 0, v131
	v_add_f32_e32 v137, v38, v39
	v_add_f32_e32 v139, v40, v41
	v_mov_b32_e32 v138, v35
	v_mov_b32_e32 v134, v36
	v_add_f32_e32 v136, v34, v35
	v_add_f32_e32 v137, v137, v139
	v_add_f32_e32 v132, v36, v37
	v_add_f32_e32 v133, v135, v133
	v_add_f32_e32 v132, v136, v132
	v_add_f32_e32 v133, v137, v133
	v_add_f32_e32 v131, v132, v133
	v_mov_b32_e32 v132, v131
	s_nop 1
	v_permlane16_swap_b32_e32 v131, v132
	s_waitcnt lgkmcnt(0)
	v_add_f32_e32 v131, v131, v132
	v_mov_b32_e32 v132, v131
	s_nop 1
	v_permlane32_swap_b32_e32 v131, v132
	s_waitcnt lgkmcnt(0)
	v_add_f32_e32 v131, v131, v132
	v_fmamk_f32 v133, v131, 0xbc800000, v49
	v_fmamk_f32 v135, v131, 0xbc800000, v47
	v_fmamk_f32 v132, v131, 0xbc800000, v48
	v_fmamk_f32 v134, v131, 0xbc800000, v46
	v_mul_f32_e32 v135, v135, v135
	v_mul_f32_e32 v133, v133, v133
	v_fmac_f32_e32 v135, v134, v134
	v_fmac_f32_e32 v133, v132, v132
	v_add_f32_e32 v132, v135, v133
	v_fmamk_f32 v134, v131, 0xbc800000, v45
	v_fmamk_f32 v136, v131, 0xbc800000, v43
	v_fmamk_f32 v133, v131, 0xbc800000, v44
	v_fmamk_f32 v135, v131, 0xbc800000, v42
	v_mul_f32_e32 v136, v136, v136
	v_mul_f32_e32 v134, v134, v134
	v_fmac_f32_e32 v136, v135, v135
	v_fmac_f32_e32 v134, v133, v133
	v_add_f32_e32 v133, v136, v134
	v_fmamk_f32 v134, v131, 0xbc800000, v41
	v_fmamk_f32 v136, v131, 0xbc800000, v39
	v_add_f32_e32 v132, v132, v133
	v_fmamk_f32 v133, v131, 0xbc800000, v40
	v_fmamk_f32 v135, v131, 0xbc800000, v38
	v_mul_f32_e32 v136, v136, v136
	v_mul_f32_e32 v134, v134, v134
	v_fmac_f32_e32 v136, v135, v135
	v_fmac_f32_e32 v134, v133, v133
	v_add_f32_e32 v133, v136, v134
	v_fmamk_f32 v134, v131, 0xbc800000, v37
	v_fmamk_f32 v136, v131, 0xbc800000, v35
	v_add_f32_e32 v132, v133, v132
	v_fmamk_f32 v133, v131, 0xbc800000, v36
	v_fmamk_f32 v135, v131, 0xbc800000, v34
	v_mul_f32_e32 v136, v136, v136
	v_mul_f32_e32 v134, v134, v134
	v_fmac_f32_e32 v136, v135, v135
	v_fmac_f32_e32 v134, v133, v133
	v_add_f32_e32 v133, v136, v134
	v_add_f32_e32 v132, v133, v132
	v_mov_b32_e32 v133, v132
	s_nop 1
	v_permlane16_swap_b32_e32 v132, v133
	s_waitcnt lgkmcnt(0)
	v_add_f32_e32 v132, v132, v133
	v_mov_b32_e32 v133, v132
	s_nop 1
	v_permlane32_swap_b32_e32 v132, v133
	s_and_saveexec_b64 s[0:1], s[4:5]
	s_cbranch_execz .LBB0_582
	s_lshl_b32 s6, s26, 11
	s_add_i32 s6, s27, s6
	v_mul_f32_e32 v134, 0x3c800000, v131
	s_waitcnt lgkmcnt(0)
	v_add_f32_e32 v135, v132, v133
	v_lshl_add_u32 v131, v170, 5, s6
	ds_write_b64 v131, v[134:135] offset:4608
.LBB0_582:
	s_or_b64 exec, exec, s[0:1]
	s_waitcnt lgkmcnt(0)
	v_add_f32_e32 v132, v31, v30
	v_add_f32_e32 v133, v32, v33
	v_add_f32_e32 v134, v27, v26
	v_add_f32_e32 v135, v28, v29
	v_add_f32_e32 v131, v132, v133
	v_add_f32_e32 v135, v134, v135
	v_add_f32_e32 v134, v134, v134
	v_add_f32_e32 v133, 0, v131
	v_add_f32_e32 v137, v22, v23
	v_add_f32_e32 v139, v24, v25
	v_mov_b32_e32 v138, v19
	v_mov_b32_e32 v134, v20
	v_add_f32_e32 v136, v18, v19
	v_add_f32_e32 v137, v137, v139
	v_add_f32_e32 v132, v20, v21
	v_add_f32_e32 v133, v135, v133
	v_add_f32_e32 v132, v136, v132
	v_add_f32_e32 v133, v137, v133
	v_add_f32_e32 v131, v132, v133
	v_mov_b32_e32 v132, v131
	s_nop 1
	v_permlane16_swap_b32_e32 v131, v132
	s_waitcnt lgkmcnt(0)
	v_add_f32_e32 v131, v131, v132
	v_mov_b32_e32 v132, v131
	s_nop 1
	v_permlane32_swap_b32_e32 v131, v132
	s_waitcnt lgkmcnt(0)
	v_add_f32_e32 v131, v131, v132
	v_fmamk_f32 v133, v131, 0xbc800000, v33
	v_fmamk_f32 v135, v131, 0xbc800000, v31
	v_fmamk_f32 v132, v131, 0xbc800000, v32
	v_fmamk_f32 v134, v131, 0xbc800000, v30
	v_mul_f32_e32 v135, v135, v135
	v_mul_f32_e32 v133, v133, v133
	v_fmac_f32_e32 v135, v134, v134
	v_fmac_f32_e32 v133, v132, v132
	v_add_f32_e32 v132, v135, v133
	v_fmamk_f32 v134, v131, 0xbc800000, v29
	v_fmamk_f32 v136, v131, 0xbc800000, v27
	v_fmamk_f32 v133, v131, 0xbc800000, v28
	v_fmamk_f32 v135, v131, 0xbc800000, v26
	v_mul_f32_e32 v136, v136, v136
	v_mul_f32_e32 v134, v134, v134
	v_fmac_f32_e32 v136, v135, v135
	v_fmac_f32_e32 v134, v133, v133
	v_add_f32_e32 v133, v136, v134
	v_fmamk_f32 v134, v131, 0xbc800000, v25
	v_fmamk_f32 v136, v131, 0xbc800000, v23
	v_add_f32_e32 v132, v132, v133
	v_fmamk_f32 v133, v131, 0xbc800000, v24
	v_fmamk_f32 v135, v131, 0xbc800000, v22
	v_mul_f32_e32 v136, v136, v136
	v_mul_f32_e32 v134, v134, v134
	v_fmac_f32_e32 v136, v135, v135
	v_fmac_f32_e32 v134, v133, v133
	v_add_f32_e32 v133, v136, v134
	v_fmamk_f32 v134, v131, 0xbc800000, v21
	v_fmamk_f32 v136, v131, 0xbc800000, v19
	v_add_f32_e32 v132, v133, v132
	v_fmamk_f32 v133, v131, 0xbc800000, v20
	v_fmamk_f32 v135, v131, 0xbc800000, v18
	v_mul_f32_e32 v136, v136, v136
	v_mul_f32_e32 v134, v134, v134
	v_fmac_f32_e32 v136, v135, v135
	v_fmac_f32_e32 v134, v133, v133
	v_add_f32_e32 v133, v136, v134
	v_add_f32_e32 v132, v133, v132
	v_mov_b32_e32 v133, v132
	s_nop 1
	v_permlane16_swap_b32_e32 v132, v133
	s_waitcnt lgkmcnt(0)
	v_add_f32_e32 v132, v132, v133
	v_mov_b32_e32 v133, v132
	s_nop 1
	v_permlane32_swap_b32_e32 v132, v133
	s_and_saveexec_b64 s[0:1], s[4:5]
	s_cbranch_execz .LBB0_584
	s_lshl_b32 s6, s26, 11
	s_add_i32 s6, s27, s6
	v_mul_f32_e32 v134, 0x3c800000, v131
	s_waitcnt lgkmcnt(0)
	v_add_f32_e32 v135, v132, v133
	v_lshl_add_u32 v131, v170, 5, s6
	ds_write_b64 v131, v[134:135] offset:5120
.LBB0_584:
	s_or_b64 exec, exec, s[0:1]
	s_waitcnt lgkmcnt(0)
	v_add_f32_e32 v132, v15, v14
	v_add_f32_e32 v133, v16, v17
	v_add_f32_e32 v134, v11, v10
	v_add_f32_e32 v135, v12, v13
	v_add_f32_e32 v131, v132, v133
	v_add_f32_e32 v135, v134, v135
	v_add_f32_e32 v134, v134, v134
	v_add_f32_e32 v133, 0, v131
	v_add_f32_e32 v137, v6, v7
	v_add_f32_e32 v139, v8, v9
	v_mov_b32_e32 v138, v3
	v_mov_b32_e32 v134, v4
	v_add_f32_e32 v136, v2, v3
	v_add_f32_e32 v137, v137, v139
	v_add_f32_e32 v132, v4, v5
	v_add_f32_e32 v133, v135, v133
	v_add_f32_e32 v132, v136, v132
	v_add_f32_e32 v133, v137, v133
	v_add_f32_e32 v131, v132, v133
	v_mov_b32_e32 v132, v131
	s_nop 1
	v_permlane16_swap_b32_e32 v131, v132
	s_waitcnt lgkmcnt(0)
	v_add_f32_e32 v131, v131, v132
	v_mov_b32_e32 v132, v131
	s_nop 1
	v_permlane32_swap_b32_e32 v131, v132
	s_waitcnt lgkmcnt(0)
	v_add_f32_e32 v131, v131, v132
	v_fmamk_f32 v133, v131, 0xbc800000, v17
	v_fmamk_f32 v135, v131, 0xbc800000, v15
	v_fmamk_f32 v132, v131, 0xbc800000, v16
	v_fmamk_f32 v134, v131, 0xbc800000, v14
	v_mul_f32_e32 v135, v135, v135
	v_mul_f32_e32 v133, v133, v133
	v_fmac_f32_e32 v135, v134, v134
	v_fmac_f32_e32 v133, v132, v132
	v_add_f32_e32 v132, v135, v133
	v_fmamk_f32 v134, v131, 0xbc800000, v13
	v_fmamk_f32 v136, v131, 0xbc800000, v11
	v_fmamk_f32 v133, v131, 0xbc800000, v12
	v_fmamk_f32 v135, v131, 0xbc800000, v10
	v_mul_f32_e32 v136, v136, v136
	v_mul_f32_e32 v134, v134, v134
	v_fmac_f32_e32 v136, v135, v135
	v_fmac_f32_e32 v134, v133, v133
	v_add_f32_e32 v133, v136, v134
	v_fmamk_f32 v134, v131, 0xbc800000, v9
	v_fmamk_f32 v136, v131, 0xbc800000, v7
	v_add_f32_e32 v132, v132, v133
	v_fmamk_f32 v133, v131, 0xbc800000, v8
	v_fmamk_f32 v135, v131, 0xbc800000, v6
	v_mul_f32_e32 v136, v136, v136
	v_mul_f32_e32 v134, v134, v134
	v_fmac_f32_e32 v136, v135, v135
	v_fmac_f32_e32 v134, v133, v133
	v_add_f32_e32 v133, v136, v134
	v_fmamk_f32 v134, v131, 0xbc800000, v5
	v_fmamk_f32 v136, v131, 0xbc800000, v3
	v_add_f32_e32 v132, v133, v132
	v_fmamk_f32 v133, v131, 0xbc800000, v4
	v_fmamk_f32 v135, v131, 0xbc800000, v2
	v_mul_f32_e32 v136, v136, v136
	v_mul_f32_e32 v134, v134, v134
	v_fmac_f32_e32 v136, v135, v135
	v_fmac_f32_e32 v134, v133, v133
	v_add_f32_e32 v133, v136, v134
	v_add_f32_e32 v132, v133, v132
	v_mov_b32_e32 v133, v132
	s_nop 1
	v_permlane16_swap_b32_e32 v132, v133
	s_waitcnt lgkmcnt(0)
	v_add_f32_e32 v132, v132, v133
	v_mov_b32_e32 v133, v132
	s_nop 1
	v_permlane32_swap_b32_e32 v132, v133
	s_and_saveexec_b64 s[0:1], s[4:5]
	s_cbranch_execz .LBB0_586
	s_lshl_b32 s6, s26, 11
	s_add_i32 s6, s27, s6
	v_mul_f32_e32 v134, 0x3c800000, v131
	s_waitcnt lgkmcnt(0)
	v_add_f32_e32 v135, v132, v133
	v_lshl_add_u32 v131, v170, 5, s6
	ds_write_b64 v131, v[134:135] offset:5632

.LBB0_610:
	s_or_b64 exec, exec, s[22:23]
	s_lshl_b32 s0, s17, 5
	s_lshl_b32 s1, s18, 8
	s_or_b32 s0, s1, s0
	v_lshrrev_b32_e32 v130, 2, v148
	v_and_or_b32 v162, v130, 12, s0
	s_lshl_b32 s0, s16, 5
	s_and_b32 s0, s0, 0xfffffc00
	v_add_u32_e32 v148, s0, v162
	v_readlane_b32 s0, v251, 45
	v_add_u32_e32 v150, s19, v152
	v_readlane_b32 s40, v251, 25
	v_ashrrev_i32_e32 v149, 31, v148
	v_readlane_b32 s1, v251, 46
	v_ashrrev_i32_e32 v151, 31, v150
	v_readlane_b32 s41, v251, 26
	v_lshl_add_u64 v[138:139], v[148:149], 2, s[0:1]
	v_ashrrev_i32_e32 v163, 31, v162
	v_lshlrev_b64 v[130:131], 12, v[150:151]
	s_mov_b64 s[0:1], s[40:41]
	v_lshl_add_u64 v[130:131], s[0:1], 0, v[130:131]
	v_lshlrev_b64 v[168:169], 2, v[162:163]
	s_waitcnt lgkmcnt(0)
	s_barrier
	v_lshl_add_u64 v[172:173], v[130:131], 0, v[168:169]
	global_load_dwordx4 v[154:157], v[172:173], off
	global_load_dwordx4 v[134:137], v[138:139], off
	s_waitcnt lgkmcnt(0)
	global_load_dwordx4 v[130:133], v[138:139], off offset:64
	global_load_dwordx4 v[158:161], v[172:173], off offset:64
	global_load_dwordx4 v[164:167], v[172:173], off offset:512
	global_load_dwordx4 v[142:145], v[138:139], off offset:512
	s_nop 0
	global_load_dwordx4 v[138:141], v[138:139], off offset:576
	s_nop 0
	global_load_dwordx4 v[172:175], v[172:173], off offset:576
	v_lshl_add_u32 v184, v152, 3, 0
	ds_read_b64 v[176:177], v184 offset:8192
	v_add_u32_e32 v152, 16, v150
	v_ashrrev_i32_e32 v153, 31, v152
	v_lshlrev_b64 v[178:179], 12, v[152:153]
	v_lshl_add_u64 v[178:179], s[0:1], 0, v[178:179]
	s_waitcnt lgkmcnt(0)
	v_pk_mul_f32 v[126:127], v[126:127], v[176:177] op_sel:[0,1]
	v_pk_mul_f32 v[128:129], v[128:129], v[176:177] op_sel:[0,1]
	v_pk_mul_f32 v[122:123], v[122:123], v[176:177] op_sel:[0,1]
	v_pk_mul_f32 v[124:125], v[124:125], v[176:177] op_sel:[0,1]
	v_pk_mul_f32 v[180:181], v[118:119], v[176:177] op_sel:[0,1]
	v_pk_mul_f32 v[188:189], v[120:121], v[176:177] op_sel:[0,1]
	v_pk_mul_f32 v[114:115], v[114:115], v[176:177] op_sel:[0,1]
	v_pk_mul_f32 v[116:117], v[116:117], v[176:177] op_sel:[0,1]
	v_lshl_add_u64 v[178:179], v[178:179], 0, v[168:169]
	v_readlane_b32 s42, v251, 27
	v_readlane_b32 s43, v251, 28
	v_readlane_b32 s44, v251, 29
	v_readlane_b32 s45, v251, 30
	v_readlane_b32 s46, v251, 31
	v_readlane_b32 s47, v251, 32
	v_readlane_b32 s48, v251, 33
	v_readlane_b32 s49, v251, 34
	v_readlane_b32 s50, v251, 35
	v_readlane_b32 s51, v251, 36
	v_readlane_b32 s52, v251, 37
	v_readlane_b32 s53, v251, 38
	v_readlane_b32 s54, v251, 39
	v_readlane_b32 s55, v251, 40
	s_waitcnt vmcnt(0)
	v_pk_fma_f32 v[120:121], v[136:137], v[128:129], v[156:157]
	v_pk_fma_f32 v[118:119], v[134:135], v[126:127], v[154:155]
	v_pk_fma_f32 v[124:125], v[132:133], v[124:125], v[160:161]
	v_pk_fma_f32 v[122:123], v[130:131], v[122:123], v[158:159]
	v_pk_fma_f32 v[128:129], v[144:145], v[188:189], v[166:167]
	v_pk_fma_f32 v[126:127], v[142:143], v[180:181], v[164:165]
	v_pk_fma_f32 v[116:117], v[140:141], v[116:117], v[174:175]
	v_pk_fma_f32 v[114:115], v[138:139], v[114:115], v[172:173]
	v_add_u32_e32 v154, 32, v150
	global_load_dwordx4 v[156:159], v[178:179], off
	global_load_dwordx4 v[164:167], v[178:179], off offset:64
	global_load_dwordx4 v[172:175], v[178:179], off offset:512
	s_nop 0
	global_load_dwordx4 v[176:179], v[178:179], off offset:576
	ds_read_b64 v[160:161], v184 offset:8320
	v_ashrrev_i32_e32 v155, 31, v154
	v_lshlrev_b64 v[180:181], 12, v[154:155]
	v_lshl_add_u64 v[180:181], s[0:1], 0, v[180:181]
	v_lshl_add_u64 v[180:181], v[180:181], 0, v[168:169]
	s_waitcnt lgkmcnt(0)
	v_pk_mul_f32 v[110:111], v[110:111], v[160:161] op_sel:[0,1]
	v_pk_mul_f32 v[112:113], v[112:113], v[160:161] op_sel:[0,1]
	v_pk_mul_f32 v[106:107], v[106:107], v[160:161] op_sel:[0,1]
	v_pk_mul_f32 v[108:109], v[108:109], v[160:161] op_sel:[0,1]
	v_pk_mul_f32 v[102:103], v[102:103], v[160:161] op_sel:[0,1]
	v_pk_mul_f32 v[104:105], v[104:105], v[160:161] op_sel:[0,1]
	v_pk_mul_f32 v[98:99], v[98:99], v[160:161] op_sel:[0,1]
	v_pk_mul_f32 v[100:101], v[100:101], v[160:161] op_sel:[0,1]
	v_mov_b32_e32 v196, v118
	v_mov_b32_e32 v197, v121
	v_mov_b32_e32 v204, v123
	v_mov_b32_e32 v205, v124
	v_mov_b32_e32 v206, v122
	v_mov_b32_e32 v207, v125
	v_add_f32_e32 v209, v126, v127
	v_add_f32_e32 v213, v128, v129
	v_mov_b32_e32 v208, v114
	v_mov_b32_e32 v212, v115
	v_mov_b32_e32 v214, v117
	s_waitcnt vmcnt(3)
	v_pk_fma_f32 v[112:113], v[136:137], v[112:113], v[158:159]
	v_pk_fma_f32 v[110:111], v[134:135], v[110:111], v[156:157]
	s_waitcnt vmcnt(2)
	v_pk_fma_f32 v[108:109], v[132:133], v[108:109], v[166:167]
	v_pk_fma_f32 v[106:107], v[130:131], v[106:107], v[164:165]
	s_waitcnt vmcnt(1)
	v_pk_fma_f32 v[104:105], v[144:145], v[104:105], v[174:175]
	v_pk_fma_f32 v[102:103], v[142:143], v[102:103], v[172:173]
	s_waitcnt vmcnt(0)
	v_pk_fma_f32 v[100:101], v[140:141], v[100:101], v[178:179]
	v_pk_fma_f32 v[98:99], v[138:139], v[98:99], v[176:177]
	v_add_u32_e32 v156, 48, v150
	global_load_dwordx4 v[158:161], v[180:181], off
	global_load_dwordx4 v[164:167], v[180:181], off offset:64
	global_load_dwordx4 v[172:175], v[180:181], off offset:512
	global_load_dwordx4 v[176:179], v[180:181], off offset:576
	ds_read_b64 v[180:181], v184 offset:8448
	v_ashrrev_i32_e32 v157, 31, v156
	v_lshlrev_b64 v[188:189], 12, v[156:157]
	v_lshl_add_u64 v[188:189], s[0:1], 0, v[188:189]
	v_lshl_add_u64 v[188:189], v[188:189], 0, v[168:169]
	s_waitcnt lgkmcnt(0)
	v_pk_mul_f32 v[94:95], v[94:95], v[180:181] op_sel:[0,1]
	v_pk_mul_f32 v[96:97], v[96:97], v[180:181] op_sel:[0,1]
	v_pk_mul_f32 v[90:91], v[90:91], v[180:181] op_sel:[0,1]
	v_pk_mul_f32 v[92:93], v[92:93], v[180:181] op_sel:[0,1]
	v_pk_mul_f32 v[86:87], v[86:87], v[180:181] op_sel:[0,1]
	v_pk_mul_f32 v[88:89], v[88:89], v[180:181] op_sel:[0,1]
	v_pk_mul_f32 v[82:83], v[82:83], v[180:181] op_sel:[0,1]
	v_pk_mul_f32 v[84:85], v[84:85], v[180:181] op_sel:[0,1]
	s_waitcnt vmcnt(3)
	v_pk_fma_f32 v[96:97], v[136:137], v[96:97], v[160:161]
	v_pk_fma_f32 v[94:95], v[134:135], v[94:95], v[158:159]
	s_waitcnt vmcnt(2)
	v_pk_fma_f32 v[92:93], v[132:133], v[92:93], v[166:167]
	v_pk_fma_f32 v[90:91], v[130:131], v[90:91], v[164:165]
	s_waitcnt vmcnt(1)
	v_pk_fma_f32 v[88:89], v[144:145], v[88:89], v[174:175]
	v_pk_fma_f32 v[86:87], v[142:143], v[86:87], v[172:173]
	s_waitcnt vmcnt(0)
	v_pk_fma_f32 v[84:85], v[140:141], v[84:85], v[178:179]
	v_pk_fma_f32 v[82:83], v[138:139], v[82:83], v[176:177]
	v_add_u32_e32 v158, 0x80, v150
	global_load_dwordx4 v[164:167], v[188:189], off
	global_load_dwordx4 v[172:175], v[188:189], off offset:64
	global_load_dwordx4 v[176:179], v[188:189], off offset:512
	s_nop 0
	global_load_dwordx4 v[188:191], v[188:189], off offset:576
	ds_read_b64 v[160:161], v184 offset:8576
	v_ashrrev_i32_e32 v159, 31, v158
	v_lshlrev_b64 v[180:181], 12, v[158:159]
	v_lshl_add_u64 v[180:181], s[0:1], 0, v[180:181]
	v_lshl_add_u64 v[180:181], v[180:181], 0, v[168:169]
	s_waitcnt lgkmcnt(0)
	v_pk_mul_f32 v[78:79], v[78:79], v[160:161] op_sel:[0,1]
	v_pk_mul_f32 v[80:81], v[80:81], v[160:161] op_sel:[0,1]
	v_pk_mul_f32 v[74:75], v[74:75], v[160:161] op_sel:[0,1]
	v_pk_mul_f32 v[76:77], v[76:77], v[160:161] op_sel:[0,1]
	v_pk_mul_f32 v[70:71], v[70:71], v[160:161] op_sel:[0,1]
	v_pk_mul_f32 v[72:73], v[72:73], v[160:161] op_sel:[0,1]
	v_pk_mul_f32 v[66:67], v[66:67], v[160:161] op_sel:[0,1]
	v_pk_mul_f32 v[68:69], v[68:69], v[160:161] op_sel:[0,1]
	v_add_u32_e32 v160, 0x90, v150
	v_ashrrev_i32_e32 v161, 31, v160
	v_lshlrev_b64 v[192:193], 12, v[160:161]
	v_lshl_add_u64 v[192:193], s[0:1], 0, v[192:193]
	v_lshl_add_u64 v[192:193], v[192:193], 0, v[168:169]
	s_waitcnt vmcnt(3)
	v_pk_fma_f32 v[80:81], v[136:137], v[80:81], v[166:167]
	v_pk_fma_f32 v[78:79], v[134:135], v[78:79], v[164:165]
	s_waitcnt vmcnt(2)
	v_pk_fma_f32 v[76:77], v[132:133], v[76:77], v[174:175]
	v_pk_fma_f32 v[74:75], v[130:131], v[74:75], v[172:173]
	s_waitcnt vmcnt(1)
	v_pk_fma_f32 v[72:73], v[144:145], v[72:73], v[178:179]
	v_pk_fma_f32 v[70:71], v[142:143], v[70:71], v[176:177]
	s_waitcnt vmcnt(0)
	v_pk_fma_f32 v[68:69], v[140:141], v[68:69], v[190:191]
	v_pk_fma_f32 v[66:67], v[138:139], v[66:67], v[188:189]
	s_nop 0
	global_load_dwordx4 v[164:167], v[180:181], off
	global_load_dwordx4 v[172:175], v[180:181], off offset:64
	global_load_dwordx4 v[176:179], v[180:181], off offset:512
	global_load_dwordx4 v[188:191], v[180:181], off offset:576
	ds_read_b64 v[180:181], v184 offset:9216
	s_waitcnt lgkmcnt(0)
	v_pk_mul_f32 v[62:63], v[62:63], v[180:181] op_sel:[0,1]
	v_pk_mul_f32 v[64:65], v[64:65], v[180:181] op_sel:[0,1]
	v_pk_mul_f32 v[58:59], v[58:59], v[180:181] op_sel:[0,1]
	v_pk_mul_f32 v[60:61], v[60:61], v[180:181] op_sel:[0,1]
	v_pk_mul_f32 v[54:55], v[54:55], v[180:181] op_sel:[0,1]
	v_pk_mul_f32 v[56:57], v[56:57], v[180:181] op_sel:[0,1]
	v_pk_mul_f32 v[50:51], v[50:51], v[180:181] op_sel:[0,1]
	v_pk_mul_f32 v[52:53], v[52:53], v[180:181] op_sel:[0,1]
	s_waitcnt vmcnt(3)
	v_pk_fma_f32 v[64:65], v[136:137], v[64:65], v[166:167]
	v_pk_fma_f32 v[62:63], v[134:135], v[62:63], v[164:165]
	s_waitcnt vmcnt(2)
	v_pk_fma_f32 v[60:61], v[132:133], v[60:61], v[174:175]
	v_pk_fma_f32 v[58:59], v[130:131], v[58:59], v[172:173]
	s_waitcnt vmcnt(1)
	v_pk_fma_f32 v[56:57], v[144:145], v[56:57], v[178:179]
	v_pk_fma_f32 v[54:55], v[142:143], v[54:55], v[176:177]
	s_waitcnt vmcnt(0)
	v_pk_fma_f32 v[52:53], v[140:141], v[52:53], v[190:191]
	v_pk_fma_f32 v[50:51], v[138:139], v[50:51], v[188:189]
	v_add_u32_e32 v164, 0xa0, v150
	global_load_dwordx4 v[172:175], v[192:193], off
	global_load_dwordx4 v[176:179], v[192:193], off offset:64
	global_load_dwordx4 v[188:191], v[192:193], off offset:512
	s_nop 0
	global_load_dwordx4 v[192:195], v[192:193], off offset:576
	ds_read_b64 v[166:167], v184 offset:9344
	v_ashrrev_i32_e32 v165, 31, v164
	v_lshlrev_b64 v[180:181], 12, v[164:165]
	v_lshl_add_u64 v[180:181], s[0:1], 0, v[180:181]
	v_lshl_add_u64 v[180:181], v[180:181], 0, v[168:169]
	s_waitcnt lgkmcnt(0)
	v_pk_mul_f32 v[46:47], v[46:47], v[166:167] op_sel:[0,1]
	v_pk_mul_f32 v[48:49], v[48:49], v[166:167] op_sel:[0,1]
	v_pk_mul_f32 v[42:43], v[42:43], v[166:167] op_sel:[0,1]
	v_pk_mul_f32 v[44:45], v[44:45], v[166:167] op_sel:[0,1]
	v_pk_mul_f32 v[38:39], v[38:39], v[166:167] op_sel:[0,1]
	v_pk_mul_f32 v[40:41], v[40:41], v[166:167] op_sel:[0,1]
	v_pk_mul_f32 v[34:35], v[34:35], v[166:167] op_sel:[0,1]
	v_pk_mul_f32 v[36:37], v[36:37], v[166:167] op_sel:[0,1]
	v_add_u32_e32 v166, 0xb0, v150
	v_ashrrev_i32_e32 v167, 31, v166
	s_waitcnt vmcnt(3)
	v_pk_fma_f32 v[48:49], v[136:137], v[48:49], v[174:175]
	v_pk_fma_f32 v[46:47], v[134:135], v[46:47], v[172:173]
	s_waitcnt vmcnt(2)
	v_pk_fma_f32 v[44:45], v[132:133], v[44:45], v[178:179]
	v_pk_fma_f32 v[42:43], v[130:131], v[42:43], v[176:177]
	s_waitcnt vmcnt(1)
	v_pk_fma_f32 v[40:41], v[144:145], v[40:41], v[190:191]
	v_pk_fma_f32 v[38:39], v[142:143], v[38:39], v[188:189]
	s_waitcnt vmcnt(0)
	v_pk_fma_f32 v[36:37], v[140:141], v[36:37], v[194:195]
	v_pk_fma_f32 v[34:35], v[138:139], v[34:35], v[192:193]
	s_nop 0
	global_load_dwordx4 v[172:175], v[180:181], off
	global_load_dwordx4 v[176:179], v[180:181], off offset:64
	global_load_dwordx4 v[188:191], v[180:181], off offset:512
	global_load_dwordx4 v[192:195], v[180:181], off offset:576
	ds_read_b64 v[210:211], v184 offset:9472
	v_lshlrev_b64 v[180:181], 12, v[166:167]
	v_lshl_add_u64 v[180:181], s[0:1], 0, v[180:181]
	v_lshl_add_u64 v[168:169], v[180:181], 0, v[168:169]
	v_mov_b32_e32 v180, v119
	s_waitcnt lgkmcnt(0)
	v_pk_mul_f32 v[30:31], v[30:31], v[210:211] op_sel:[0,1]
	v_pk_mul_f32 v[32:33], v[32:33], v[210:211] op_sel:[0,1]
	v_pk_mul_f32 v[26:27], v[26:27], v[210:211] op_sel:[0,1]
	v_pk_mul_f32 v[28:29], v[28:29], v[210:211] op_sel:[0,1]
	v_pk_mul_f32 v[22:23], v[22:23], v[210:211] op_sel:[0,1]
	v_pk_mul_f32 v[24:25], v[24:25], v[210:211] op_sel:[0,1]
	v_pk_mul_f32 v[18:19], v[18:19], v[210:211] op_sel:[0,1]
	v_pk_mul_f32 v[20:21], v[20:21], v[210:211] op_sel:[0,1]
	v_mov_b32_e32 v181, v120
	s_waitcnt vmcnt(3)
	v_pk_fma_f32 v[32:33], v[136:137], v[32:33], v[174:175]
	v_pk_fma_f32 v[30:31], v[134:135], v[30:31], v[172:173]
	s_waitcnt vmcnt(2)
	v_pk_fma_f32 v[28:29], v[132:133], v[28:29], v[178:179]
	v_pk_fma_f32 v[26:27], v[130:131], v[26:27], v[176:177]
	s_waitcnt vmcnt(1)
	v_pk_fma_f32 v[24:25], v[144:145], v[24:25], v[190:191]
	v_pk_fma_f32 v[22:23], v[142:143], v[22:23], v[188:189]
	s_waitcnt vmcnt(0)
	v_pk_fma_f32 v[20:21], v[140:141], v[20:21], v[194:195]
	v_pk_fma_f32 v[18:19], v[138:139], v[18:19], v[192:193]
	v_pk_add_f32 v[172:173], v[180:181], v[196:197]
	global_load_dwordx4 v[174:177], v[168:169], off
	global_load_dwordx4 v[178:181], v[168:169], off offset:64
	global_load_dwordx4 v[188:191], v[168:169], off offset:512
	global_load_dwordx4 v[192:195], v[168:169], off offset:576
	v_add_f32_e32 v196, v204, v206
	v_add_f32_e32 v197, v205, v207
	v_add_f32_e32 v172, v172, v173
	v_add_f32_e32 v168, v196, v196
	v_add_f32_e32 v169, v196, v197
	v_add_f32_e32 v215, 0, v172
	v_add_f32_e32 v204, v208, v212
	v_add_f32_e32 v205, v209, v213
	v_add_f32_e32 v168, v116, v214
	v_add_f32_e32 v169, v169, v215
	s_nop 0
	v_add_f32_e32 v168, v204, v168
	v_add_f32_e32 v169, v205, v169
	s_nop 0
	v_add_f32_e32 v168, v168, v169
	v_mov_b32_e32 v169, v168
	s_nop 1
	v_permlane16_swap_b32_e32 v168, v169
	s_waitcnt lgkmcnt(0)
	v_add_f32_e32 v168, v168, v169
	v_mov_b32_e32 v169, v168
	s_nop 1
	v_permlane32_swap_b32_e32 v168, v169
	s_waitcnt lgkmcnt(0)
	v_add_f32_e32 v168, v168, v169
	v_fmamk_f32 v172, v168, 0xbc800000, v121
	v_fmamk_f32 v187, v168, 0xbc800000, v119
	v_fmamk_f32 v197, v168, 0xbc800000, v125
	v_fmamk_f32 v205, v168, 0xbc800000, v123
	v_fmamk_f32 v169, v168, 0xbc800000, v120
	v_fmamk_f32 v173, v168, 0xbc800000, v118
	v_fmamk_f32 v196, v168, 0xbc800000, v124
	v_fmamk_f32 v204, v168, 0xbc800000, v122
	v_fmamk_f32 v207, v168, 0xbc800000, v129
	v_fmamk_f32 v209, v168, 0xbc800000, v127
	v_mul_f32_e32 v187, v187, v187
	v_mul_f32_e32 v172, v172, v172
	v_mul_f32_e32 v205, v205, v205
	v_mul_f32_e32 v197, v197, v197
	v_fmamk_f32 v206, v168, 0xbc800000, v128
	v_fmamk_f32 v208, v168, 0xbc800000, v126
	v_fmamk_f32 v211, v168, 0xbc800000, v117
	v_fmamk_f32 v213, v168, 0xbc800000, v115
	v_mul_f32_e32 v209, v209, v209
	v_mul_f32_e32 v207, v207, v207
	v_fmac_f32_e32 v187, v173, v173
	v_fmac_f32_e32 v172, v169, v169
	v_fmac_f32_e32 v205, v204, v204
	v_fmac_f32_e32 v197, v196, v196
	v_fmamk_f32 v210, v168, 0xbc800000, v116
	v_fmamk_f32 v212, v168, 0xbc800000, v114
	v_mul_f32_e32 v213, v213, v213
	v_mul_f32_e32 v211, v211, v211
	v_fmac_f32_e32 v209, v208, v208
	v_fmac_f32_e32 v207, v206, v206
	v_add_f32_e32 v169, v187, v172
	v_add_f32_e32 v172, v205, v197
	v_fmac_f32_e32 v213, v212, v212
	v_fmac_f32_e32 v211, v210, v210
	v_add_f32_e32 v173, v209, v207
	v_add_f32_e32 v169, v169, v172
	v_add_f32_e32 v187, v213, v211
	v_add_f32_e32 v169, v173, v169
	v_add_f32_e32 v169, v187, v169
	v_mov_b32_e32 v172, v169
	s_nop 1
	v_permlane16_swap_b32_e32 v169, v172
	ds_read_b64 v[196:197], v184 offset:9600
	s_waitcnt lgkmcnt(1)
	v_add_f32_e32 v169, v169, v172
	ds_bpermute_b32 v172, v202, v169
	s_waitcnt lgkmcnt(1)
	v_mul_f32_e32 v14, v14, v197
	v_mul_f32_e32 v15, v15, v197
	v_mul_f32_e32 v16, v16, v197
	v_mul_f32_e32 v17, v17, v197
	v_mul_f32_e32 v10, v10, v197
	v_mul_f32_e32 v11, v11, v197
	v_mul_f32_e32 v12, v12, v197
	v_mul_f32_e32 v13, v13, v197
	v_mul_f32_e32 v6, v6, v197
	v_mul_f32_e32 v7, v7, v197
	v_mul_f32_e32 v8, v8, v197
	v_mul_f32_e32 v9, v9, v197
	v_mul_f32_e32 v2, v2, v197
	v_mul_f32_e32 v3, v3, v197
	v_mul_f32_e32 v4, v4, v197
	v_mul_f32_e32 v5, v5, v197
	s_waitcnt vmcnt(3)
	v_pk_fma_f32 v[16:17], v[136:137], v[16:17], v[176:177]
	v_pk_fma_f32 v[14:15], v[134:135], v[14:15], v[174:175]
	s_waitcnt vmcnt(2)
	v_pk_fma_f32 v[12:13], v[132:133], v[12:13], v[180:181]
	v_pk_fma_f32 v[10:11], v[130:131], v[10:11], v[178:179]
	s_waitcnt vmcnt(1)
	v_pk_fma_f32 v[8:9], v[144:145], v[8:9], v[190:191]
	v_pk_fma_f32 v[6:7], v[142:143], v[6:7], v[188:189]
	s_waitcnt vmcnt(0)
	v_pk_fma_f32 v[4:5], v[140:141], v[4:5], v[194:195]
	v_pk_fma_f32 v[2:3], v[138:139], v[2:3], v[192:193]
	s_nop 0
	s_and_saveexec_b64 s[0:1], s[4:5]
	s_cbranch_execz .LBB0_612
	s_lshl_b32 s17, s26, 11
	s_add_i32 s17, s27, s17
	v_mul_f32_e32 v130, 0x3c800000, v168
	s_waitcnt lgkmcnt(0)
	v_add_f32_e32 v131, v169, v172
	v_lshl_add_u32 v132, v170, 5, s17
	ds_write_b64 v132, v[130:131]
.LBB0_612:
	s_or_b64 exec, exec, s[0:1]
	v_add_f32_e32 v130, v111, v110
	v_add_f32_e32 v131, v112, v113
	v_add_f32_e32 v132, v107, v106
	v_add_f32_e32 v133, v108, v109
	v_add_f32_e32 v130, v130, v131
	v_add_f32_e32 v133, v132, v133
	v_add_f32_e32 v132, v132, v132
	v_add_f32_e32 v131, 0, v130
	v_add_f32_e32 v135, v102, v103
	v_add_f32_e32 v137, v104, v105
	v_mov_b32_e32 v136, v99
	v_add_f32_e32 v134, v98, v99
	v_add_f32_e32 v135, v135, v137
	v_add_f32_e32 v130, v100, v101
	v_add_f32_e32 v131, v133, v131
	s_nop 0
	v_add_f32_e32 v130, v134, v130
	v_add_f32_e32 v131, v135, v131
	s_nop 0
	v_add_f32_e32 v130, v130, v131
	v_mov_b32_e32 v131, v130
	s_nop 1
	v_permlane16_swap_b32_e32 v130, v131
	s_waitcnt lgkmcnt(0)
	v_add_f32_e32 v130, v130, v131
	v_mov_b32_e32 v131, v130
	s_nop 1
	v_permlane32_swap_b32_e32 v130, v131
	s_waitcnt lgkmcnt(0)
	v_add_f32_e32 v130, v130, v131
	v_fmamk_f32 v132, v130, 0xbc800000, v113
	v_fmamk_f32 v134, v130, 0xbc800000, v111
	v_fmamk_f32 v131, v130, 0xbc800000, v112
	v_fmamk_f32 v133, v130, 0xbc800000, v110
	v_mul_f32_e32 v134, v134, v134
	v_mul_f32_e32 v132, v132, v132
	v_fmac_f32_e32 v134, v133, v133
	v_fmac_f32_e32 v132, v131, v131
	v_fmamk_f32 v133, v130, 0xbc800000, v109
	v_fmamk_f32 v135, v130, 0xbc800000, v107
	v_add_f32_e32 v131, v134, v132
	v_fmamk_f32 v132, v130, 0xbc800000, v108
	v_fmamk_f32 v134, v130, 0xbc800000, v106
	v_mul_f32_e32 v135, v135, v135
	v_mul_f32_e32 v133, v133, v133
	v_fmac_f32_e32 v135, v134, v134
	v_fmac_f32_e32 v133, v132, v132
	v_add_f32_e32 v132, v135, v133
	v_fmamk_f32 v133, v130, 0xbc800000, v105
	v_fmamk_f32 v135, v130, 0xbc800000, v103
	v_add_f32_e32 v131, v131, v132
	v_fmamk_f32 v132, v130, 0xbc800000, v104
	v_fmamk_f32 v134, v130, 0xbc800000, v102
	v_mul_f32_e32 v135, v135, v135
	v_mul_f32_e32 v133, v133, v133
	v_fmac_f32_e32 v135, v134, v134
	v_fmac_f32_e32 v133, v132, v132
	v_add_f32_e32 v132, v135, v133
	v_fmamk_f32 v133, v130, 0xbc800000, v101
	v_fmamk_f32 v135, v130, 0xbc800000, v99
	v_add_f32_e32 v131, v132, v131
	v_fmamk_f32 v132, v130, 0xbc800000, v100
	v_fmamk_f32 v134, v130, 0xbc800000, v98
	v_mul_f32_e32 v135, v135, v135
	v_mul_f32_e32 v133, v133, v133
	v_fmac_f32_e32 v135, v134, v134
	v_fmac_f32_e32 v133, v132, v132
	v_add_f32_e32 v132, v135, v133
	v_add_f32_e32 v131, v132, v131
	v_mov_b32_e32 v132, v131
	s_nop 1
	v_permlane16_swap_b32_e32 v131, v132
	s_waitcnt lgkmcnt(0)
	v_add_f32_e32 v131, v131, v132
	v_mov_b32_e32 v132, v131
	s_nop 1
	v_permlane32_swap_b32_e32 v131, v132
	s_and_saveexec_b64 s[0:1], s[4:5]
	s_cbranch_execz .LBB0_614
	s_lshl_b32 s17, s26, 11
	s_add_i32 s17, s27, s17
	v_mul_f32_e32 v130, 0x3c800000, v130
	s_waitcnt lgkmcnt(0)
	v_add_f32_e32 v131, v131, v132
	v_lshl_add_u32 v132, v170, 5, s17
	ds_write_b64 v132, v[130:131] offset:512
.LBB0_614:
	s_or_b64 exec, exec, s[0:1]
	s_waitcnt lgkmcnt(0)
	v_add_f32_e32 v130, v95, v94
	v_add_f32_e32 v131, v96, v97
	v_add_f32_e32 v132, v91, v90
	v_add_f32_e32 v133, v92, v93
	v_add_f32_e32 v130, v130, v131
	v_add_f32_e32 v133, v132, v133
	v_add_f32_e32 v132, v132, v132
	v_add_f32_e32 v131, 0, v130
	v_add_f32_e32 v135, v86, v87
	v_add_f32_e32 v137, v88, v89
	v_mov_b32_e32 v136, v83
	v_add_f32_e32 v134, v82, v83
	v_add_f32_e32 v135, v135, v137
	v_add_f32_e32 v130, v84, v85
	v_add_f32_e32 v131, v133, v131
	s_nop 0
	v_add_f32_e32 v130, v134, v130
	v_add_f32_e32 v131, v135, v131
	s_nop 0
	v_add_f32_e32 v130, v130, v131
	v_mov_b32_e32 v131, v130
	s_nop 1
	v_permlane16_swap_b32_e32 v130, v131
	s_waitcnt lgkmcnt(0)
	v_add_f32_e32 v130, v130, v131
	v_mov_b32_e32 v131, v130
	s_nop 1
	v_permlane32_swap_b32_e32 v130, v131
	s_waitcnt lgkmcnt(0)
	v_add_f32_e32 v130, v130, v131
	v_fmamk_f32 v132, v130, 0xbc800000, v97
	v_fmamk_f32 v134, v130, 0xbc800000, v95
	v_fmamk_f32 v131, v130, 0xbc800000, v96
	v_fmamk_f32 v133, v130, 0xbc800000, v94
	v_mul_f32_e32 v134, v134, v134
	v_mul_f32_e32 v132, v132, v132
	v_fmac_f32_e32 v134, v133, v133
	v_fmac_f32_e32 v132, v131, v131
	v_fmamk_f32 v133, v130, 0xbc800000, v93
	v_fmamk_f32 v135, v130, 0xbc800000, v91
	v_add_f32_e32 v131, v134, v132
	v_fmamk_f32 v132, v130, 0xbc800000, v92
	v_fmamk_f32 v134, v130, 0xbc800000, v90
	v_mul_f32_e32 v135, v135, v135
	v_mul_f32_e32 v133, v133, v133
	v_fmac_f32_e32 v135, v134, v134
	v_fmac_f32_e32 v133, v132, v132
	v_add_f32_e32 v132, v135, v133
	v_fmamk_f32 v133, v130, 0xbc800000, v89
	v_fmamk_f32 v135, v130, 0xbc800000, v87
	v_add_f32_e32 v131, v131, v132
	v_fmamk_f32 v132, v130, 0xbc800000, v88
	v_fmamk_f32 v134, v130, 0xbc800000, v86
	v_mul_f32_e32 v135, v135, v135
	v_mul_f32_e32 v133, v133, v133
	v_fmac_f32_e32 v135, v134, v134
	v_fmac_f32_e32 v133, v132, v132
	v_add_f32_e32 v132, v135, v133
	v_fmamk_f32 v133, v130, 0xbc800000, v85
	v_fmamk_f32 v135, v130, 0xbc800000, v83
	v_add_f32_e32 v131, v132, v131
	v_fmamk_f32 v132, v130, 0xbc800000, v84
	v_fmamk_f32 v134, v130, 0xbc800000, v82
	v_mul_f32_e32 v135, v135, v135
	v_mul_f32_e32 v133, v133, v133
	v_fmac_f32_e32 v135, v134, v134
	v_fmac_f32_e32 v133, v132, v132
	v_add_f32_e32 v132, v135, v133
	v_add_f32_e32 v131, v132, v131
	v_mov_b32_e32 v132, v131
	s_nop 1
	v_permlane16_swap_b32_e32 v131, v132
	s_waitcnt lgkmcnt(0)
	v_add_f32_e32 v131, v131, v132
	v_mov_b32_e32 v132, v131
	s_nop 1
	v_permlane32_swap_b32_e32 v131, v132
	s_and_saveexec_b64 s[0:1], s[4:5]
	s_cbranch_execz .LBB0_616
	s_lshl_b32 s17, s26, 11
	s_add_i32 s17, s27, s17
	v_mul_f32_e32 v130, 0x3c800000, v130
	s_waitcnt lgkmcnt(0)
	v_add_f32_e32 v131, v131, v132
	v_lshl_add_u32 v132, v170, 5, s17
	ds_write_b64 v132, v[130:131] offset:1024
.LBB0_616:
	s_or_b64 exec, exec, s[0:1]
	s_waitcnt lgkmcnt(0)
	v_add_f32_e32 v130, v79, v78
	v_add_f32_e32 v131, v80, v81
	v_add_f32_e32 v132, v75, v74
	v_add_f32_e32 v133, v76, v77
	v_add_f32_e32 v130, v130, v131
	v_add_f32_e32 v133, v132, v133
	v_add_f32_e32 v132, v132, v132
	v_add_f32_e32 v131, 0, v130
	v_add_f32_e32 v135, v70, v71
	v_add_f32_e32 v137, v72, v73
	v_mov_b32_e32 v136, v67
	v_add_f32_e32 v134, v66, v67
	v_add_f32_e32 v135, v135, v137
	v_add_f32_e32 v130, v68, v69
	v_add_f32_e32 v131, v133, v131
	s_nop 0
	v_add_f32_e32 v130, v134, v130
	v_add_f32_e32 v131, v135, v131
	s_nop 0
	v_add_f32_e32 v130, v130, v131
	v_mov_b32_e32 v131, v130
	s_nop 1
	v_permlane16_swap_b32_e32 v130, v131
	s_waitcnt lgkmcnt(0)
	v_add_f32_e32 v130, v130, v131
	v_mov_b32_e32 v131, v130
	s_nop 1
	v_permlane32_swap_b32_e32 v130, v131
	s_waitcnt lgkmcnt(0)
	v_add_f32_e32 v130, v130, v131
	v_fmamk_f32 v132, v130, 0xbc800000, v81
	v_fmamk_f32 v134, v130, 0xbc800000, v79
	v_fmamk_f32 v131, v130, 0xbc800000, v80
	v_fmamk_f32 v133, v130, 0xbc800000, v78
	v_mul_f32_e32 v134, v134, v134
	v_mul_f32_e32 v132, v132, v132
	v_fmac_f32_e32 v134, v133, v133
	v_fmac_f32_e32 v132, v131, v131
	v_fmamk_f32 v133, v130, 0xbc800000, v77
	v_fmamk_f32 v135, v130, 0xbc800000, v75
	v_add_f32_e32 v131, v134, v132
	v_fmamk_f32 v132, v130, 0xbc800000, v76
	v_fmamk_f32 v134, v130, 0xbc800000, v74
	v_mul_f32_e32 v135, v135, v135
	v_mul_f32_e32 v133, v133, v133
	v_fmac_f32_e32 v135, v134, v134
	v_fmac_f32_e32 v133, v132, v132
	v_add_f32_e32 v132, v135, v133
	v_fmamk_f32 v133, v130, 0xbc800000, v73
	v_fmamk_f32 v135, v130, 0xbc800000, v71
	v_add_f32_e32 v131, v131, v132
	v_fmamk_f32 v132, v130, 0xbc800000, v72
	v_fmamk_f32 v134, v130, 0xbc800000, v70
	v_mul_f32_e32 v135, v135, v135
	v_mul_f32_e32 v133, v133, v133
	v_fmac_f32_e32 v135, v134, v134
	v_fmac_f32_e32 v133, v132, v132
	v_add_f32_e32 v132, v135, v133
	v_fmamk_f32 v133, v130, 0xbc800000, v69
	v_fmamk_f32 v135, v130, 0xbc800000, v67
	v_add_f32_e32 v131, v132, v131
	v_fmamk_f32 v132, v130, 0xbc800000, v68
	v_fmamk_f32 v134, v130, 0xbc800000, v66
	v_mul_f32_e32 v135, v135, v135
	v_mul_f32_e32 v133, v133, v133
	v_fmac_f32_e32 v135, v134, v134
	v_fmac_f32_e32 v133, v132, v132
	v_add_f32_e32 v132, v135, v133
	v_add_f32_e32 v131, v132, v131
	v_mov_b32_e32 v132, v131
	s_nop 1
	v_permlane16_swap_b32_e32 v131, v132
	s_waitcnt lgkmcnt(0)
	v_add_f32_e32 v131, v131, v132
	v_mov_b32_e32 v132, v131
	s_nop 1
	v_permlane32_swap_b32_e32 v131, v132
	s_and_saveexec_b64 s[0:1], s[4:5]
	s_cbranch_execz .LBB0_618
	s_lshl_b32 s17, s26, 11
	s_add_i32 s17, s27, s17
	v_mul_f32_e32 v130, 0x3c800000, v130
	s_waitcnt lgkmcnt(0)
	v_add_f32_e32 v131, v131, v132
	v_lshl_add_u32 v132, v170, 5, s17
	ds_write_b64 v132, v[130:131] offset:1536
.LBB0_618:
	s_or_b64 exec, exec, s[0:1]
	s_waitcnt lgkmcnt(0)
	v_add_f32_e32 v130, v63, v62
	v_add_f32_e32 v131, v64, v65
	v_add_f32_e32 v132, v59, v58
	v_add_f32_e32 v133, v60, v61
	v_add_f32_e32 v130, v130, v131
	v_add_f32_e32 v133, v132, v133
	v_add_f32_e32 v132, v132, v132
	v_add_f32_e32 v131, 0, v130
	v_add_f32_e32 v135, v54, v55
	v_add_f32_e32 v137, v56, v57
	v_mov_b32_e32 v136, v51
	v_add_f32_e32 v134, v50, v51
	v_add_f32_e32 v135, v135, v137
	v_add_f32_e32 v130, v52, v53
	v_add_f32_e32 v131, v133, v131
	s_nop 0
	v_add_f32_e32 v130, v134, v130
	v_add_f32_e32 v131, v135, v131
	s_nop 0
	v_add_f32_e32 v130, v130, v131
	v_mov_b32_e32 v131, v130
	s_nop 1
	v_permlane16_swap_b32_e32 v130, v131
	s_waitcnt lgkmcnt(0)
	v_add_f32_e32 v130, v130, v131
	v_mov_b32_e32 v131, v130
	s_nop 1
	v_permlane32_swap_b32_e32 v130, v131
	s_waitcnt lgkmcnt(0)
	v_add_f32_e32 v130, v130, v131
	v_fmamk_f32 v132, v130, 0xbc800000, v65
	v_fmamk_f32 v134, v130, 0xbc800000, v63
	v_fmamk_f32 v131, v130, 0xbc800000, v64
	v_fmamk_f32 v133, v130, 0xbc800000, v62
	v_mul_f32_e32 v134, v134, v134
	v_mul_f32_e32 v132, v132, v132
	v_fmac_f32_e32 v134, v133, v133
	v_fmac_f32_e32 v132, v131, v131
	v_fmamk_f32 v133, v130, 0xbc800000, v61
	v_fmamk_f32 v135, v130, 0xbc800000, v59
	v_add_f32_e32 v131, v134, v132
	v_fmamk_f32 v132, v130, 0xbc800000, v60
	v_fmamk_f32 v134, v130, 0xbc800000, v58
	v_mul_f32_e32 v135, v135, v135
	v_mul_f32_e32 v133, v133, v133
	v_fmac_f32_e32 v135, v134, v134
	v_fmac_f32_e32 v133, v132, v132
	v_add_f32_e32 v132, v135, v133
	v_fmamk_f32 v133, v130, 0xbc800000, v57
	v_fmamk_f32 v135, v130, 0xbc800000, v55
	v_add_f32_e32 v131, v131, v132
	v_fmamk_f32 v132, v130, 0xbc800000, v56
	v_fmamk_f32 v134, v130, 0xbc800000, v54
	v_mul_f32_e32 v135, v135, v135
	v_mul_f32_e32 v133, v133, v133
	v_fmac_f32_e32 v135, v134, v134
	v_fmac_f32_e32 v133, v132, v132
	v_add_f32_e32 v132, v135, v133
	v_fmamk_f32 v133, v130, 0xbc800000, v53
	v_fmamk_f32 v135, v130, 0xbc800000, v51
	v_add_f32_e32 v131, v132, v131
	v_fmamk_f32 v132, v130, 0xbc800000, v52
	v_fmamk_f32 v134, v130, 0xbc800000, v50
	v_mul_f32_e32 v135, v135, v135
	v_mul_f32_e32 v133, v133, v133
	v_fmac_f32_e32 v135, v134, v134
	v_fmac_f32_e32 v133, v132, v132
	v_add_f32_e32 v132, v135, v133
	v_add_f32_e32 v131, v132, v131
	v_mov_b32_e32 v132, v131
	s_nop 1
	v_permlane16_swap_b32_e32 v131, v132
	s_waitcnt lgkmcnt(0)
	v_add_f32_e32 v131, v131, v132
	v_mov_b32_e32 v132, v131
	s_nop 1
	v_permlane32_swap_b32_e32 v131, v132
	s_and_saveexec_b64 s[0:1], s[4:5]
	s_cbranch_execz .LBB0_620
	s_lshl_b32 s17, s26, 11
	s_add_i32 s17, s27, s17
	v_mul_f32_e32 v130, 0x3c800000, v130
	s_waitcnt lgkmcnt(0)
	v_add_f32_e32 v131, v131, v132
	v_lshl_add_u32 v132, v170, 5, s17
	ds_write_b64 v132, v[130:131] offset:4096
.LBB0_620:
	s_or_b64 exec, exec, s[0:1]
	s_waitcnt lgkmcnt(0)
	v_add_f32_e32 v130, v47, v46
	v_add_f32_e32 v131, v48, v49
	v_add_f32_e32 v132, v43, v42
	v_add_f32_e32 v133, v44, v45
	v_add_f32_e32 v130, v130, v131
	v_add_f32_e32 v133, v132, v133
	v_add_f32_e32 v132, v132, v132
	v_add_f32_e32 v131, 0, v130
	v_add_f32_e32 v135, v38, v39
	v_add_f32_e32 v137, v40, v41
	v_mov_b32_e32 v136, v35
	v_add_f32_e32 v134, v34, v35
	v_add_f32_e32 v135, v135, v137
	v_add_f32_e32 v130, v36, v37
	v_add_f32_e32 v131, v133, v131
	s_nop 0
	v_add_f32_e32 v130, v134, v130
	v_add_f32_e32 v131, v135, v131
	s_nop 0
	v_add_f32_e32 v130, v130, v131
	v_mov_b32_e32 v131, v130
	s_nop 1
	v_permlane16_swap_b32_e32 v130, v131
	s_waitcnt lgkmcnt(0)
	v_add_f32_e32 v130, v130, v131
	v_mov_b32_e32 v131, v130
	s_nop 1
	v_permlane32_swap_b32_e32 v130, v131
	s_waitcnt lgkmcnt(0)
	v_add_f32_e32 v130, v130, v131
	v_fmamk_f32 v132, v130, 0xbc800000, v49
	v_fmamk_f32 v134, v130, 0xbc800000, v47
	v_fmamk_f32 v131, v130, 0xbc800000, v48
	v_fmamk_f32 v133, v130, 0xbc800000, v46
	v_mul_f32_e32 v134, v134, v134
	v_mul_f32_e32 v132, v132, v132
	v_fmac_f32_e32 v134, v133, v133
	v_fmac_f32_e32 v132, v131, v131
	v_fmamk_f32 v133, v130, 0xbc800000, v45
	v_fmamk_f32 v135, v130, 0xbc800000, v43
	v_add_f32_e32 v131, v134, v132
	v_fmamk_f32 v132, v130, 0xbc800000, v44
	v_fmamk_f32 v134, v130, 0xbc800000, v42
	v_mul_f32_e32 v135, v135, v135
	v_mul_f32_e32 v133, v133, v133
	v_fmac_f32_e32 v135, v134, v134
	v_fmac_f32_e32 v133, v132, v132
	v_add_f32_e32 v132, v135, v133
	v_fmamk_f32 v133, v130, 0xbc800000, v41
	v_fmamk_f32 v135, v130, 0xbc800000, v39
	v_add_f32_e32 v131, v131, v132
	v_fmamk_f32 v132, v130, 0xbc800000, v40
	v_fmamk_f32 v134, v130, 0xbc800000, v38
	v_mul_f32_e32 v135, v135, v135
	v_mul_f32_e32 v133, v133, v133
	v_fmac_f32_e32 v135, v134, v134
	v_fmac_f32_e32 v133, v132, v132
	v_add_f32_e32 v132, v135, v133
	v_fmamk_f32 v133, v130, 0xbc800000, v37
	v_fmamk_f32 v135, v130, 0xbc800000, v35
	v_add_f32_e32 v131, v132, v131
	v_fmamk_f32 v132, v130, 0xbc800000, v36
	v_fmamk_f32 v134, v130, 0xbc800000, v34
	v_mul_f32_e32 v135, v135, v135
	v_mul_f32_e32 v133, v133, v133
	v_fmac_f32_e32 v135, v134, v134
	v_fmac_f32_e32 v133, v132, v132
	v_add_f32_e32 v132, v135, v133
	v_add_f32_e32 v131, v132, v131
	v_mov_b32_e32 v132, v131
	s_nop 1
	v_permlane16_swap_b32_e32 v131, v132
	s_waitcnt lgkmcnt(0)
	v_add_f32_e32 v131, v131, v132
	v_mov_b32_e32 v132, v131
	s_nop 1
	v_permlane32_swap_b32_e32 v131, v132
	s_and_saveexec_b64 s[0:1], s[4:5]
	s_cbranch_execz .LBB0_622
	s_lshl_b32 s17, s26, 11
	s_add_i32 s17, s27, s17
	v_mul_f32_e32 v130, 0x3c800000, v130
	s_waitcnt lgkmcnt(0)
	v_add_f32_e32 v131, v131, v132
	v_lshl_add_u32 v132, v170, 5, s17
	ds_write_b64 v132, v[130:131] offset:4608
.LBB0_622:
	s_or_b64 exec, exec, s[0:1]
	s_waitcnt lgkmcnt(0)
	v_add_f32_e32 v130, v31, v30
	v_add_f32_e32 v131, v32, v33
	v_add_f32_e32 v132, v27, v26
	v_add_f32_e32 v133, v28, v29
	v_add_f32_e32 v130, v130, v131
	v_add_f32_e32 v133, v132, v133
	v_add_f32_e32 v132, v132, v132
	v_add_f32_e32 v131, 0, v130
	v_add_f32_e32 v135, v22, v23
	v_add_f32_e32 v137, v24, v25
	v_mov_b32_e32 v136, v19
	v_add_f32_e32 v134, v18, v19
	v_add_f32_e32 v135, v135, v137
	v_add_f32_e32 v130, v20, v21
	v_add_f32_e32 v131, v133, v131
	s_nop 0
	v_add_f32_e32 v130, v134, v130
	v_add_f32_e32 v131, v135, v131
	s_nop 0
	v_add_f32_e32 v130, v130, v131
	v_mov_b32_e32 v131, v130
	s_nop 1
	v_permlane16_swap_b32_e32 v130, v131
	s_waitcnt lgkmcnt(0)
	v_add_f32_e32 v130, v130, v131
	v_mov_b32_e32 v131, v130
	s_nop 1
	v_permlane32_swap_b32_e32 v130, v131
	s_waitcnt lgkmcnt(0)
	v_add_f32_e32 v130, v130, v131
	v_fmamk_f32 v132, v130, 0xbc800000, v33
	v_fmamk_f32 v134, v130, 0xbc800000, v31
	v_fmamk_f32 v131, v130, 0xbc800000, v32
	v_fmamk_f32 v133, v130, 0xbc800000, v30
	v_mul_f32_e32 v134, v134, v134
	v_mul_f32_e32 v132, v132, v132
	v_fmac_f32_e32 v134, v133, v133
	v_fmac_f32_e32 v132, v131, v131
	v_fmamk_f32 v133, v130, 0xbc800000, v29
	v_fmamk_f32 v135, v130, 0xbc800000, v27
	v_add_f32_e32 v131, v134, v132
	v_fmamk_f32 v132, v130, 0xbc800000, v28
	v_fmamk_f32 v134, v130, 0xbc800000, v26
	v_mul_f32_e32 v135, v135, v135
	v_mul_f32_e32 v133, v133, v133
	v_fmac_f32_e32 v135, v134, v134
	v_fmac_f32_e32 v133, v132, v132
	v_add_f32_e32 v132, v135, v133
	v_fmamk_f32 v133, v130, 0xbc800000, v25
	v_fmamk_f32 v135, v130, 0xbc800000, v23
	v_add_f32_e32 v131, v131, v132
	v_fmamk_f32 v132, v130, 0xbc800000, v24
	v_fmamk_f32 v134, v130, 0xbc800000, v22
	v_mul_f32_e32 v135, v135, v135
	v_mul_f32_e32 v133, v133, v133
	v_fmac_f32_e32 v135, v134, v134
	v_fmac_f32_e32 v133, v132, v132
	v_add_f32_e32 v132, v135, v133
	v_fmamk_f32 v133, v130, 0xbc800000, v21
	v_fmamk_f32 v135, v130, 0xbc800000, v19
	v_add_f32_e32 v131, v132, v131
	v_fmamk_f32 v132, v130, 0xbc800000, v20
	v_fmamk_f32 v134, v130, 0xbc800000, v18
	v_mul_f32_e32 v135, v135, v135
	v_mul_f32_e32 v133, v133, v133
	v_fmac_f32_e32 v135, v134, v134
	v_fmac_f32_e32 v133, v132, v132
	v_add_f32_e32 v132, v135, v133
	v_add_f32_e32 v131, v132, v131
	v_mov_b32_e32 v132, v131
	s_nop 1
	v_permlane16_swap_b32_e32 v131, v132
	s_waitcnt lgkmcnt(0)
	v_add_f32_e32 v131, v131, v132
	v_mov_b32_e32 v132, v131
	s_nop 1
	v_permlane32_swap_b32_e32 v131, v132
	s_and_saveexec_b64 s[0:1], s[4:5]
	s_cbranch_execz .LBB0_624
	s_lshl_b32 s17, s26, 11
	s_add_i32 s17, s27, s17
	v_mul_f32_e32 v130, 0x3c800000, v130
	s_waitcnt lgkmcnt(0)
	v_add_f32_e32 v131, v131, v132
	v_lshl_add_u32 v132, v170, 5, s17
	ds_write_b64 v132, v[130:131] offset:5120
.LBB0_624:
	s_or_b64 exec, exec, s[0:1]
	s_waitcnt lgkmcnt(0)
	v_add_f32_e32 v130, v15, v14
	v_add_f32_e32 v131, v16, v17
	v_add_f32_e32 v132, v11, v10
	v_add_f32_e32 v133, v12, v13
	v_add_f32_e32 v130, v130, v131
	v_add_f32_e32 v133, v132, v133
	v_add_f32_e32 v132, v132, v132
	v_add_f32_e32 v131, 0, v130
	v_add_f32_e32 v135, v6, v7
	v_add_f32_e32 v137, v8, v9
	v_mov_b32_e32 v136, v3
	v_add_f32_e32 v134, v2, v3
	v_add_f32_e32 v135, v135, v137
	v_add_f32_e32 v130, v4, v5
	v_add_f32_e32 v131, v133, v131
	s_nop 0
	v_add_f32_e32 v130, v134, v130
	v_add_f32_e32 v131, v135, v131
	s_nop 0
	v_add_f32_e32 v130, v130, v131
	v_mov_b32_e32 v131, v130
	s_nop 1
	v_permlane16_swap_b32_e32 v130, v131
	s_waitcnt lgkmcnt(0)
	v_add_f32_e32 v130, v130, v131
	v_mov_b32_e32 v131, v130
	s_nop 1
	v_permlane32_swap_b32_e32 v130, v131
	s_waitcnt lgkmcnt(0)
	v_add_f32_e32 v130, v130, v131
	v_fmamk_f32 v132, v130, 0xbc800000, v17
	v_fmamk_f32 v134, v130, 0xbc800000, v15
	v_fmamk_f32 v131, v130, 0xbc800000, v16
	v_fmamk_f32 v133, v130, 0xbc800000, v14
	v_mul_f32_e32 v134, v134, v134
	v_mul_f32_e32 v132, v132, v132
	v_fmac_f32_e32 v134, v133, v133
	v_fmac_f32_e32 v132, v131, v131
	v_fmamk_f32 v133, v130, 0xbc800000, v13
	v_fmamk_f32 v135, v130, 0xbc800000, v11
	v_add_f32_e32 v131, v134, v132
	v_fmamk_f32 v132, v130, 0xbc800000, v12
	v_fmamk_f32 v134, v130, 0xbc800000, v10
	v_mul_f32_e32 v135, v135, v135
	v_mul_f32_e32 v133, v133, v133
	v_fmac_f32_e32 v135, v134, v134
	v_fmac_f32_e32 v133, v132, v132
	v_add_f32_e32 v132, v135, v133
	v_fmamk_f32 v133, v130, 0xbc800000, v9
	v_fmamk_f32 v135, v130, 0xbc800000, v7
	v_add_f32_e32 v131, v131, v132
	v_fmamk_f32 v132, v130, 0xbc800000, v8
	v_fmamk_f32 v134, v130, 0xbc800000, v6
	v_mul_f32_e32 v135, v135, v135
	v_mul_f32_e32 v133, v133, v133
	v_fmac_f32_e32 v135, v134, v134
	v_fmac_f32_e32 v133, v132, v132
	v_add_f32_e32 v132, v135, v133
	v_fmamk_f32 v133, v130, 0xbc800000, v5
	v_fmamk_f32 v135, v130, 0xbc800000, v3
	v_add_f32_e32 v131, v132, v131
	v_fmamk_f32 v132, v130, 0xbc800000, v4
	v_fmamk_f32 v134, v130, 0xbc800000, v2
	v_mul_f32_e32 v135, v135, v135
	v_mul_f32_e32 v133, v133, v133
	v_fmac_f32_e32 v135, v134, v134
	v_fmac_f32_e32 v133, v132, v132
	v_add_f32_e32 v132, v135, v133
	v_add_f32_e32 v131, v132, v131
	v_mov_b32_e32 v132, v131
	s_nop 1
	v_permlane16_swap_b32_e32 v131, v132
	s_waitcnt lgkmcnt(0)
	v_add_f32_e32 v131, v131, v132
	v_mov_b32_e32 v132, v131
	s_nop 1
	v_permlane32_swap_b32_e32 v131, v132
	s_and_saveexec_b64 s[0:1], s[4:5]
	s_cbranch_execz .LBB0_626
	s_lshl_b32 s4, s26, 11
	s_add_i32 s27, s27, s4
	v_mul_f32_e32 v130, 0x3c800000, v130
	s_waitcnt lgkmcnt(0)
	v_add_f32_e32 v131, v131, v132
	v_lshl_add_u32 v132, v170, 5, s27
	ds_write_b64 v132, v[130:131] offset:5632

.LBB0_856:
	v_add_f32_e32 v130, v127, v126
	v_add_f32_e32 v131, v128, v129
	v_add_f32_e32 v132, v123, v122
	v_add_f32_e32 v133, v124, v125
	v_add_f32_e32 v130, v130, v131
	v_add_f32_e32 v133, v132, v133
	v_add_f32_e32 v132, v132, v132
	v_add_f32_e32 v131, 0, v130
	v_add_f32_e32 v135, v118, v119
	v_add_f32_e32 v137, v120, v121
	v_mov_b32_e32 v136, v115
	v_add_f32_e32 v134, v114, v115
	v_add_f32_e32 v135, v135, v137
	v_add_f32_e32 v130, v116, v117
	v_add_f32_e32 v131, v133, v131
	v_add_f32_e32 v130, v134, v130
	v_add_f32_e32 v131, v135, v131
	v_add_f32_e32 v130, v130, v131
	v_mov_b32_e32 v131, v130
	s_nop 1
	v_permlane16_swap_b32_e32 v130, v131
	s_lshl_b32 s0, s30, 3
	s_add_i32 s28, s0, 0
	s_barrier
	s_waitcnt lgkmcnt(0)
	v_add_f32_e32 v130, v130, v131
	v_mov_b32_e32 v131, v130
	s_nop 1
	v_permlane32_swap_b32_e32 v130, v131
	s_waitcnt lgkmcnt(0)
	v_add_f32_e32 v131, v130, v131
	v_fmamk_f32 v132, v131, 0xbc800000, v129
	v_fmamk_f32 v134, v131, 0xbc800000, v127
	v_fmamk_f32 v130, v131, 0xbc800000, v128
	v_fmamk_f32 v133, v131, 0xbc800000, v126
	v_mul_f32_e32 v134, v134, v134
	v_mul_f32_e32 v132, v132, v132
	v_fmac_f32_e32 v134, v133, v133
	v_fmac_f32_e32 v132, v130, v130
	v_add_f32_e32 v130, v134, v132
	v_fmamk_f32 v133, v131, 0xbc800000, v125
	v_fmamk_f32 v135, v131, 0xbc800000, v123
	v_fmamk_f32 v132, v131, 0xbc800000, v124
	v_fmamk_f32 v134, v131, 0xbc800000, v122
	v_mul_f32_e32 v135, v135, v135
	v_mul_f32_e32 v133, v133, v133
	v_fmac_f32_e32 v135, v134, v134
	v_fmac_f32_e32 v133, v132, v132
	v_add_f32_e32 v132, v135, v133
	v_fmamk_f32 v133, v131, 0xbc800000, v121
	v_fmamk_f32 v135, v131, 0xbc800000, v119
	v_add_f32_e32 v130, v130, v132
	v_fmamk_f32 v132, v131, 0xbc800000, v120
	v_fmamk_f32 v134, v131, 0xbc800000, v118
	v_mul_f32_e32 v135, v135, v135
	v_mul_f32_e32 v133, v133, v133
	v_fmac_f32_e32 v135, v134, v134
	v_fmac_f32_e32 v133, v132, v132
	v_add_f32_e32 v132, v135, v133
	v_fmamk_f32 v133, v131, 0xbc800000, v117
	v_fmamk_f32 v135, v131, 0xbc800000, v115
	v_add_f32_e32 v130, v132, v130
	v_fmamk_f32 v132, v131, 0xbc800000, v116
	v_fmamk_f32 v134, v131, 0xbc800000, v114
	v_mul_f32_e32 v135, v135, v135
	v_mul_f32_e32 v133, v133, v133
	v_fmac_f32_e32 v135, v134, v134
	v_fmac_f32_e32 v133, v132, v132
	v_add_f32_e32 v132, v135, v133
	v_add_f32_e32 v132, v132, v130
	v_mov_b32_e32 v133, v132
	s_nop 1
	v_permlane16_swap_b32_e32 v132, v133
	v_and_b32_e32 v130, 63, v148
	v_cmp_gt_u32_e64 s[6:7], 16, v130
	s_waitcnt lgkmcnt(0)
	v_add_f32_e32 v132, v132, v133
	v_mov_b32_e32 v133, v132
	s_nop 1
	v_permlane32_swap_b32_e32 v132, v133
	s_and_saveexec_b64 s[0:1], s[6:7]
	s_cbranch_execz .LBB0_858
	s_lshl_b32 s8, s27, 11
	s_add_i32 s8, s28, s8
	v_mul_f32_e32 v134, 0x3c800000, v131
	s_waitcnt lgkmcnt(0)
	v_add_f32_e32 v135, v132, v133
	v_lshl_add_u32 v131, v170, 5, s8
	ds_write_b64 v131, v[134:135]
.LBB0_858:
	s_or_b64 exec, exec, s[0:1]
	s_waitcnt lgkmcnt(0)
	v_add_f32_e32 v132, v111, v110
	v_add_f32_e32 v133, v112, v113
	v_add_f32_e32 v134, v107, v106
	v_add_f32_e32 v135, v108, v109
	v_add_f32_e32 v131, v132, v133
	v_add_f32_e32 v135, v134, v135
	v_add_f32_e32 v134, v134, v134
	v_add_f32_e32 v133, 0, v131
	v_add_f32_e32 v137, v102, v103
	v_add_f32_e32 v139, v104, v105
	v_mov_b32_e32 v138, v99
	v_mov_b32_e32 v134, v100
	v_add_f32_e32 v136, v98, v99
	v_add_f32_e32 v137, v137, v139
	v_add_f32_e32 v132, v100, v101
	v_add_f32_e32 v133, v135, v133
	v_add_f32_e32 v132, v136, v132
	v_add_f32_e32 v133, v137, v133
	v_add_f32_e32 v131, v132, v133
	v_mov_b32_e32 v132, v131
	s_nop 1
	v_permlane16_swap_b32_e32 v131, v132
	s_waitcnt lgkmcnt(0)
	v_add_f32_e32 v131, v131, v132
	v_mov_b32_e32 v132, v131
	s_nop 1
	v_permlane32_swap_b32_e32 v131, v132
	s_waitcnt lgkmcnt(0)
	v_add_f32_e32 v131, v131, v132
	v_fmamk_f32 v133, v131, 0xbc800000, v113
	v_fmamk_f32 v135, v131, 0xbc800000, v111
	v_fmamk_f32 v132, v131, 0xbc800000, v112
	v_fmamk_f32 v134, v131, 0xbc800000, v110
	v_mul_f32_e32 v135, v135, v135
	v_mul_f32_e32 v133, v133, v133
	v_fmac_f32_e32 v135, v134, v134
	v_fmac_f32_e32 v133, v132, v132
	v_add_f32_e32 v132, v135, v133
	v_fmamk_f32 v134, v131, 0xbc800000, v109
	v_fmamk_f32 v136, v131, 0xbc800000, v107
	v_fmamk_f32 v133, v131, 0xbc800000, v108
	v_fmamk_f32 v135, v131, 0xbc800000, v106
	v_mul_f32_e32 v136, v136, v136
	v_mul_f32_e32 v134, v134, v134
	v_fmac_f32_e32 v136, v135, v135
	v_fmac_f32_e32 v134, v133, v133
	v_add_f32_e32 v133, v136, v134
	v_fmamk_f32 v134, v131, 0xbc800000, v105
	v_fmamk_f32 v136, v131, 0xbc800000, v103
	v_add_f32_e32 v132, v132, v133
	v_fmamk_f32 v133, v131, 0xbc800000, v104
	v_fmamk_f32 v135, v131, 0xbc800000, v102
	v_mul_f32_e32 v136, v136, v136
	v_mul_f32_e32 v134, v134, v134
	v_fmac_f32_e32 v136, v135, v135
	v_fmac_f32_e32 v134, v133, v133
	v_add_f32_e32 v133, v136, v134
	v_fmamk_f32 v134, v131, 0xbc800000, v101
	v_fmamk_f32 v136, v131, 0xbc800000, v99
	v_add_f32_e32 v132, v133, v132
	v_fmamk_f32 v133, v131, 0xbc800000, v100
	v_fmamk_f32 v135, v131, 0xbc800000, v98
	v_mul_f32_e32 v136, v136, v136
	v_mul_f32_e32 v134, v134, v134
	v_fmac_f32_e32 v136, v135, v135
	v_fmac_f32_e32 v134, v133, v133
	v_add_f32_e32 v133, v136, v134
	v_add_f32_e32 v132, v133, v132
	v_mov_b32_e32 v133, v132
	s_nop 1
	v_permlane16_swap_b32_e32 v132, v133
	s_waitcnt lgkmcnt(0)
	v_add_f32_e32 v132, v132, v133
	v_mov_b32_e32 v133, v132
	s_nop 1
	v_permlane32_swap_b32_e32 v132, v133
	s_and_saveexec_b64 s[0:1], s[6:7]
	s_cbranch_execz .LBB0_860
	s_lshl_b32 s8, s27, 11
	s_add_i32 s8, s28, s8
	v_mul_f32_e32 v134, 0x3c800000, v131
	s_waitcnt lgkmcnt(0)
	v_add_f32_e32 v135, v132, v133
	v_lshl_add_u32 v131, v170, 5, s8
	ds_write_b64 v131, v[134:135] offset:512
.LBB0_860:
	s_or_b64 exec, exec, s[0:1]
	s_waitcnt lgkmcnt(0)
	v_add_f32_e32 v132, v95, v94
	v_add_f32_e32 v133, v96, v97
	v_add_f32_e32 v134, v91, v90
	v_add_f32_e32 v135, v92, v93
	v_add_f32_e32 v131, v132, v133
	v_add_f32_e32 v135, v134, v135
	v_add_f32_e32 v134, v134, v134
	v_add_f32_e32 v133, 0, v131
	v_add_f32_e32 v137, v86, v87
	v_add_f32_e32 v139, v88, v89
	v_mov_b32_e32 v138, v83
	v_mov_b32_e32 v134, v84
	v_add_f32_e32 v136, v82, v83
	v_add_f32_e32 v137, v137, v139
	v_add_f32_e32 v132, v84, v85
	v_add_f32_e32 v133, v135, v133
	v_add_f32_e32 v132, v136, v132
	v_add_f32_e32 v133, v137, v133
	v_add_f32_e32 v131, v132, v133
	v_mov_b32_e32 v132, v131
	s_nop 1
	v_permlane16_swap_b32_e32 v131, v132
	s_waitcnt lgkmcnt(0)
	v_add_f32_e32 v131, v131, v132
	v_mov_b32_e32 v132, v131
	s_nop 1
	v_permlane32_swap_b32_e32 v131, v132
	s_waitcnt lgkmcnt(0)
	v_add_f32_e32 v131, v131, v132
	v_fmamk_f32 v133, v131, 0xbc800000, v97
	v_fmamk_f32 v135, v131, 0xbc800000, v95
	v_fmamk_f32 v132, v131, 0xbc800000, v96
	v_fmamk_f32 v134, v131, 0xbc800000, v94
	v_mul_f32_e32 v135, v135, v135
	v_mul_f32_e32 v133, v133, v133
	v_fmac_f32_e32 v135, v134, v134
	v_fmac_f32_e32 v133, v132, v132
	v_add_f32_e32 v132, v135, v133
	v_fmamk_f32 v134, v131, 0xbc800000, v93
	v_fmamk_f32 v136, v131, 0xbc800000, v91
	v_fmamk_f32 v133, v131, 0xbc800000, v92
	v_fmamk_f32 v135, v131, 0xbc800000, v90
	v_mul_f32_e32 v136, v136, v136
	v_mul_f32_e32 v134, v134, v134
	v_fmac_f32_e32 v136, v135, v135
	v_fmac_f32_e32 v134, v133, v133
	v_add_f32_e32 v133, v136, v134
	v_fmamk_f32 v134, v131, 0xbc800000, v89
	v_fmamk_f32 v136, v131, 0xbc800000, v87
	v_add_f32_e32 v132, v132, v133
	v_fmamk_f32 v133, v131, 0xbc800000, v88
	v_fmamk_f32 v135, v131, 0xbc800000, v86
	v_mul_f32_e32 v136, v136, v136
	v_mul_f32_e32 v134, v134, v134
	v_fmac_f32_e32 v136, v135, v135
	v_fmac_f32_e32 v134, v133, v133
	v_add_f32_e32 v133, v136, v134
	v_fmamk_f32 v134, v131, 0xbc800000, v85
	v_fmamk_f32 v136, v131, 0xbc800000, v83
	v_add_f32_e32 v132, v133, v132
	v_fmamk_f32 v133, v131, 0xbc800000, v84
	v_fmamk_f32 v135, v131, 0xbc800000, v82
	v_mul_f32_e32 v136, v136, v136
	v_mul_f32_e32 v134, v134, v134
	v_fmac_f32_e32 v136, v135, v135
	v_fmac_f32_e32 v134, v133, v133
	v_add_f32_e32 v133, v136, v134
	v_add_f32_e32 v132, v133, v132
	v_mov_b32_e32 v133, v132
	s_nop 1
	v_permlane16_swap_b32_e32 v132, v133
	s_waitcnt lgkmcnt(0)
	v_add_f32_e32 v132, v132, v133
	v_mov_b32_e32 v133, v132
	s_nop 1
	v_permlane32_swap_b32_e32 v132, v133
	s_and_saveexec_b64 s[0:1], s[6:7]
	s_cbranch_execz .LBB0_862
	s_lshl_b32 s8, s27, 11
	s_add_i32 s8, s28, s8
	v_mul_f32_e32 v134, 0x3c800000, v131
	s_waitcnt lgkmcnt(0)
	v_add_f32_e32 v135, v132, v133
	v_lshl_add_u32 v131, v170, 5, s8
	ds_write_b64 v131, v[134:135] offset:1024
.LBB0_862:
	s_or_b64 exec, exec, s[0:1]
	s_waitcnt lgkmcnt(0)
	v_add_f32_e32 v132, v79, v78
	v_add_f32_e32 v133, v80, v81
	v_add_f32_e32 v134, v75, v74
	v_add_f32_e32 v135, v76, v77
	v_add_f32_e32 v131, v132, v133
	v_add_f32_e32 v135, v134, v135
	v_add_f32_e32 v134, v134, v134
	v_add_f32_e32 v133, 0, v131
	v_add_f32_e32 v137, v70, v71
	v_add_f32_e32 v139, v72, v73
	v_mov_b32_e32 v138, v67
	v_mov_b32_e32 v134, v68
	v_add_f32_e32 v136, v66, v67
	v_add_f32_e32 v137, v137, v139
	v_add_f32_e32 v132, v68, v69
	v_add_f32_e32 v133, v135, v133
	v_add_f32_e32 v132, v136, v132
	v_add_f32_e32 v133, v137, v133
	v_add_f32_e32 v131, v132, v133
	v_mov_b32_e32 v132, v131
	s_nop 1
	v_permlane16_swap_b32_e32 v131, v132
	s_waitcnt lgkmcnt(0)
	v_add_f32_e32 v131, v131, v132
	v_mov_b32_e32 v132, v131
	s_nop 1
	v_permlane32_swap_b32_e32 v131, v132
	s_waitcnt lgkmcnt(0)
	v_add_f32_e32 v131, v131, v132
	v_fmamk_f32 v133, v131, 0xbc800000, v81
	v_fmamk_f32 v135, v131, 0xbc800000, v79
	v_fmamk_f32 v132, v131, 0xbc800000, v80
	v_fmamk_f32 v134, v131, 0xbc800000, v78
	v_mul_f32_e32 v135, v135, v135
	v_mul_f32_e32 v133, v133, v133
	v_fmac_f32_e32 v135, v134, v134
	v_fmac_f32_e32 v133, v132, v132
	v_add_f32_e32 v132, v135, v133
	v_fmamk_f32 v134, v131, 0xbc800000, v77
	v_fmamk_f32 v136, v131, 0xbc800000, v75
	v_fmamk_f32 v133, v131, 0xbc800000, v76
	v_fmamk_f32 v135, v131, 0xbc800000, v74
	v_mul_f32_e32 v136, v136, v136
	v_mul_f32_e32 v134, v134, v134
	v_fmac_f32_e32 v136, v135, v135
	v_fmac_f32_e32 v134, v133, v133
	v_add_f32_e32 v133, v136, v134
	v_fmamk_f32 v134, v131, 0xbc800000, v73
	v_fmamk_f32 v136, v131, 0xbc800000, v71
	v_add_f32_e32 v132, v132, v133
	v_fmamk_f32 v133, v131, 0xbc800000, v72
	v_fmamk_f32 v135, v131, 0xbc800000, v70
	v_mul_f32_e32 v136, v136, v136
	v_mul_f32_e32 v134, v134, v134
	v_fmac_f32_e32 v136, v135, v135
	v_fmac_f32_e32 v134, v133, v133
	v_add_f32_e32 v133, v136, v134
	v_fmamk_f32 v134, v131, 0xbc800000, v69
	v_fmamk_f32 v136, v131, 0xbc800000, v67
	v_add_f32_e32 v132, v133, v132
	v_fmamk_f32 v133, v131, 0xbc800000, v68
	v_fmamk_f32 v135, v131, 0xbc800000, v66
	v_mul_f32_e32 v136, v136, v136
	v_mul_f32_e32 v134, v134, v134
	v_fmac_f32_e32 v136, v135, v135
	v_fmac_f32_e32 v134, v133, v133
	v_add_f32_e32 v133, v136, v134
	v_add_f32_e32 v132, v133, v132
	v_mov_b32_e32 v133, v132
	s_nop 1
	v_permlane16_swap_b32_e32 v132, v133
	s_waitcnt lgkmcnt(0)
	v_add_f32_e32 v132, v132, v133
	v_mov_b32_e32 v133, v132
	s_nop 1
	v_permlane32_swap_b32_e32 v132, v133
	s_and_saveexec_b64 s[0:1], s[6:7]
	s_cbranch_execz .LBB0_864
	s_lshl_b32 s8, s27, 11
	s_add_i32 s8, s28, s8
	v_mul_f32_e32 v134, 0x3c800000, v131
	s_waitcnt lgkmcnt(0)
	v_add_f32_e32 v135, v132, v133
	v_lshl_add_u32 v131, v170, 5, s8
	ds_write_b64 v131, v[134:135] offset:1536
.LBB0_864:
	s_or_b64 exec, exec, s[0:1]
	s_waitcnt lgkmcnt(0)
	v_add_f32_e32 v132, v63, v62
	v_add_f32_e32 v133, v64, v65
	v_add_f32_e32 v134, v59, v58
	v_add_f32_e32 v135, v60, v61
	v_add_f32_e32 v131, v132, v133
	v_add_f32_e32 v135, v134, v135
	v_add_f32_e32 v134, v134, v134
	v_add_f32_e32 v133, 0, v131
	v_add_f32_e32 v137, v54, v55
	v_add_f32_e32 v139, v56, v57
	v_mov_b32_e32 v138, v51
	v_mov_b32_e32 v134, v52
	v_add_f32_e32 v136, v50, v51
	v_add_f32_e32 v137, v137, v139
	v_add_f32_e32 v132, v52, v53
	v_add_f32_e32 v133, v135, v133
	v_add_f32_e32 v132, v136, v132
	v_add_f32_e32 v133, v137, v133
	v_add_f32_e32 v131, v132, v133
	v_mov_b32_e32 v132, v131
	s_nop 1
	v_permlane16_swap_b32_e32 v131, v132
	s_waitcnt lgkmcnt(0)
	v_add_f32_e32 v131, v131, v132
	v_mov_b32_e32 v132, v131
	s_nop 1
	v_permlane32_swap_b32_e32 v131, v132
	s_waitcnt lgkmcnt(0)
	v_add_f32_e32 v131, v131, v132
	v_fmamk_f32 v133, v131, 0xbc800000, v65
	v_fmamk_f32 v135, v131, 0xbc800000, v63
	v_fmamk_f32 v132, v131, 0xbc800000, v64
	v_fmamk_f32 v134, v131, 0xbc800000, v62
	v_mul_f32_e32 v135, v135, v135
	v_mul_f32_e32 v133, v133, v133
	v_fmac_f32_e32 v135, v134, v134
	v_fmac_f32_e32 v133, v132, v132
	v_add_f32_e32 v132, v135, v133
	v_fmamk_f32 v134, v131, 0xbc800000, v61
	v_fmamk_f32 v136, v131, 0xbc800000, v59
	v_fmamk_f32 v133, v131, 0xbc800000, v60
	v_fmamk_f32 v135, v131, 0xbc800000, v58
	v_mul_f32_e32 v136, v136, v136
	v_mul_f32_e32 v134, v134, v134
	v_fmac_f32_e32 v136, v135, v135
	v_fmac_f32_e32 v134, v133, v133
	v_add_f32_e32 v133, v136, v134
	v_fmamk_f32 v134, v131, 0xbc800000, v57
	v_fmamk_f32 v136, v131, 0xbc800000, v55
	v_add_f32_e32 v132, v132, v133
	v_fmamk_f32 v133, v131, 0xbc800000, v56
	v_fmamk_f32 v135, v131, 0xbc800000, v54
	v_mul_f32_e32 v136, v136, v136
	v_mul_f32_e32 v134, v134, v134
	v_fmac_f32_e32 v136, v135, v135
	v_fmac_f32_e32 v134, v133, v133
	v_add_f32_e32 v133, v136, v134
	v_fmamk_f32 v134, v131, 0xbc800000, v53
	v_fmamk_f32 v136, v131, 0xbc800000, v51
	v_add_f32_e32 v132, v133, v132
	v_fmamk_f32 v133, v131, 0xbc800000, v52
	v_fmamk_f32 v135, v131, 0xbc800000, v50
	v_mul_f32_e32 v136, v136, v136
	v_mul_f32_e32 v134, v134, v134
	v_fmac_f32_e32 v136, v135, v135
	v_fmac_f32_e32 v134, v133, v133
	v_add_f32_e32 v133, v136, v134
	v_add_f32_e32 v132, v133, v132
	v_mov_b32_e32 v133, v132
	s_nop 1
	v_permlane16_swap_b32_e32 v132, v133
	s_waitcnt lgkmcnt(0)
	v_add_f32_e32 v132, v132, v133
	v_mov_b32_e32 v133, v132
	s_nop 1
	v_permlane32_swap_b32_e32 v132, v133
	s_and_saveexec_b64 s[0:1], s[6:7]
	s_cbranch_execz .LBB0_866
	s_lshl_b32 s8, s27, 11
	s_add_i32 s8, s28, s8
	v_mul_f32_e32 v134, 0x3c800000, v131
	s_waitcnt lgkmcnt(0)
	v_add_f32_e32 v135, v132, v133
	v_lshl_add_u32 v131, v170, 5, s8
	ds_write_b64 v131, v[134:135] offset:4096
.LBB0_866:
	s_or_b64 exec, exec, s[0:1]
	s_waitcnt lgkmcnt(0)
	v_add_f32_e32 v132, v47, v46
	v_add_f32_e32 v133, v48, v49
	v_add_f32_e32 v134, v43, v42
	v_add_f32_e32 v135, v44, v45
	v_add_f32_e32 v131, v132, v133
	v_add_f32_e32 v135, v134, v135
	v_add_f32_e32 v134, v134, v134
	v_add_f32_e32 v133, 0, v131
	v_add_f32_e32 v137, v38, v39
	v_add_f32_e32 v139, v40, v41
	v_mov_b32_e32 v138, v35
	v_mov_b32_e32 v134, v36
	v_add_f32_e32 v136, v34, v35
	v_add_f32_e32 v137, v137, v139
	v_add_f32_e32 v132, v36, v37
	v_add_f32_e32 v133, v135, v133
	v_add_f32_e32 v132, v136, v132
	v_add_f32_e32 v133, v137, v133
	v_add_f32_e32 v131, v132, v133
	v_mov_b32_e32 v132, v131
	s_nop 1
	v_permlane16_swap_b32_e32 v131, v132
	s_waitcnt lgkmcnt(0)
	v_add_f32_e32 v131, v131, v132
	v_mov_b32_e32 v132, v131
	s_nop 1
	v_permlane32_swap_b32_e32 v131, v132
	s_waitcnt lgkmcnt(0)
	v_add_f32_e32 v131, v131, v132
	v_fmamk_f32 v133, v131, 0xbc800000, v49
	v_fmamk_f32 v135, v131, 0xbc800000, v47
	v_fmamk_f32 v132, v131, 0xbc800000, v48
	v_fmamk_f32 v134, v131, 0xbc800000, v46
	v_mul_f32_e32 v135, v135, v135
	v_mul_f32_e32 v133, v133, v133
	v_fmac_f32_e32 v135, v134, v134
	v_fmac_f32_e32 v133, v132, v132
	v_add_f32_e32 v132, v135, v133
	v_fmamk_f32 v134, v131, 0xbc800000, v45
	v_fmamk_f32 v136, v131, 0xbc800000, v43
	v_fmamk_f32 v133, v131, 0xbc800000, v44
	v_fmamk_f32 v135, v131, 0xbc800000, v42
	v_mul_f32_e32 v136, v136, v136
	v_mul_f32_e32 v134, v134, v134
	v_fmac_f32_e32 v136, v135, v135
	v_fmac_f32_e32 v134, v133, v133
	v_add_f32_e32 v133, v136, v134
	v_fmamk_f32 v134, v131, 0xbc800000, v41
	v_fmamk_f32 v136, v131, 0xbc800000, v39
	v_add_f32_e32 v132, v132, v133
	v_fmamk_f32 v133, v131, 0xbc800000, v40
	v_fmamk_f32 v135, v131, 0xbc800000, v38
	v_mul_f32_e32 v136, v136, v136
	v_mul_f32_e32 v134, v134, v134
	v_fmac_f32_e32 v136, v135, v135
	v_fmac_f32_e32 v134, v133, v133
	v_add_f32_e32 v133, v136, v134
	v_fmamk_f32 v134, v131, 0xbc800000, v37
	v_fmamk_f32 v136, v131, 0xbc800000, v35
	v_add_f32_e32 v132, v133, v132
	v_fmamk_f32 v133, v131, 0xbc800000, v36
	v_fmamk_f32 v135, v131, 0xbc800000, v34
	v_mul_f32_e32 v136, v136, v136
	v_mul_f32_e32 v134, v134, v134
	v_fmac_f32_e32 v136, v135, v135
	v_fmac_f32_e32 v134, v133, v133
	v_add_f32_e32 v133, v136, v134
	v_add_f32_e32 v132, v133, v132
	v_mov_b32_e32 v133, v132
	s_nop 1
	v_permlane16_swap_b32_e32 v132, v133
	s_waitcnt lgkmcnt(0)
	v_add_f32_e32 v132, v132, v133
	v_mov_b32_e32 v133, v132
	s_nop 1
	v_permlane32_swap_b32_e32 v132, v133
	s_and_saveexec_b64 s[0:1], s[6:7]
	s_cbranch_execz .LBB0_868
	s_lshl_b32 s8, s27, 11
	s_add_i32 s8, s28, s8
	v_mul_f32_e32 v134, 0x3c800000, v131
	s_waitcnt lgkmcnt(0)
	v_add_f32_e32 v135, v132, v133
	v_lshl_add_u32 v131, v170, 5, s8
	ds_write_b64 v131, v[134:135] offset:4608
.LBB0_868:
	s_or_b64 exec, exec, s[0:1]
	s_waitcnt lgkmcnt(0)
	v_add_f32_e32 v132, v31, v30
	v_add_f32_e32 v133, v32, v33
	v_add_f32_e32 v134, v27, v26
	v_add_f32_e32 v135, v28, v29
	v_add_f32_e32 v131, v132, v133
	v_add_f32_e32 v135, v134, v135
	v_add_f32_e32 v134, v134, v134
	v_add_f32_e32 v133, 0, v131
	v_add_f32_e32 v137, v22, v23
	v_add_f32_e32 v139, v24, v25
	v_mov_b32_e32 v138, v19
	v_mov_b32_e32 v134, v20
	v_add_f32_e32 v136, v18, v19
	v_add_f32_e32 v137, v137, v139
	v_add_f32_e32 v132, v20, v21
	v_add_f32_e32 v133, v135, v133
	v_add_f32_e32 v132, v136, v132
	v_add_f32_e32 v133, v137, v133
	v_add_f32_e32 v131, v132, v133
	v_mov_b32_e32 v132, v131
	s_nop 1
	v_permlane16_swap_b32_e32 v131, v132
	s_waitcnt lgkmcnt(0)
	v_add_f32_e32 v131, v131, v132
	v_mov_b32_e32 v132, v131
	s_nop 1
	v_permlane32_swap_b32_e32 v131, v132
	s_waitcnt lgkmcnt(0)
	v_add_f32_e32 v131, v131, v132
	v_fmamk_f32 v133, v131, 0xbc800000, v33
	v_fmamk_f32 v135, v131, 0xbc800000, v31
	v_fmamk_f32 v132, v131, 0xbc800000, v32
	v_fmamk_f32 v134, v131, 0xbc800000, v30
	v_mul_f32_e32 v135, v135, v135
	v_mul_f32_e32 v133, v133, v133
	v_fmac_f32_e32 v135, v134, v134
	v_fmac_f32_e32 v133, v132, v132
	v_add_f32_e32 v132, v135, v133
	v_fmamk_f32 v134, v131, 0xbc800000, v29
	v_fmamk_f32 v136, v131, 0xbc800000, v27
	v_fmamk_f32 v133, v131, 0xbc800000, v28
	v_fmamk_f32 v135, v131, 0xbc800000, v26
	v_mul_f32_e32 v136, v136, v136
	v_mul_f32_e32 v134, v134, v134
	v_fmac_f32_e32 v136, v135, v135
	v_fmac_f32_e32 v134, v133, v133
	v_add_f32_e32 v133, v136, v134
	v_fmamk_f32 v134, v131, 0xbc800000, v25
	v_fmamk_f32 v136, v131, 0xbc800000, v23
	v_add_f32_e32 v132, v132, v133
	v_fmamk_f32 v133, v131, 0xbc800000, v24
	v_fmamk_f32 v135, v131, 0xbc800000, v22
	v_mul_f32_e32 v136, v136, v136
	v_mul_f32_e32 v134, v134, v134
	v_fmac_f32_e32 v136, v135, v135
	v_fmac_f32_e32 v134, v133, v133
	v_add_f32_e32 v133, v136, v134
	v_fmamk_f32 v134, v131, 0xbc800000, v21
	v_fmamk_f32 v136, v131, 0xbc800000, v19
	v_add_f32_e32 v132, v133, v132
	v_fmamk_f32 v133, v131, 0xbc800000, v20
	v_fmamk_f32 v135, v131, 0xbc800000, v18
	v_mul_f32_e32 v136, v136, v136
	v_mul_f32_e32 v134, v134, v134
	v_fmac_f32_e32 v136, v135, v135
	v_fmac_f32_e32 v134, v133, v133
	v_add_f32_e32 v133, v136, v134
	v_add_f32_e32 v132, v133, v132
	v_mov_b32_e32 v133, v132
	s_nop 1
	v_permlane16_swap_b32_e32 v132, v133
	s_waitcnt lgkmcnt(0)
	v_add_f32_e32 v132, v132, v133
	v_mov_b32_e32 v133, v132
	s_nop 1
	v_permlane32_swap_b32_e32 v132, v133
	s_and_saveexec_b64 s[0:1], s[6:7]
	s_cbranch_execz .LBB0_870
	s_lshl_b32 s8, s27, 11
	s_add_i32 s8, s28, s8
	v_mul_f32_e32 v134, 0x3c800000, v131
	s_waitcnt lgkmcnt(0)
	v_add_f32_e32 v135, v132, v133
	v_lshl_add_u32 v131, v170, 5, s8
	ds_write_b64 v131, v[134:135] offset:5120
.LBB0_870:
	s_or_b64 exec, exec, s[0:1]
	s_waitcnt lgkmcnt(0)
	v_add_f32_e32 v132, v15, v14
	v_add_f32_e32 v133, v16, v17
	v_add_f32_e32 v134, v11, v10
	v_add_f32_e32 v135, v12, v13
	v_add_f32_e32 v131, v132, v133
	v_add_f32_e32 v135, v134, v135
	v_add_f32_e32 v134, v134, v134
	v_add_f32_e32 v133, 0, v131
	v_add_f32_e32 v137, v6, v7
	v_add_f32_e32 v139, v8, v9
	v_mov_b32_e32 v138, v3
	v_mov_b32_e32 v134, v4
	v_add_f32_e32 v136, v2, v3
	v_add_f32_e32 v137, v137, v139
	v_add_f32_e32 v132, v4, v5
	v_add_f32_e32 v133, v135, v133
	v_add_f32_e32 v132, v136, v132
	v_add_f32_e32 v133, v137, v133
	v_add_f32_e32 v131, v132, v133
	v_mov_b32_e32 v132, v131
	s_nop 1
	v_permlane16_swap_b32_e32 v131, v132
	s_waitcnt lgkmcnt(0)
	v_add_f32_e32 v131, v131, v132
	v_mov_b32_e32 v132, v131
	s_nop 1
	v_permlane32_swap_b32_e32 v131, v132
	s_waitcnt lgkmcnt(0)
	v_add_f32_e32 v131, v131, v132
	v_fmamk_f32 v133, v131, 0xbc800000, v17
	v_fmamk_f32 v135, v131, 0xbc800000, v15
	v_fmamk_f32 v132, v131, 0xbc800000, v16
	v_fmamk_f32 v134, v131, 0xbc800000, v14
	v_mul_f32_e32 v135, v135, v135
	v_mul_f32_e32 v133, v133, v133
	v_fmac_f32_e32 v135, v134, v134
	v_fmac_f32_e32 v133, v132, v132
	v_add_f32_e32 v132, v135, v133
	v_fmamk_f32 v134, v131, 0xbc800000, v13
	v_fmamk_f32 v136, v131, 0xbc800000, v11
	v_fmamk_f32 v133, v131, 0xbc800000, v12
	v_fmamk_f32 v135, v131, 0xbc800000, v10
	v_mul_f32_e32 v136, v136, v136
	v_mul_f32_e32 v134, v134, v134
	v_fmac_f32_e32 v136, v135, v135
	v_fmac_f32_e32 v134, v133, v133
	v_add_f32_e32 v133, v136, v134
	v_fmamk_f32 v134, v131, 0xbc800000, v9
	v_fmamk_f32 v136, v131, 0xbc800000, v7
	v_add_f32_e32 v132, v132, v133
	v_fmamk_f32 v133, v131, 0xbc800000, v8
	v_fmamk_f32 v135, v131, 0xbc800000, v6
	v_mul_f32_e32 v136, v136, v136
	v_mul_f32_e32 v134, v134, v134
	v_fmac_f32_e32 v136, v135, v135
	v_fmac_f32_e32 v134, v133, v133
	v_add_f32_e32 v133, v136, v134
	v_fmamk_f32 v134, v131, 0xbc800000, v5
	v_fmamk_f32 v136, v131, 0xbc800000, v3
	v_add_f32_e32 v132, v133, v132
	v_fmamk_f32 v133, v131, 0xbc800000, v4
	v_fmamk_f32 v135, v131, 0xbc800000, v2
	v_mul_f32_e32 v136, v136, v136
	v_mul_f32_e32 v134, v134, v134
	v_fmac_f32_e32 v136, v135, v135
	v_fmac_f32_e32 v134, v133, v133
	v_add_f32_e32 v133, v136, v134
	v_add_f32_e32 v132, v133, v132
	v_mov_b32_e32 v133, v132
	s_nop 1
	v_permlane16_swap_b32_e32 v132, v133
	s_waitcnt lgkmcnt(0)
	v_add_f32_e32 v132, v132, v133
	v_mov_b32_e32 v133, v132
	s_nop 1
	v_permlane32_swap_b32_e32 v132, v133
	s_and_saveexec_b64 s[0:1], s[6:7]
	s_cbranch_execz .LBB0_872
	s_lshl_b32 s8, s27, 11
	s_add_i32 s8, s28, s8
	v_mul_f32_e32 v134, 0x3c800000, v131
	s_waitcnt lgkmcnt(0)
	v_add_f32_e32 v135, v132, v133
	v_lshl_add_u32 v131, v170, 5, s8
	ds_write_b64 v131, v[134:135] offset:5632

.LBB0_896:
	s_or_b64 exec, exec, s[20:21]
	s_lshl_b32 s0, s30, 5
	s_lshl_b32 s1, s16, 8
	s_or_b32 s0, s1, s0
	v_lshrrev_b32_e32 v130, 2, v148
	v_and_or_b32 v162, v130, 12, s0
	v_add_u32_e32 v150, s17, v152
	s_lshl_b32 s0, s26, 5
	v_ashrrev_i32_e32 v151, 31, v150
	s_and_b32 s0, s0, 0xfffffc00
	v_ashrrev_i32_e32 v163, 31, v162
	v_lshlrev_b64 v[130:131], 11, v[150:151]
	v_add_u32_e32 v132, s0, v162
	v_lshl_add_u64 v[130:131], s[56:57], 0, v[130:131]
	v_lshlrev_b64 v[168:169], 1, v[162:163]
	s_waitcnt lgkmcnt(0)
	v_ashrrev_i32_e32 v133, 31, v132
	s_waitcnt lgkmcnt(0)
	s_barrier
	v_lshl_add_u64 v[130:131], v[130:131], 0, v[168:169]
	v_lshl_add_u64 v[148:149], v[132:133], 2, s[34:35]
	s_mov_b32 s17, 0x106000
	v_add_co_u32_e32 v130, vcc, s17, v148
	s_mov_b64 s[0:1], 0x106000
	s_nop 0
	v_addc_co_u32_e32 v131, vcc, 0, v149, vcc
	global_load_dwordx4 v[138:141], v[130:131], off
	v_lshl_add_u64 v[130:131], v[148:149], 0, s[0:1]
	global_load_dwordx4 v[142:145], v[130:131], off offset:64
	global_load_dwordx4 v[134:137], v[130:131], off offset:512
	s_nop 0
	global_load_dwordx4 v[130:133], v[130:131], off offset:576
	v_lshl_add_u32 v246, v150, 11, v168
	global_load_dwordx2 v[216:217], v246, s[56:57]
	global_load_dwordx2 v[218:219], v246, s[56:57] offset:32
	global_load_dwordx2 v[220:221], v246, s[56:57] offset:256
	global_load_dwordx2 v[222:223], v246, s[56:57] offset:288
	v_add_u32_e32 v247, 0x8000, v246
	global_load_dwordx2 v[224:225], v247, s[56:57]
	global_load_dwordx2 v[232:233], v247, s[56:57] offset:32
	global_load_dwordx2 v[234:235], v247, s[56:57] offset:256
	global_load_dwordx2 v[236:237], v247, s[56:57] offset:288
	v_add_u32_e32 v247, 0x10000, v246
	global_load_dwordx2 v[238:239], v247, s[56:57]
	global_load_dwordx2 v[240:241], v247, s[56:57] offset:32
	global_load_dwordx2 v[242:243], v247, s[56:57] offset:256
	global_load_dwordx2 v[244:245], v247, s[56:57] offset:288
	v_lshl_add_u32 v185, v152, 3, 0
	ds_read_b64 v[164:165], v185 offset:8192
	v_add_u32_e32 v152, 16, v150
	v_ashrrev_i32_e32 v153, 31, v152
	v_lshlrev_b64 v[166:167], 11, v[152:153]
	v_lshl_add_u64 v[166:167], s[56:57], 0, v[166:167]
	s_waitcnt lgkmcnt(0)
	v_pk_mul_f32 v[128:129], v[128:129], v[164:165] op_sel:[0,1]
	v_pk_mul_f32 v[126:127], v[126:127], v[164:165] op_sel:[0,1]
	v_pk_mul_f32 v[122:123], v[122:123], v[164:165] op_sel:[0,1]
	v_pk_mul_f32 v[124:125], v[124:125], v[164:165] op_sel:[0,1]
	v_pk_mul_f32 v[172:173], v[118:119], v[164:165] op_sel:[0,1]
	v_pk_mul_f32 v[174:175], v[120:121], v[164:165] op_sel:[0,1]
	v_pk_mul_f32 v[114:115], v[114:115], v[164:165] op_sel:[0,1]
	v_pk_mul_f32 v[116:117], v[116:117], v[164:165] op_sel:[0,1]
	v_lshl_add_u64 v[166:167], v[166:167], 0, v[168:169]
	s_waitcnt vmcnt(11)
	v_lshlrev_b32_e32 v118, 16, v216
	v_and_b32_e32 v119, 0xffff0000, v216
	v_lshlrev_b32_e32 v120, 16, v217
	v_and_b32_e32 v121, 0xffff0000, v217
	s_waitcnt vmcnt(10)
	v_lshlrev_b32_e32 v154, 16, v218
	v_and_b32_e32 v155, 0xffff0000, v218
	v_lshlrev_b32_e32 v156, 16, v219
	v_and_b32_e32 v157, 0xffff0000, v219
	s_waitcnt vmcnt(9)
	v_lshlrev_b32_e32 v164, 16, v220
	v_and_b32_e32 v165, 0xffff0000, v220
	v_lshlrev_b32_e32 v158, 16, v221
	v_and_b32_e32 v159, 0xffff0000, v221
	s_waitcnt vmcnt(8)
	v_lshlrev_b32_e32 v176, 16, v222
	v_and_b32_e32 v177, 0xffff0000, v222
	v_lshlrev_b32_e32 v160, 16, v223
	v_and_b32_e32 v161, 0xffff0000, v223
	v_pk_fma_f32 v[118:119], v[138:139], v[126:127], v[118:119]
	v_pk_fma_f32 v[120:121], v[140:141], v[128:129], v[120:121]
	v_pk_fma_f32 v[124:125], v[144:145], v[124:125], v[156:157]
	v_pk_fma_f32 v[122:123], v[142:143], v[122:123], v[154:155]
	v_pk_fma_f32 v[128:129], v[136:137], v[174:175], v[158:159]
	v_pk_fma_f32 v[126:127], v[134:135], v[172:173], v[164:165]
	v_pk_fma_f32 v[116:117], v[132:133], v[116:117], v[160:161]
	v_pk_fma_f32 v[114:115], v[130:131], v[114:115], v[176:177]
	v_add_u32_e32 v154, 32, v150
	v_add_u32_e32 v247, 0x18000, v246
	global_load_dwordx2 v[216:217], v247, s[56:57]
	global_load_dwordx2 v[218:219], v247, s[56:57] offset:32
	global_load_dwordx2 v[220:221], v247, s[56:57] offset:256
	global_load_dwordx2 v[222:223], v247, s[56:57] offset:288
	ds_read_b64 v[166:167], v185 offset:8320
	v_ashrrev_i32_e32 v155, 31, v154
	v_lshlrev_b64 v[172:173], 11, v[154:155]
	v_lshl_add_u64 v[172:173], s[56:57], 0, v[172:173]
	v_lshl_add_u64 v[172:173], v[172:173], 0, v[168:169]
	s_waitcnt lgkmcnt(0)
	v_pk_mul_f32 v[110:111], v[110:111], v[166:167] op_sel:[0,1]
	v_pk_mul_f32 v[112:113], v[112:113], v[166:167] op_sel:[0,1]
	v_pk_mul_f32 v[106:107], v[106:107], v[166:167] op_sel:[0,1]
	v_pk_mul_f32 v[108:109], v[108:109], v[166:167] op_sel:[0,1]
	v_pk_mul_f32 v[102:103], v[102:103], v[166:167] op_sel:[0,1]
	v_pk_mul_f32 v[104:105], v[104:105], v[166:167] op_sel:[0,1]
	v_pk_mul_f32 v[98:99], v[98:99], v[166:167] op_sel:[0,1]
	v_pk_mul_f32 v[100:101], v[100:101], v[166:167] op_sel:[0,1]
	v_add_f32_e32 v195, v126, v127
	v_add_f32_e32 v205, v128, v129
	v_mov_b32_e32 v194, v114
	v_mov_b32_e32 v204, v115
	v_mov_b32_e32 v206, v117
	s_waitcnt vmcnt(11)
	v_lshlrev_b32_e32 v166, 16, v224
	v_and_b32_e32 v167, 0xffff0000, v224
	v_lshlrev_b32_e32 v156, 16, v225
	v_and_b32_e32 v157, 0xffff0000, v225
	s_waitcnt vmcnt(10)
	v_lshlrev_b32_e32 v174, 16, v232
	v_and_b32_e32 v175, 0xffff0000, v232
	v_lshlrev_b32_e32 v158, 16, v233
	v_and_b32_e32 v159, 0xffff0000, v233
	s_waitcnt vmcnt(9)
	v_lshlrev_b32_e32 v176, 16, v234
	v_and_b32_e32 v177, 0xffff0000, v234
	v_lshlrev_b32_e32 v160, 16, v235
	v_and_b32_e32 v161, 0xffff0000, v235
	s_waitcnt vmcnt(8)
	v_lshlrev_b32_e32 v178, 16, v236
	v_and_b32_e32 v179, 0xffff0000, v236
	v_lshlrev_b32_e32 v164, 16, v237
	v_and_b32_e32 v165, 0xffff0000, v237
	v_pk_fma_f32 v[112:113], v[140:141], v[112:113], v[156:157]
	v_pk_fma_f32 v[110:111], v[138:139], v[110:111], v[166:167]
	v_pk_fma_f32 v[108:109], v[144:145], v[108:109], v[158:159]
	v_pk_fma_f32 v[106:107], v[142:143], v[106:107], v[174:175]
	v_pk_fma_f32 v[104:105], v[136:137], v[104:105], v[160:161]
	v_pk_fma_f32 v[102:103], v[134:135], v[102:103], v[176:177]
	v_pk_fma_f32 v[100:101], v[132:133], v[100:101], v[164:165]
	v_pk_fma_f32 v[98:99], v[130:131], v[98:99], v[178:179]
	v_add_u32_e32 v156, 48, v150
	v_add_u32_e32 v247, 0x40000, v246
	global_load_dwordx2 v[224:225], v247, s[56:57]
	global_load_dwordx2 v[232:233], v247, s[56:57] offset:32
	global_load_dwordx2 v[234:235], v247, s[56:57] offset:256
	global_load_dwordx2 v[236:237], v247, s[56:57] offset:288
	ds_read_b64 v[172:173], v185 offset:8448
	v_ashrrev_i32_e32 v157, 31, v156
	v_lshlrev_b64 v[174:175], 11, v[156:157]
	v_lshl_add_u64 v[174:175], s[56:57], 0, v[174:175]
	v_lshl_add_u64 v[174:175], v[174:175], 0, v[168:169]
	s_waitcnt lgkmcnt(0)
	v_pk_mul_f32 v[94:95], v[94:95], v[172:173] op_sel:[0,1]
	v_pk_mul_f32 v[96:97], v[96:97], v[172:173] op_sel:[0,1]
	v_pk_mul_f32 v[90:91], v[90:91], v[172:173] op_sel:[0,1]
	v_pk_mul_f32 v[92:93], v[92:93], v[172:173] op_sel:[0,1]
	v_pk_mul_f32 v[86:87], v[86:87], v[172:173] op_sel:[0,1]
	v_pk_mul_f32 v[88:89], v[88:89], v[172:173] op_sel:[0,1]
	v_pk_mul_f32 v[82:83], v[82:83], v[172:173] op_sel:[0,1]
	v_pk_mul_f32 v[84:85], v[84:85], v[172:173] op_sel:[0,1]
	s_waitcnt vmcnt(11)
	v_lshlrev_b32_e32 v172, 16, v238
	v_and_b32_e32 v173, 0xffff0000, v238
	v_lshlrev_b32_e32 v158, 16, v239
	v_and_b32_e32 v159, 0xffff0000, v239
	s_waitcnt vmcnt(10)
	v_lshlrev_b32_e32 v176, 16, v240
	v_and_b32_e32 v177, 0xffff0000, v240
	v_lshlrev_b32_e32 v160, 16, v241
	v_and_b32_e32 v161, 0xffff0000, v241
	s_waitcnt vmcnt(9)
	v_lshlrev_b32_e32 v178, 16, v242
	v_and_b32_e32 v179, 0xffff0000, v242
	v_lshlrev_b32_e32 v164, 16, v243
	v_and_b32_e32 v165, 0xffff0000, v243
	s_waitcnt vmcnt(8)
	v_lshlrev_b32_e32 v180, 16, v244
	v_and_b32_e32 v181, 0xffff0000, v244
	v_lshlrev_b32_e32 v166, 16, v245
	v_and_b32_e32 v167, 0xffff0000, v245
	v_pk_fma_f32 v[96:97], v[140:141], v[96:97], v[158:159]
	v_pk_fma_f32 v[94:95], v[138:139], v[94:95], v[172:173]
	v_pk_fma_f32 v[92:93], v[144:145], v[92:93], v[160:161]
	v_pk_fma_f32 v[90:91], v[142:143], v[90:91], v[176:177]
	v_pk_fma_f32 v[88:89], v[136:137], v[88:89], v[164:165]
	v_pk_fma_f32 v[86:87], v[134:135], v[86:87], v[178:179]
	v_pk_fma_f32 v[84:85], v[132:133], v[84:85], v[166:167]
	v_pk_fma_f32 v[82:83], v[130:131], v[82:83], v[180:181]
	v_add_u32_e32 v158, 0x80, v150
	v_add_u32_e32 v247, 0x48000, v246
	global_load_dwordx2 v[238:239], v247, s[56:57]
	global_load_dwordx2 v[240:241], v247, s[56:57] offset:32
	global_load_dwordx2 v[242:243], v247, s[56:57] offset:256
	global_load_dwordx2 v[244:245], v247, s[56:57] offset:288
	ds_read_b64 v[174:175], v185 offset:8576
	v_ashrrev_i32_e32 v159, 31, v158
	v_lshlrev_b64 v[176:177], 11, v[158:159]
	v_lshl_add_u64 v[176:177], s[56:57], 0, v[176:177]
	v_lshl_add_u64 v[176:177], v[176:177], 0, v[168:169]
	s_waitcnt lgkmcnt(0)
	v_pk_mul_f32 v[78:79], v[78:79], v[174:175] op_sel:[0,1]
	v_pk_mul_f32 v[80:81], v[80:81], v[174:175] op_sel:[0,1]
	v_pk_mul_f32 v[74:75], v[74:75], v[174:175] op_sel:[0,1]
	v_pk_mul_f32 v[76:77], v[76:77], v[174:175] op_sel:[0,1]
	v_pk_mul_f32 v[70:71], v[70:71], v[174:175] op_sel:[0,1]
	v_pk_mul_f32 v[72:73], v[72:73], v[174:175] op_sel:[0,1]
	v_pk_mul_f32 v[66:67], v[66:67], v[174:175] op_sel:[0,1]
	v_pk_mul_f32 v[68:69], v[68:69], v[174:175] op_sel:[0,1]
	s_waitcnt vmcnt(11)
	v_lshlrev_b32_e32 v174, 16, v216
	v_and_b32_e32 v175, 0xffff0000, v216
	v_lshlrev_b32_e32 v160, 16, v217
	v_and_b32_e32 v161, 0xffff0000, v217
	s_waitcnt vmcnt(10)
	v_lshlrev_b32_e32 v178, 16, v218
	v_and_b32_e32 v179, 0xffff0000, v218
	v_lshlrev_b32_e32 v164, 16, v219
	v_and_b32_e32 v165, 0xffff0000, v219
	s_waitcnt vmcnt(9)
	v_lshlrev_b32_e32 v180, 16, v220
	v_and_b32_e32 v181, 0xffff0000, v220
	v_lshlrev_b32_e32 v166, 16, v221
	v_and_b32_e32 v167, 0xffff0000, v221
	s_waitcnt vmcnt(8)
	v_lshlrev_b32_e32 v188, 16, v222
	v_and_b32_e32 v189, 0xffff0000, v222
	v_lshlrev_b32_e32 v172, 16, v223
	v_and_b32_e32 v173, 0xffff0000, v223
	v_pk_fma_f32 v[80:81], v[140:141], v[80:81], v[160:161]
	v_pk_fma_f32 v[78:79], v[138:139], v[78:79], v[174:175]
	v_pk_fma_f32 v[76:77], v[144:145], v[76:77], v[164:165]
	v_pk_fma_f32 v[74:75], v[142:143], v[74:75], v[178:179]
	v_pk_fma_f32 v[72:73], v[136:137], v[72:73], v[166:167]
	v_pk_fma_f32 v[70:71], v[134:135], v[70:71], v[180:181]
	v_pk_fma_f32 v[68:69], v[132:133], v[68:69], v[172:173]
	v_pk_fma_f32 v[66:67], v[130:131], v[66:67], v[188:189]
	v_add_u32_e32 v160, 0x90, v150
	v_add_u32_e32 v247, 0x50000, v246
	global_load_dwordx2 v[216:217], v247, s[56:57]
	global_load_dwordx2 v[218:219], v247, s[56:57] offset:32
	global_load_dwordx2 v[220:221], v247, s[56:57] offset:256
	global_load_dwordx2 v[222:223], v247, s[56:57] offset:288
	ds_read_b64 v[176:177], v185 offset:9216
	v_ashrrev_i32_e32 v161, 31, v160
	v_lshlrev_b64 v[178:179], 11, v[160:161]
	v_lshl_add_u64 v[178:179], s[56:57], 0, v[178:179]
	v_lshl_add_u64 v[178:179], v[178:179], 0, v[168:169]
	s_waitcnt lgkmcnt(0)
	v_pk_mul_f32 v[62:63], v[62:63], v[176:177] op_sel:[0,1]
	v_pk_mul_f32 v[64:65], v[64:65], v[176:177] op_sel:[0,1]
	v_pk_mul_f32 v[58:59], v[58:59], v[176:177] op_sel:[0,1]
	v_pk_mul_f32 v[60:61], v[60:61], v[176:177] op_sel:[0,1]
	v_pk_mul_f32 v[54:55], v[54:55], v[176:177] op_sel:[0,1]
	v_pk_mul_f32 v[56:57], v[56:57], v[176:177] op_sel:[0,1]
	v_pk_mul_f32 v[50:51], v[50:51], v[176:177] op_sel:[0,1]
	v_pk_mul_f32 v[52:53], v[52:53], v[176:177] op_sel:[0,1]
	s_waitcnt vmcnt(11)
	v_lshlrev_b32_e32 v176, 16, v224
	v_and_b32_e32 v177, 0xffff0000, v224
	v_lshlrev_b32_e32 v164, 16, v225
	v_and_b32_e32 v165, 0xffff0000, v225
	s_waitcnt vmcnt(10)
	v_lshlrev_b32_e32 v180, 16, v232
	v_and_b32_e32 v181, 0xffff0000, v232
	v_lshlrev_b32_e32 v166, 16, v233
	v_and_b32_e32 v167, 0xffff0000, v233
	s_waitcnt vmcnt(9)
	v_lshlrev_b32_e32 v188, 16, v234
	v_and_b32_e32 v189, 0xffff0000, v234
	v_lshlrev_b32_e32 v172, 16, v235
	v_and_b32_e32 v173, 0xffff0000, v235
	s_waitcnt vmcnt(8)
	v_lshlrev_b32_e32 v190, 16, v236
	v_and_b32_e32 v191, 0xffff0000, v236
	v_lshlrev_b32_e32 v174, 16, v237
	v_and_b32_e32 v175, 0xffff0000, v237
	v_pk_fma_f32 v[64:65], v[140:141], v[64:65], v[164:165]
	v_pk_fma_f32 v[62:63], v[138:139], v[62:63], v[176:177]
	v_pk_fma_f32 v[60:61], v[144:145], v[60:61], v[166:167]
	v_pk_fma_f32 v[58:59], v[142:143], v[58:59], v[180:181]
	v_pk_fma_f32 v[56:57], v[136:137], v[56:57], v[172:173]
	v_pk_fma_f32 v[54:55], v[134:135], v[54:55], v[188:189]
	v_pk_fma_f32 v[52:53], v[132:133], v[52:53], v[174:175]
	v_pk_fma_f32 v[50:51], v[130:131], v[50:51], v[190:191]
	v_add_u32_e32 v164, 0xa0, v150
	v_add_u32_e32 v247, 0x58000, v246
	global_load_dwordx2 v[224:225], v247, s[56:57]
	global_load_dwordx2 v[232:233], v247, s[56:57] offset:32
	global_load_dwordx2 v[234:235], v247, s[56:57] offset:256
	global_load_dwordx2 v[236:237], v247, s[56:57] offset:288
	ds_read_b64 v[178:179], v185 offset:9344
	v_ashrrev_i32_e32 v165, 31, v164
	v_lshlrev_b64 v[180:181], 11, v[164:165]
	v_lshl_add_u64 v[180:181], s[56:57], 0, v[180:181]
	v_lshl_add_u64 v[180:181], v[180:181], 0, v[168:169]
	s_waitcnt lgkmcnt(0)
	v_pk_mul_f32 v[46:47], v[46:47], v[178:179] op_sel:[0,1]
	v_pk_mul_f32 v[48:49], v[48:49], v[178:179] op_sel:[0,1]
	v_pk_mul_f32 v[42:43], v[42:43], v[178:179] op_sel:[0,1]
	v_pk_mul_f32 v[44:45], v[44:45], v[178:179] op_sel:[0,1]
	v_pk_mul_f32 v[38:39], v[38:39], v[178:179] op_sel:[0,1]
	v_pk_mul_f32 v[40:41], v[40:41], v[178:179] op_sel:[0,1]
	v_pk_mul_f32 v[34:35], v[34:35], v[178:179] op_sel:[0,1]
	v_pk_mul_f32 v[36:37], v[36:37], v[178:179] op_sel:[0,1]
	s_waitcnt vmcnt(11)
	v_lshlrev_b32_e32 v178, 16, v238
	v_and_b32_e32 v179, 0xffff0000, v238
	v_lshlrev_b32_e32 v166, 16, v239
	v_and_b32_e32 v167, 0xffff0000, v239
	s_waitcnt vmcnt(10)
	v_lshlrev_b32_e32 v188, 16, v240
	v_and_b32_e32 v189, 0xffff0000, v240
	v_lshlrev_b32_e32 v172, 16, v241
	v_and_b32_e32 v173, 0xffff0000, v241
	s_waitcnt vmcnt(9)
	v_lshlrev_b32_e32 v190, 16, v242
	v_and_b32_e32 v191, 0xffff0000, v242
	v_lshlrev_b32_e32 v174, 16, v243
	v_and_b32_e32 v175, 0xffff0000, v243
	s_waitcnt vmcnt(8)
	v_lshlrev_b32_e32 v192, 16, v244
	v_and_b32_e32 v193, 0xffff0000, v244
	v_lshlrev_b32_e32 v176, 16, v245
	v_and_b32_e32 v177, 0xffff0000, v245
	v_pk_fma_f32 v[48:49], v[140:141], v[48:49], v[166:167]
	v_pk_fma_f32 v[46:47], v[138:139], v[46:47], v[178:179]
	v_pk_fma_f32 v[44:45], v[144:145], v[44:45], v[172:173]
	v_pk_fma_f32 v[42:43], v[142:143], v[42:43], v[188:189]
	v_pk_fma_f32 v[40:41], v[136:137], v[40:41], v[174:175]
	v_pk_fma_f32 v[38:39], v[134:135], v[38:39], v[190:191]
	v_pk_fma_f32 v[36:37], v[132:133], v[36:37], v[176:177]
	v_pk_fma_f32 v[34:35], v[130:131], v[34:35], v[192:193]
	v_add_u32_e32 v166, 0xb0, v150
	ds_read_b64 v[196:197], v185 offset:9472
	v_ashrrev_i32_e32 v167, 31, v166
	v_lshlrev_b64 v[180:181], 11, v[166:167]
	v_lshl_add_u64 v[180:181], s[56:57], 0, v[180:181]
	v_lshl_add_u64 v[168:169], v[180:181], 0, v[168:169]
	s_waitcnt lgkmcnt(0)
	v_mul_f32_e32 v30, v30, v197
	v_mul_f32_e32 v31, v31, v197
	v_mul_f32_e32 v32, v32, v197
	v_mul_f32_e32 v33, v33, v197
	v_mul_f32_e32 v26, v26, v197
	v_mul_f32_e32 v27, v27, v197
	v_mul_f32_e32 v28, v28, v197
	v_mul_f32_e32 v29, v29, v197
	v_mul_f32_e32 v22, v22, v197
	v_mul_f32_e32 v23, v23, v197
	v_mul_f32_e32 v24, v24, v197
	v_mul_f32_e32 v25, v25, v197
	v_mul_f32_e32 v18, v18, v197
	v_mul_f32_e32 v19, v19, v197
	v_mul_f32_e32 v20, v20, v197
	v_mul_f32_e32 v21, v21, v197
	s_waitcnt vmcnt(7)
	v_lshlrev_b32_e32 v196, 16, v216
	v_and_b32_e32 v197, 0xffff0000, v216
	v_lshlrev_b32_e32 v172, 16, v217
	v_and_b32_e32 v173, 0xffff0000, v217
	s_waitcnt vmcnt(5)
	v_lshlrev_b32_e32 v210, 16, v220
	v_and_b32_e32 v211, 0xffff0000, v220
	v_lshlrev_b32_e32 v176, 16, v221
	v_and_b32_e32 v177, 0xffff0000, v221
	v_pk_fma_f32 v[32:33], v[140:141], v[32:33], v[172:173]
	v_pk_fma_f32 v[24:25], v[136:137], v[24:25], v[176:177]
	v_add_f32_e32 v172, v119, v118
	v_add_f32_e32 v173, v120, v121
	v_add_f32_e32 v176, v123, v122
	v_add_f32_e32 v177, v124, v125
	v_add_f32_e32 v188, v172, v173
	v_add_f32_e32 v172, v176, v176
	v_add_f32_e32 v173, v176, v177
	s_waitcnt vmcnt(6)
	v_lshlrev_b32_e32 v208, 16, v218
	v_and_b32_e32 v209, 0xffff0000, v218
	v_lshlrev_b32_e32 v174, 16, v219
	v_and_b32_e32 v175, 0xffff0000, v219
	s_waitcnt vmcnt(4)
	v_lshlrev_b32_e32 v212, 16, v222
	v_and_b32_e32 v213, 0xffff0000, v222
	v_lshlrev_b32_e32 v178, 16, v223
	v_and_b32_e32 v179, 0xffff0000, v223
	v_add_f32_e32 v207, 0, v188
	v_pk_fma_f32 v[30:31], v[138:139], v[30:31], v[196:197]
	v_pk_fma_f32 v[28:29], v[144:145], v[28:29], v[174:175]
	v_pk_fma_f32 v[26:27], v[142:143], v[26:27], v[208:209]
	v_pk_fma_f32 v[22:23], v[134:135], v[22:23], v[210:211]
	v_pk_fma_f32 v[20:21], v[132:133], v[20:21], v[178:179]
	v_pk_fma_f32 v[18:19], v[130:131], v[18:19], v[212:213]
	v_add_f32_e32 v178, v194, v204
	v_add_f32_e32 v179, v195, v205
	v_add_f32_e32 v172, v116, v206
	v_add_f32_e32 v173, v173, v207
	v_add_f32_e32 v172, v178, v172
	v_add_f32_e32 v173, v179, v173
	v_add_f32_e32 v168, v172, v173
	v_mov_b32_e32 v169, v168
	s_nop 1
	v_permlane16_swap_b32_e32 v168, v169
	s_waitcnt lgkmcnt(0)
	v_add_f32_e32 v168, v168, v169
	v_mov_b32_e32 v169, v168
	s_nop 1
	v_permlane32_swap_b32_e32 v168, v169
	s_waitcnt lgkmcnt(0)
	v_add_f32_e32 v168, v168, v169
	v_fmamk_f32 v172, v168, 0xbc800000, v121
	v_fmamk_f32 v188, v168, 0xbc800000, v119
	v_fmamk_f32 v190, v168, 0xbc800000, v125
	v_fmamk_f32 v192, v168, 0xbc800000, v123
	v_fmamk_f32 v169, v168, 0xbc800000, v120
	v_fmamk_f32 v173, v168, 0xbc800000, v118
	v_fmamk_f32 v189, v168, 0xbc800000, v124
	v_fmamk_f32 v191, v168, 0xbc800000, v122
	v_fmamk_f32 v194, v168, 0xbc800000, v129
	v_fmamk_f32 v196, v168, 0xbc800000, v127
	v_mul_f32_e32 v188, v188, v188
	v_mul_f32_e32 v172, v172, v172
	v_mul_f32_e32 v192, v192, v192
	v_mul_f32_e32 v190, v190, v190
	v_fmamk_f32 v193, v168, 0xbc800000, v128
	v_fmamk_f32 v195, v168, 0xbc800000, v126
	v_fmamk_f32 v200, v168, 0xbc800000, v117
	v_fmamk_f32 v205, v168, 0xbc800000, v115
	v_mul_f32_e32 v196, v196, v196
	v_mul_f32_e32 v194, v194, v194
	v_fmac_f32_e32 v188, v173, v173
	v_fmac_f32_e32 v172, v169, v169
	v_fmac_f32_e32 v192, v191, v191
	v_fmac_f32_e32 v190, v189, v189
	v_fmamk_f32 v197, v168, 0xbc800000, v116
	v_fmamk_f32 v204, v168, 0xbc800000, v114
	v_mul_f32_e32 v205, v205, v205
	v_mul_f32_e32 v200, v200, v200
	v_fmac_f32_e32 v196, v195, v195
	v_fmac_f32_e32 v194, v193, v193
	v_add_f32_e32 v169, v188, v172
	v_add_f32_e32 v172, v192, v190
	v_fmac_f32_e32 v205, v204, v204
	v_fmac_f32_e32 v200, v197, v197
	v_add_f32_e32 v173, v196, v194
	v_add_f32_e32 v169, v169, v172
	v_add_f32_e32 v188, v205, v200
	v_add_f32_e32 v169, v173, v169
	v_add_f32_e32 v169, v188, v169
	v_mov_b32_e32 v172, v169
	s_nop 1
	v_permlane16_swap_b32_e32 v169, v172
	ds_read_b64 v[188:189], v185 offset:9600
	s_waitcnt lgkmcnt(1)
	v_add_f32_e32 v169, v169, v172
	ds_bpermute_b32 v172, v202, v169
	s_waitcnt lgkmcnt(1)
	v_mul_f32_e32 v14, v14, v189
	v_mul_f32_e32 v15, v15, v189
	v_mul_f32_e32 v16, v16, v189
	v_mul_f32_e32 v17, v17, v189
	v_mul_f32_e32 v10, v10, v189
	v_mul_f32_e32 v11, v11, v189
	v_mul_f32_e32 v12, v12, v189
	v_mul_f32_e32 v13, v13, v189
	v_mul_f32_e32 v6, v6, v189
	v_mul_f32_e32 v7, v7, v189
	v_mul_f32_e32 v8, v8, v189
	v_mul_f32_e32 v9, v9, v189
	v_mul_f32_e32 v2, v2, v189
	v_mul_f32_e32 v3, v3, v189
	v_mul_f32_e32 v4, v4, v189
	v_mul_f32_e32 v5, v5, v189
	s_waitcnt vmcnt(3)
	v_lshlrev_b32_e32 v188, 16, v224
	v_and_b32_e32 v189, 0xffff0000, v224
	v_lshlrev_b32_e32 v174, 16, v225
	v_and_b32_e32 v175, 0xffff0000, v225
	s_waitcnt vmcnt(2)
	v_lshlrev_b32_e32 v190, 16, v232
	v_and_b32_e32 v191, 0xffff0000, v232
	v_lshlrev_b32_e32 v180, 16, v233
	v_and_b32_e32 v181, 0xffff0000, v233
	s_waitcnt vmcnt(1)
	v_lshlrev_b32_e32 v192, 16, v234
	v_and_b32_e32 v193, 0xffff0000, v234
	v_lshlrev_b32_e32 v176, 16, v235
	v_and_b32_e32 v177, 0xffff0000, v235
	s_waitcnt vmcnt(0)
	v_lshlrev_b32_e32 v194, 16, v236
	v_and_b32_e32 v195, 0xffff0000, v236
	v_lshlrev_b32_e32 v178, 16, v237
	v_and_b32_e32 v179, 0xffff0000, v237
	v_pk_fma_f32 v[16:17], v[140:141], v[16:17], v[174:175]
	v_pk_fma_f32 v[14:15], v[138:139], v[14:15], v[188:189]
	v_pk_fma_f32 v[12:13], v[144:145], v[12:13], v[180:181]
	v_pk_fma_f32 v[10:11], v[142:143], v[10:11], v[190:191]
	v_pk_fma_f32 v[8:9], v[136:137], v[8:9], v[176:177]
	v_pk_fma_f32 v[6:7], v[134:135], v[6:7], v[192:193]
	v_pk_fma_f32 v[4:5], v[132:133], v[4:5], v[178:179]
	v_pk_fma_f32 v[2:3], v[130:131], v[2:3], v[194:195]
	s_nop 0
	s_and_saveexec_b64 s[0:1], s[6:7]
	s_cbranch_execz .LBB0_898
	s_lshl_b32 s17, s27, 11
	s_add_i32 s17, s28, s17
	v_mul_f32_e32 v130, 0x3c800000, v168
	s_waitcnt lgkmcnt(0)
	v_add_f32_e32 v131, v169, v172
	v_lshl_add_u32 v132, v170, 5, s17
	ds_write_b64 v132, v[130:131]
.LBB0_898:
	s_or_b64 exec, exec, s[0:1]
	v_add_f32_e32 v130, v111, v110
	v_add_f32_e32 v131, v112, v113
	v_add_f32_e32 v132, v107, v106
	v_add_f32_e32 v133, v108, v109
	v_add_f32_e32 v130, v130, v131
	v_add_f32_e32 v133, v132, v133
	v_add_f32_e32 v132, v132, v132
	v_add_f32_e32 v131, 0, v130
	v_add_f32_e32 v135, v102, v103
	v_add_f32_e32 v137, v104, v105
	v_mov_b32_e32 v136, v99
	v_add_f32_e32 v134, v98, v99
	v_add_f32_e32 v135, v135, v137
	v_add_f32_e32 v130, v100, v101
	v_add_f32_e32 v131, v133, v131
	s_nop 0
	v_add_f32_e32 v130, v134, v130
	v_add_f32_e32 v131, v135, v131
	s_nop 0
	v_add_f32_e32 v130, v130, v131
	v_mov_b32_e32 v131, v130
	s_nop 1
	v_permlane16_swap_b32_e32 v130, v131
	s_waitcnt lgkmcnt(0)
	v_add_f32_e32 v130, v130, v131
	v_mov_b32_e32 v131, v130
	s_nop 1
	v_permlane32_swap_b32_e32 v130, v131
	s_waitcnt lgkmcnt(0)
	v_add_f32_e32 v130, v130, v131
	v_fmamk_f32 v132, v130, 0xbc800000, v113
	v_fmamk_f32 v134, v130, 0xbc800000, v111
	v_fmamk_f32 v131, v130, 0xbc800000, v112
	v_fmamk_f32 v133, v130, 0xbc800000, v110
	v_mul_f32_e32 v134, v134, v134
	v_mul_f32_e32 v132, v132, v132
	v_fmac_f32_e32 v134, v133, v133
	v_fmac_f32_e32 v132, v131, v131
	v_fmamk_f32 v133, v130, 0xbc800000, v109
	v_fmamk_f32 v135, v130, 0xbc800000, v107
	v_add_f32_e32 v131, v134, v132
	v_fmamk_f32 v132, v130, 0xbc800000, v108
	v_fmamk_f32 v134, v130, 0xbc800000, v106
	v_mul_f32_e32 v135, v135, v135
	v_mul_f32_e32 v133, v133, v133
	v_fmac_f32_e32 v135, v134, v134
	v_fmac_f32_e32 v133, v132, v132
	v_add_f32_e32 v132, v135, v133
	v_fmamk_f32 v133, v130, 0xbc800000, v105
	v_fmamk_f32 v135, v130, 0xbc800000, v103
	v_add_f32_e32 v131, v131, v132
	v_fmamk_f32 v132, v130, 0xbc800000, v104
	v_fmamk_f32 v134, v130, 0xbc800000, v102
	v_mul_f32_e32 v135, v135, v135
	v_mul_f32_e32 v133, v133, v133
	v_fmac_f32_e32 v135, v134, v134
	v_fmac_f32_e32 v133, v132, v132
	v_add_f32_e32 v132, v135, v133
	v_fmamk_f32 v133, v130, 0xbc800000, v101
	v_fmamk_f32 v135, v130, 0xbc800000, v99
	v_add_f32_e32 v131, v132, v131
	v_fmamk_f32 v132, v130, 0xbc800000, v100
	v_fmamk_f32 v134, v130, 0xbc800000, v98
	v_mul_f32_e32 v135, v135, v135
	v_mul_f32_e32 v133, v133, v133
	v_fmac_f32_e32 v135, v134, v134
	v_fmac_f32_e32 v133, v132, v132
	v_add_f32_e32 v132, v135, v133
	v_add_f32_e32 v131, v132, v131
	v_mov_b32_e32 v132, v131
	s_nop 1
	v_permlane16_swap_b32_e32 v131, v132
	s_waitcnt lgkmcnt(0)
	v_add_f32_e32 v131, v131, v132
	v_mov_b32_e32 v132, v131
	s_nop 1
	v_permlane32_swap_b32_e32 v131, v132
	s_and_saveexec_b64 s[0:1], s[6:7]
	s_cbranch_execz .LBB0_900
	s_lshl_b32 s17, s27, 11
	s_add_i32 s17, s28, s17
	v_mul_f32_e32 v130, 0x3c800000, v130
	s_waitcnt lgkmcnt(0)
	v_add_f32_e32 v131, v131, v132
	v_lshl_add_u32 v132, v170, 5, s17
	ds_write_b64 v132, v[130:131] offset:512
.LBB0_900:
	s_or_b64 exec, exec, s[0:1]
	s_waitcnt lgkmcnt(0)
	v_add_f32_e32 v130, v95, v94
	v_add_f32_e32 v131, v96, v97
	v_add_f32_e32 v132, v91, v90
	v_add_f32_e32 v133, v92, v93
	v_add_f32_e32 v130, v130, v131
	v_add_f32_e32 v133, v132, v133
	v_add_f32_e32 v132, v132, v132
	v_add_f32_e32 v131, 0, v130
	v_add_f32_e32 v135, v86, v87
	v_add_f32_e32 v137, v88, v89
	v_mov_b32_e32 v136, v83
	v_add_f32_e32 v134, v82, v83
	v_add_f32_e32 v135, v135, v137
	v_add_f32_e32 v130, v84, v85
	v_add_f32_e32 v131, v133, v131
	s_nop 0
	v_add_f32_e32 v130, v134, v130
	v_add_f32_e32 v131, v135, v131
	s_nop 0
	v_add_f32_e32 v130, v130, v131
	v_mov_b32_e32 v131, v130
	s_nop 1
	v_permlane16_swap_b32_e32 v130, v131
	s_waitcnt lgkmcnt(0)
	v_add_f32_e32 v130, v130, v131
	v_mov_b32_e32 v131, v130
	s_nop 1
	v_permlane32_swap_b32_e32 v130, v131
	s_waitcnt lgkmcnt(0)
	v_add_f32_e32 v130, v130, v131
	v_fmamk_f32 v132, v130, 0xbc800000, v97
	v_fmamk_f32 v134, v130, 0xbc800000, v95
	v_fmamk_f32 v131, v130, 0xbc800000, v96
	v_fmamk_f32 v133, v130, 0xbc800000, v94
	v_mul_f32_e32 v134, v134, v134
	v_mul_f32_e32 v132, v132, v132
	v_fmac_f32_e32 v134, v133, v133
	v_fmac_f32_e32 v132, v131, v131
	v_fmamk_f32 v133, v130, 0xbc800000, v93
	v_fmamk_f32 v135, v130, 0xbc800000, v91
	v_add_f32_e32 v131, v134, v132
	v_fmamk_f32 v132, v130, 0xbc800000, v92
	v_fmamk_f32 v134, v130, 0xbc800000, v90
	v_mul_f32_e32 v135, v135, v135
	v_mul_f32_e32 v133, v133, v133
	v_fmac_f32_e32 v135, v134, v134
	v_fmac_f32_e32 v133, v132, v132
	v_add_f32_e32 v132, v135, v133
	v_fmamk_f32 v133, v130, 0xbc800000, v89
	v_fmamk_f32 v135, v130, 0xbc800000, v87
	v_add_f32_e32 v131, v131, v132
	v_fmamk_f32 v132, v130, 0xbc800000, v88
	v_fmamk_f32 v134, v130, 0xbc800000, v86
	v_mul_f32_e32 v135, v135, v135
	v_mul_f32_e32 v133, v133, v133
	v_fmac_f32_e32 v135, v134, v134
	v_fmac_f32_e32 v133, v132, v132
	v_add_f32_e32 v132, v135, v133
	v_fmamk_f32 v133, v130, 0xbc800000, v85
	v_fmamk_f32 v135, v130, 0xbc800000, v83
	v_add_f32_e32 v131, v132, v131
	v_fmamk_f32 v132, v130, 0xbc800000, v84
	v_fmamk_f32 v134, v130, 0xbc800000, v82
	v_mul_f32_e32 v135, v135, v135
	v_mul_f32_e32 v133, v133, v133
	v_fmac_f32_e32 v135, v134, v134
	v_fmac_f32_e32 v133, v132, v132
	v_add_f32_e32 v132, v135, v133
	v_add_f32_e32 v131, v132, v131
	v_mov_b32_e32 v132, v131
	s_nop 1
	v_permlane16_swap_b32_e32 v131, v132
	s_waitcnt lgkmcnt(0)
	v_add_f32_e32 v131, v131, v132
	v_mov_b32_e32 v132, v131
	s_nop 1
	v_permlane32_swap_b32_e32 v131, v132
	s_and_saveexec_b64 s[0:1], s[6:7]
	s_cbranch_execz .LBB0_902
	s_lshl_b32 s17, s27, 11
	s_add_i32 s17, s28, s17
	v_mul_f32_e32 v130, 0x3c800000, v130
	s_waitcnt lgkmcnt(0)
	v_add_f32_e32 v131, v131, v132
	v_lshl_add_u32 v132, v170, 5, s17
	ds_write_b64 v132, v[130:131] offset:1024
.LBB0_902:
	s_or_b64 exec, exec, s[0:1]
	s_waitcnt lgkmcnt(0)
	v_add_f32_e32 v130, v79, v78
	v_add_f32_e32 v131, v80, v81
	v_add_f32_e32 v132, v75, v74
	v_add_f32_e32 v133, v76, v77
	v_add_f32_e32 v130, v130, v131
	v_add_f32_e32 v133, v132, v133
	v_add_f32_e32 v132, v132, v132
	v_add_f32_e32 v131, 0, v130
	v_add_f32_e32 v135, v70, v71
	v_add_f32_e32 v137, v72, v73
	v_mov_b32_e32 v136, v67
	v_add_f32_e32 v134, v66, v67
	v_add_f32_e32 v135, v135, v137
	v_add_f32_e32 v130, v68, v69
	v_add_f32_e32 v131, v133, v131
	s_nop 0
	v_add_f32_e32 v130, v134, v130
	v_add_f32_e32 v131, v135, v131
	s_nop 0
	v_add_f32_e32 v130, v130, v131
	v_mov_b32_e32 v131, v130
	s_nop 1
	v_permlane16_swap_b32_e32 v130, v131
	s_waitcnt lgkmcnt(0)
	v_add_f32_e32 v130, v130, v131
	v_mov_b32_e32 v131, v130
	s_nop 1
	v_permlane32_swap_b32_e32 v130, v131
	s_waitcnt lgkmcnt(0)
	v_add_f32_e32 v130, v130, v131
	v_fmamk_f32 v132, v130, 0xbc800000, v81
	v_fmamk_f32 v134, v130, 0xbc800000, v79
	v_fmamk_f32 v131, v130, 0xbc800000, v80
	v_fmamk_f32 v133, v130, 0xbc800000, v78
	v_mul_f32_e32 v134, v134, v134
	v_mul_f32_e32 v132, v132, v132
	v_fmac_f32_e32 v134, v133, v133
	v_fmac_f32_e32 v132, v131, v131
	v_fmamk_f32 v133, v130, 0xbc800000, v77
	v_fmamk_f32 v135, v130, 0xbc800000, v75
	v_add_f32_e32 v131, v134, v132
	v_fmamk_f32 v132, v130, 0xbc800000, v76
	v_fmamk_f32 v134, v130, 0xbc800000, v74
	v_mul_f32_e32 v135, v135, v135
	v_mul_f32_e32 v133, v133, v133
	v_fmac_f32_e32 v135, v134, v134
	v_fmac_f32_e32 v133, v132, v132
	v_add_f32_e32 v132, v135, v133
	v_fmamk_f32 v133, v130, 0xbc800000, v73
	v_fmamk_f32 v135, v130, 0xbc800000, v71
	v_add_f32_e32 v131, v131, v132
	v_fmamk_f32 v132, v130, 0xbc800000, v72
	v_fmamk_f32 v134, v130, 0xbc800000, v70
	v_mul_f32_e32 v135, v135, v135
	v_mul_f32_e32 v133, v133, v133
	v_fmac_f32_e32 v135, v134, v134
	v_fmac_f32_e32 v133, v132, v132
	v_add_f32_e32 v132, v135, v133
	v_fmamk_f32 v133, v130, 0xbc800000, v69
	v_fmamk_f32 v135, v130, 0xbc800000, v67
	v_add_f32_e32 v131, v132, v131
	v_fmamk_f32 v132, v130, 0xbc800000, v68
	v_fmamk_f32 v134, v130, 0xbc800000, v66
	v_mul_f32_e32 v135, v135, v135
	v_mul_f32_e32 v133, v133, v133
	v_fmac_f32_e32 v135, v134, v134
	v_fmac_f32_e32 v133, v132, v132
	v_add_f32_e32 v132, v135, v133
	v_add_f32_e32 v131, v132, v131
	v_mov_b32_e32 v132, v131
	s_nop 1
	v_permlane16_swap_b32_e32 v131, v132
	s_waitcnt lgkmcnt(0)
	v_add_f32_e32 v131, v131, v132
	v_mov_b32_e32 v132, v131
	s_nop 1
	v_permlane32_swap_b32_e32 v131, v132
	s_and_saveexec_b64 s[0:1], s[6:7]
	s_cbranch_execz .LBB0_904
	s_lshl_b32 s17, s27, 11
	s_add_i32 s17, s28, s17
	v_mul_f32_e32 v130, 0x3c800000, v130
	s_waitcnt lgkmcnt(0)
	v_add_f32_e32 v131, v131, v132
	v_lshl_add_u32 v132, v170, 5, s17
	ds_write_b64 v132, v[130:131] offset:1536
.LBB0_904:
	s_or_b64 exec, exec, s[0:1]
	s_waitcnt lgkmcnt(0)
	v_add_f32_e32 v130, v63, v62
	v_add_f32_e32 v131, v64, v65
	v_add_f32_e32 v132, v59, v58
	v_add_f32_e32 v133, v60, v61
	v_add_f32_e32 v130, v130, v131
	v_add_f32_e32 v133, v132, v133
	v_add_f32_e32 v132, v132, v132
	v_add_f32_e32 v131, 0, v130
	v_add_f32_e32 v135, v54, v55
	v_add_f32_e32 v137, v56, v57
	v_mov_b32_e32 v136, v51
	v_add_f32_e32 v134, v50, v51
	v_add_f32_e32 v135, v135, v137
	v_add_f32_e32 v130, v52, v53
	v_add_f32_e32 v131, v133, v131
	s_nop 0
	v_add_f32_e32 v130, v134, v130
	v_add_f32_e32 v131, v135, v131
	s_nop 0
	v_add_f32_e32 v130, v130, v131
	v_mov_b32_e32 v131, v130
	s_nop 1
	v_permlane16_swap_b32_e32 v130, v131
	s_waitcnt lgkmcnt(0)
	v_add_f32_e32 v130, v130, v131
	v_mov_b32_e32 v131, v130
	s_nop 1
	v_permlane32_swap_b32_e32 v130, v131
	s_waitcnt lgkmcnt(0)
	v_add_f32_e32 v130, v130, v131
	v_fmamk_f32 v132, v130, 0xbc800000, v65
	v_fmamk_f32 v134, v130, 0xbc800000, v63
	v_fmamk_f32 v131, v130, 0xbc800000, v64
	v_fmamk_f32 v133, v130, 0xbc800000, v62
	v_mul_f32_e32 v134, v134, v134
	v_mul_f32_e32 v132, v132, v132
	v_fmac_f32_e32 v134, v133, v133
	v_fmac_f32_e32 v132, v131, v131
	v_fmamk_f32 v133, v130, 0xbc800000, v61
	v_fmamk_f32 v135, v130, 0xbc800000, v59
	v_add_f32_e32 v131, v134, v132
	v_fmamk_f32 v132, v130, 0xbc800000, v60
	v_fmamk_f32 v134, v130, 0xbc800000, v58
	v_mul_f32_e32 v135, v135, v135
	v_mul_f32_e32 v133, v133, v133
	v_fmac_f32_e32 v135, v134, v134
	v_fmac_f32_e32 v133, v132, v132
	v_add_f32_e32 v132, v135, v133
	v_fmamk_f32 v133, v130, 0xbc800000, v57
	v_fmamk_f32 v135, v130, 0xbc800000, v55
	v_add_f32_e32 v131, v131, v132
	v_fmamk_f32 v132, v130, 0xbc800000, v56
	v_fmamk_f32 v134, v130, 0xbc800000, v54
	v_mul_f32_e32 v135, v135, v135
	v_mul_f32_e32 v133, v133, v133
	v_fmac_f32_e32 v135, v134, v134
	v_fmac_f32_e32 v133, v132, v132
	v_add_f32_e32 v132, v135, v133
	v_fmamk_f32 v133, v130, 0xbc800000, v53
	v_fmamk_f32 v135, v130, 0xbc800000, v51
	v_add_f32_e32 v131, v132, v131
	v_fmamk_f32 v132, v130, 0xbc800000, v52
	v_fmamk_f32 v134, v130, 0xbc800000, v50
	v_mul_f32_e32 v135, v135, v135
	v_mul_f32_e32 v133, v133, v133
	v_fmac_f32_e32 v135, v134, v134
	v_fmac_f32_e32 v133, v132, v132
	v_add_f32_e32 v132, v135, v133
	v_add_f32_e32 v131, v132, v131
	v_mov_b32_e32 v132, v131
	s_nop 1
	v_permlane16_swap_b32_e32 v131, v132
	s_waitcnt lgkmcnt(0)
	v_add_f32_e32 v131, v131, v132
	v_mov_b32_e32 v132, v131
	s_nop 1
	v_permlane32_swap_b32_e32 v131, v132
	s_and_saveexec_b64 s[0:1], s[6:7]
	s_cbranch_execz .LBB0_906
	s_lshl_b32 s17, s27, 11
	s_add_i32 s17, s28, s17
	v_mul_f32_e32 v130, 0x3c800000, v130
	s_waitcnt lgkmcnt(0)
	v_add_f32_e32 v131, v131, v132
	v_lshl_add_u32 v132, v170, 5, s17
	ds_write_b64 v132, v[130:131] offset:4096
.LBB0_906:
	s_or_b64 exec, exec, s[0:1]
	s_waitcnt lgkmcnt(0)
	v_add_f32_e32 v130, v47, v46
	v_add_f32_e32 v131, v48, v49
	v_add_f32_e32 v132, v43, v42
	v_add_f32_e32 v133, v44, v45
	v_add_f32_e32 v130, v130, v131
	v_add_f32_e32 v133, v132, v133
	v_add_f32_e32 v132, v132, v132
	v_add_f32_e32 v131, 0, v130
	v_add_f32_e32 v135, v38, v39
	v_add_f32_e32 v137, v40, v41
	v_mov_b32_e32 v136, v35
	v_add_f32_e32 v134, v34, v35
	v_add_f32_e32 v135, v135, v137
	v_add_f32_e32 v130, v36, v37
	v_add_f32_e32 v131, v133, v131
	s_nop 0
	v_add_f32_e32 v130, v134, v130
	v_add_f32_e32 v131, v135, v131
	s_nop 0
	v_add_f32_e32 v130, v130, v131
	v_mov_b32_e32 v131, v130
	s_nop 1
	v_permlane16_swap_b32_e32 v130, v131
	s_waitcnt lgkmcnt(0)
	v_add_f32_e32 v130, v130, v131
	v_mov_b32_e32 v131, v130
	s_nop 1
	v_permlane32_swap_b32_e32 v130, v131
	s_waitcnt lgkmcnt(0)
	v_add_f32_e32 v130, v130, v131
	v_fmamk_f32 v132, v130, 0xbc800000, v49
	v_fmamk_f32 v134, v130, 0xbc800000, v47
	v_fmamk_f32 v131, v130, 0xbc800000, v48
	v_fmamk_f32 v133, v130, 0xbc800000, v46
	v_mul_f32_e32 v134, v134, v134
	v_mul_f32_e32 v132, v132, v132
	v_fmac_f32_e32 v134, v133, v133
	v_fmac_f32_e32 v132, v131, v131
	v_fmamk_f32 v133, v130, 0xbc800000, v45
	v_fmamk_f32 v135, v130, 0xbc800000, v43
	v_add_f32_e32 v131, v134, v132
	v_fmamk_f32 v132, v130, 0xbc800000, v44
	v_fmamk_f32 v134, v130, 0xbc800000, v42
	v_mul_f32_e32 v135, v135, v135
	v_mul_f32_e32 v133, v133, v133
	v_fmac_f32_e32 v135, v134, v134
	v_fmac_f32_e32 v133, v132, v132
	v_add_f32_e32 v132, v135, v133
	v_fmamk_f32 v133, v130, 0xbc800000, v41
	v_fmamk_f32 v135, v130, 0xbc800000, v39
	v_add_f32_e32 v131, v131, v132
	v_fmamk_f32 v132, v130, 0xbc800000, v40
	v_fmamk_f32 v134, v130, 0xbc800000, v38
	v_mul_f32_e32 v135, v135, v135
	v_mul_f32_e32 v133, v133, v133
	v_fmac_f32_e32 v135, v134, v134
	v_fmac_f32_e32 v133, v132, v132
	v_add_f32_e32 v132, v135, v133
	v_fmamk_f32 v133, v130, 0xbc800000, v37
	v_fmamk_f32 v135, v130, 0xbc800000, v35
	v_add_f32_e32 v131, v132, v131
	v_fmamk_f32 v132, v130, 0xbc800000, v36
	v_fmamk_f32 v134, v130, 0xbc800000, v34
	v_mul_f32_e32 v135, v135, v135
	v_mul_f32_e32 v133, v133, v133
	v_fmac_f32_e32 v135, v134, v134
	v_fmac_f32_e32 v133, v132, v132
	v_add_f32_e32 v132, v135, v133
	v_add_f32_e32 v131, v132, v131
	v_mov_b32_e32 v132, v131
	s_nop 1
	v_permlane16_swap_b32_e32 v131, v132
	s_waitcnt lgkmcnt(0)
	v_add_f32_e32 v131, v131, v132
	v_mov_b32_e32 v132, v131
	s_nop 1
	v_permlane32_swap_b32_e32 v131, v132
	s_and_saveexec_b64 s[0:1], s[6:7]
	s_cbranch_execz .LBB0_908
	s_lshl_b32 s17, s27, 11
	s_add_i32 s17, s28, s17
	v_mul_f32_e32 v130, 0x3c800000, v130
	s_waitcnt lgkmcnt(0)
	v_add_f32_e32 v131, v131, v132
	v_lshl_add_u32 v132, v170, 5, s17
	ds_write_b64 v132, v[130:131] offset:4608
.LBB0_908:
	s_or_b64 exec, exec, s[0:1]
	s_waitcnt lgkmcnt(0)
	v_add_f32_e32 v130, v31, v30
	v_add_f32_e32 v131, v32, v33
	v_add_f32_e32 v132, v27, v26
	v_add_f32_e32 v133, v28, v29
	v_add_f32_e32 v130, v130, v131
	v_add_f32_e32 v133, v132, v133
	v_add_f32_e32 v132, v132, v132
	v_add_f32_e32 v131, 0, v130
	v_add_f32_e32 v135, v22, v23
	v_add_f32_e32 v137, v24, v25
	v_mov_b32_e32 v136, v19
	v_add_f32_e32 v134, v18, v19
	v_add_f32_e32 v135, v135, v137
	v_add_f32_e32 v130, v20, v21
	v_add_f32_e32 v131, v133, v131
	s_nop 0
	v_add_f32_e32 v130, v134, v130
	v_add_f32_e32 v131, v135, v131
	s_nop 0
	v_add_f32_e32 v130, v130, v131
	v_mov_b32_e32 v131, v130
	s_nop 1
	v_permlane16_swap_b32_e32 v130, v131
	s_waitcnt lgkmcnt(0)
	v_add_f32_e32 v130, v130, v131
	v_mov_b32_e32 v131, v130
	s_nop 1
	v_permlane32_swap_b32_e32 v130, v131
	s_waitcnt lgkmcnt(0)
	v_add_f32_e32 v130, v130, v131
	v_fmamk_f32 v132, v130, 0xbc800000, v33
	v_fmamk_f32 v134, v130, 0xbc800000, v31
	v_fmamk_f32 v131, v130, 0xbc800000, v32
	v_fmamk_f32 v133, v130, 0xbc800000, v30
	v_mul_f32_e32 v134, v134, v134
	v_mul_f32_e32 v132, v132, v132
	v_fmac_f32_e32 v134, v133, v133
	v_fmac_f32_e32 v132, v131, v131
	v_fmamk_f32 v133, v130, 0xbc800000, v29
	v_fmamk_f32 v135, v130, 0xbc800000, v27
	v_add_f32_e32 v131, v134, v132
	v_fmamk_f32 v132, v130, 0xbc800000, v28
	v_fmamk_f32 v134, v130, 0xbc800000, v26
	v_mul_f32_e32 v135, v135, v135
	v_mul_f32_e32 v133, v133, v133
	v_fmac_f32_e32 v135, v134, v134
	v_fmac_f32_e32 v133, v132, v132
	v_add_f32_e32 v132, v135, v133
	v_fmamk_f32 v133, v130, 0xbc800000, v25
	v_fmamk_f32 v135, v130, 0xbc800000, v23
	v_add_f32_e32 v131, v131, v132
	v_fmamk_f32 v132, v130, 0xbc800000, v24
	v_fmamk_f32 v134, v130, 0xbc800000, v22
	v_mul_f32_e32 v135, v135, v135
	v_mul_f32_e32 v133, v133, v133
	v_fmac_f32_e32 v135, v134, v134
	v_fmac_f32_e32 v133, v132, v132
	v_add_f32_e32 v132, v135, v133
	v_fmamk_f32 v133, v130, 0xbc800000, v21
	v_fmamk_f32 v135, v130, 0xbc800000, v19
	v_add_f32_e32 v131, v132, v131
	v_fmamk_f32 v132, v130, 0xbc800000, v20
	v_fmamk_f32 v134, v130, 0xbc800000, v18
	v_mul_f32_e32 v135, v135, v135
	v_mul_f32_e32 v133, v133, v133
	v_fmac_f32_e32 v135, v134, v134
	v_fmac_f32_e32 v133, v132, v132
	v_add_f32_e32 v132, v135, v133
	v_add_f32_e32 v131, v132, v131
	v_mov_b32_e32 v132, v131
	s_nop 1
	v_permlane16_swap_b32_e32 v131, v132
	s_waitcnt lgkmcnt(0)
	v_add_f32_e32 v131, v131, v132
	v_mov_b32_e32 v132, v131
	s_nop 1
	v_permlane32_swap_b32_e32 v131, v132
	s_and_saveexec_b64 s[0:1], s[6:7]
	s_cbranch_execz .LBB0_910
	s_lshl_b32 s17, s27, 11
	s_add_i32 s17, s28, s17
	v_mul_f32_e32 v130, 0x3c800000, v130
	s_waitcnt lgkmcnt(0)
	v_add_f32_e32 v131, v131, v132
	v_lshl_add_u32 v132, v170, 5, s17
	ds_write_b64 v132, v[130:131] offset:5120
.LBB0_910:
	s_or_b64 exec, exec, s[0:1]
	s_waitcnt lgkmcnt(0)
	v_add_f32_e32 v130, v15, v14
	v_add_f32_e32 v131, v16, v17
	v_add_f32_e32 v132, v11, v10
	v_add_f32_e32 v133, v12, v13
	v_add_f32_e32 v130, v130, v131
	v_add_f32_e32 v133, v132, v133
	v_add_f32_e32 v132, v132, v132
	v_add_f32_e32 v131, 0, v130
	v_add_f32_e32 v135, v6, v7
	v_add_f32_e32 v137, v8, v9
	v_mov_b32_e32 v136, v3
	v_add_f32_e32 v134, v2, v3
	v_add_f32_e32 v135, v135, v137
	v_add_f32_e32 v130, v4, v5
	v_add_f32_e32 v131, v133, v131
	s_nop 0
	v_add_f32_e32 v130, v134, v130
	v_add_f32_e32 v131, v135, v131
	s_nop 0
	v_add_f32_e32 v130, v130, v131
	v_mov_b32_e32 v131, v130
	s_nop 1
	v_permlane16_swap_b32_e32 v130, v131
	s_waitcnt lgkmcnt(0)
	v_add_f32_e32 v130, v130, v131
	v_mov_b32_e32 v131, v130
	s_nop 1
	v_permlane32_swap_b32_e32 v130, v131
	s_waitcnt lgkmcnt(0)
	v_add_f32_e32 v130, v130, v131
	v_fmamk_f32 v132, v130, 0xbc800000, v17
	v_fmamk_f32 v134, v130, 0xbc800000, v15
	v_fmamk_f32 v131, v130, 0xbc800000, v16
	v_fmamk_f32 v133, v130, 0xbc800000, v14
	v_mul_f32_e32 v134, v134, v134
	v_mul_f32_e32 v132, v132, v132
	v_fmac_f32_e32 v134, v133, v133
	v_fmac_f32_e32 v132, v131, v131
	v_fmamk_f32 v133, v130, 0xbc800000, v13
	v_fmamk_f32 v135, v130, 0xbc800000, v11
	v_add_f32_e32 v131, v134, v132
	v_fmamk_f32 v132, v130, 0xbc800000, v12
	v_fmamk_f32 v134, v130, 0xbc800000, v10
	v_mul_f32_e32 v135, v135, v135
	v_mul_f32_e32 v133, v133, v133
	v_fmac_f32_e32 v135, v134, v134
	v_fmac_f32_e32 v133, v132, v132
	v_add_f32_e32 v132, v135, v133
	v_fmamk_f32 v133, v130, 0xbc800000, v9
	v_fmamk_f32 v135, v130, 0xbc800000, v7
	v_add_f32_e32 v131, v131, v132
	v_fmamk_f32 v132, v130, 0xbc800000, v8
	v_fmamk_f32 v134, v130, 0xbc800000, v6
	v_mul_f32_e32 v135, v135, v135
	v_mul_f32_e32 v133, v133, v133
	v_fmac_f32_e32 v135, v134, v134
	v_fmac_f32_e32 v133, v132, v132
	v_add_f32_e32 v132, v135, v133
	v_fmamk_f32 v133, v130, 0xbc800000, v5
	v_fmamk_f32 v135, v130, 0xbc800000, v3
	v_add_f32_e32 v131, v132, v131
	v_fmamk_f32 v132, v130, 0xbc800000, v4
	v_fmamk_f32 v134, v130, 0xbc800000, v2
	v_mul_f32_e32 v135, v135, v135
	v_mul_f32_e32 v133, v133, v133
	v_fmac_f32_e32 v135, v134, v134
	v_fmac_f32_e32 v133, v132, v132
	v_add_f32_e32 v132, v135, v133
	v_add_f32_e32 v131, v132, v131
	v_mov_b32_e32 v132, v131
	s_nop 1
	v_permlane16_swap_b32_e32 v131, v132
	s_waitcnt lgkmcnt(0)
	v_add_f32_e32 v131, v131, v132
	v_mov_b32_e32 v132, v131
	s_nop 1
	v_permlane32_swap_b32_e32 v131, v132
	s_and_saveexec_b64 s[0:1], s[6:7]
	s_cbranch_execz .LBB0_912
	s_lshl_b32 s6, s27, 11
	s_add_i32 s28, s28, s6
	v_mul_f32_e32 v130, 0x3c800000, v130
	s_waitcnt lgkmcnt(0)
	v_add_f32_e32 v131, v131, v132
	v_lshl_add_u32 v132, v170, 5, s28
	ds_write_b64 v132, v[130:131] offset:5632

.LBB0_1451:
	v_add_f32_e32 v130, v127, v126
	v_add_f32_e32 v131, v128, v129
	v_add_f32_e32 v132, v123, v122
	v_add_f32_e32 v133, v124, v125
	v_add_f32_e32 v130, v130, v131
	v_add_f32_e32 v133, v132, v133
	v_add_f32_e32 v132, v132, v132
	v_add_f32_e32 v131, 0, v130
	v_add_f32_e32 v135, v118, v119
	v_add_f32_e32 v137, v120, v121
	v_mov_b32_e32 v136, v115
	v_add_f32_e32 v134, v114, v115
	v_add_f32_e32 v135, v135, v137
	v_add_f32_e32 v130, v116, v117
	v_add_f32_e32 v131, v133, v131
	v_add_f32_e32 v130, v134, v130
	v_add_f32_e32 v131, v135, v131
	v_add_f32_e32 v130, v130, v131
	v_mov_b32_e32 v131, v130
	s_nop 1
	v_permlane16_swap_b32_e32 v130, v131
	s_lshl_b32 s0, s40, 3
	s_add_i32 s17, s0, 0
	s_barrier
	s_waitcnt lgkmcnt(0)
	v_add_f32_e32 v130, v130, v131
	v_mov_b32_e32 v131, v130
	s_nop 1
	v_permlane32_swap_b32_e32 v130, v131
	s_waitcnt lgkmcnt(0)
	v_add_f32_e32 v131, v130, v131
	v_fmamk_f32 v132, v131, 0xbc800000, v129
	v_fmamk_f32 v134, v131, 0xbc800000, v127
	v_fmamk_f32 v130, v131, 0xbc800000, v128
	v_fmamk_f32 v133, v131, 0xbc800000, v126
	v_mul_f32_e32 v134, v134, v134
	v_mul_f32_e32 v132, v132, v132
	v_fmac_f32_e32 v134, v133, v133
	v_fmac_f32_e32 v132, v130, v130
	v_add_f32_e32 v130, v134, v132
	v_fmamk_f32 v133, v131, 0xbc800000, v125
	v_fmamk_f32 v135, v131, 0xbc800000, v123
	v_fmamk_f32 v132, v131, 0xbc800000, v124
	v_fmamk_f32 v134, v131, 0xbc800000, v122
	v_mul_f32_e32 v135, v135, v135
	v_mul_f32_e32 v133, v133, v133
	v_fmac_f32_e32 v135, v134, v134
	v_fmac_f32_e32 v133, v132, v132
	v_add_f32_e32 v132, v135, v133
	v_fmamk_f32 v133, v131, 0xbc800000, v121
	v_fmamk_f32 v135, v131, 0xbc800000, v119
	v_add_f32_e32 v130, v130, v132
	v_fmamk_f32 v132, v131, 0xbc800000, v120
	v_fmamk_f32 v134, v131, 0xbc800000, v118
	v_mul_f32_e32 v135, v135, v135
	v_mul_f32_e32 v133, v133, v133
	v_fmac_f32_e32 v135, v134, v134
	v_fmac_f32_e32 v133, v132, v132
	v_add_f32_e32 v132, v135, v133
	v_fmamk_f32 v133, v131, 0xbc800000, v117
	v_fmamk_f32 v135, v131, 0xbc800000, v115
	v_add_f32_e32 v130, v132, v130
	v_fmamk_f32 v132, v131, 0xbc800000, v116
	v_fmamk_f32 v134, v131, 0xbc800000, v114
	v_mul_f32_e32 v135, v135, v135
	v_mul_f32_e32 v133, v133, v133
	v_fmac_f32_e32 v135, v134, v134
	v_fmac_f32_e32 v133, v132, v132
	v_add_f32_e32 v132, v135, v133
	v_add_f32_e32 v132, v132, v130
	v_mov_b32_e32 v133, v132
	s_nop 1
	v_permlane16_swap_b32_e32 v132, v133
	v_and_b32_e32 v130, 63, v148
	v_cmp_gt_u32_e64 s[6:7], 16, v130
	s_waitcnt lgkmcnt(0)
	v_add_f32_e32 v132, v132, v133
	v_mov_b32_e32 v133, v132
	s_nop 1
	v_permlane32_swap_b32_e32 v132, v133
	s_and_saveexec_b64 s[0:1], s[6:7]
	s_cbranch_execz .LBB0_1453
	s_lshl_b32 s8, s33, 11
	s_add_i32 s8, s17, s8
	v_mul_f32_e32 v134, 0x3c800000, v131
	s_waitcnt lgkmcnt(0)
	v_add_f32_e32 v135, v132, v133
	v_lshl_add_u32 v131, v170, 5, s8
	ds_write_b64 v131, v[134:135]
.LBB0_1453:
	s_or_b64 exec, exec, s[0:1]
	s_waitcnt lgkmcnt(0)
	v_add_f32_e32 v132, v111, v110
	v_add_f32_e32 v133, v112, v113
	v_add_f32_e32 v134, v107, v106
	v_add_f32_e32 v135, v108, v109
	v_add_f32_e32 v131, v132, v133
	v_add_f32_e32 v135, v134, v135
	v_add_f32_e32 v134, v134, v134
	v_add_f32_e32 v133, 0, v131
	v_add_f32_e32 v137, v102, v103
	v_add_f32_e32 v139, v104, v105
	v_mov_b32_e32 v138, v99
	v_mov_b32_e32 v134, v100
	v_add_f32_e32 v136, v98, v99
	v_add_f32_e32 v137, v137, v139
	v_add_f32_e32 v132, v100, v101
	v_add_f32_e32 v133, v135, v133
	v_add_f32_e32 v132, v136, v132
	v_add_f32_e32 v133, v137, v133
	v_add_f32_e32 v131, v132, v133
	v_mov_b32_e32 v132, v131
	s_nop 1
	v_permlane16_swap_b32_e32 v131, v132
	s_waitcnt lgkmcnt(0)
	v_add_f32_e32 v131, v131, v132
	v_mov_b32_e32 v132, v131
	s_nop 1
	v_permlane32_swap_b32_e32 v131, v132
	s_waitcnt lgkmcnt(0)
	v_add_f32_e32 v131, v131, v132
	v_fmamk_f32 v133, v131, 0xbc800000, v113
	v_fmamk_f32 v135, v131, 0xbc800000, v111
	v_fmamk_f32 v132, v131, 0xbc800000, v112
	v_fmamk_f32 v134, v131, 0xbc800000, v110
	v_mul_f32_e32 v135, v135, v135
	v_mul_f32_e32 v133, v133, v133
	v_fmac_f32_e32 v135, v134, v134
	v_fmac_f32_e32 v133, v132, v132
	v_add_f32_e32 v132, v135, v133
	v_fmamk_f32 v134, v131, 0xbc800000, v109
	v_fmamk_f32 v136, v131, 0xbc800000, v107
	v_fmamk_f32 v133, v131, 0xbc800000, v108
	v_fmamk_f32 v135, v131, 0xbc800000, v106
	v_mul_f32_e32 v136, v136, v136
	v_mul_f32_e32 v134, v134, v134
	v_fmac_f32_e32 v136, v135, v135
	v_fmac_f32_e32 v134, v133, v133
	v_add_f32_e32 v133, v136, v134
	v_fmamk_f32 v134, v131, 0xbc800000, v105
	v_fmamk_f32 v136, v131, 0xbc800000, v103
	v_add_f32_e32 v132, v132, v133
	v_fmamk_f32 v133, v131, 0xbc800000, v104
	v_fmamk_f32 v135, v131, 0xbc800000, v102
	v_mul_f32_e32 v136, v136, v136
	v_mul_f32_e32 v134, v134, v134
	v_fmac_f32_e32 v136, v135, v135
	v_fmac_f32_e32 v134, v133, v133
	v_add_f32_e32 v133, v136, v134
	v_fmamk_f32 v134, v131, 0xbc800000, v101
	v_fmamk_f32 v136, v131, 0xbc800000, v99
	v_add_f32_e32 v132, v133, v132
	v_fmamk_f32 v133, v131, 0xbc800000, v100
	v_fmamk_f32 v135, v131, 0xbc800000, v98
	v_mul_f32_e32 v136, v136, v136
	v_mul_f32_e32 v134, v134, v134
	v_fmac_f32_e32 v136, v135, v135
	v_fmac_f32_e32 v134, v133, v133
	v_add_f32_e32 v133, v136, v134
	v_add_f32_e32 v132, v133, v132
	v_mov_b32_e32 v133, v132
	s_nop 1
	v_permlane16_swap_b32_e32 v132, v133
	s_waitcnt lgkmcnt(0)
	v_add_f32_e32 v132, v132, v133
	v_mov_b32_e32 v133, v132
	s_nop 1
	v_permlane32_swap_b32_e32 v132, v133
	s_and_saveexec_b64 s[0:1], s[6:7]
	s_cbranch_execz .LBB0_1455
	s_lshl_b32 s8, s33, 11
	s_add_i32 s8, s17, s8
	v_mul_f32_e32 v134, 0x3c800000, v131
	s_waitcnt lgkmcnt(0)
	v_add_f32_e32 v135, v132, v133
	v_lshl_add_u32 v131, v170, 5, s8
	ds_write_b64 v131, v[134:135] offset:512
.LBB0_1455:
	s_or_b64 exec, exec, s[0:1]
	s_waitcnt lgkmcnt(0)
	v_add_f32_e32 v132, v95, v94
	v_add_f32_e32 v133, v96, v97
	v_add_f32_e32 v134, v91, v90
	v_add_f32_e32 v135, v92, v93
	v_add_f32_e32 v131, v132, v133
	v_add_f32_e32 v135, v134, v135
	v_add_f32_e32 v134, v134, v134
	v_add_f32_e32 v133, 0, v131
	v_add_f32_e32 v137, v86, v87
	v_add_f32_e32 v139, v88, v89
	v_mov_b32_e32 v138, v83
	v_mov_b32_e32 v134, v84
	v_add_f32_e32 v136, v82, v83
	v_add_f32_e32 v137, v137, v139
	v_add_f32_e32 v132, v84, v85
	v_add_f32_e32 v133, v135, v133
	v_add_f32_e32 v132, v136, v132
	v_add_f32_e32 v133, v137, v133
	v_add_f32_e32 v131, v132, v133
	v_mov_b32_e32 v132, v131
	s_nop 1
	v_permlane16_swap_b32_e32 v131, v132
	s_waitcnt lgkmcnt(0)
	v_add_f32_e32 v131, v131, v132
	v_mov_b32_e32 v132, v131
	s_nop 1
	v_permlane32_swap_b32_e32 v131, v132
	s_waitcnt lgkmcnt(0)
	v_add_f32_e32 v131, v131, v132
	v_fmamk_f32 v133, v131, 0xbc800000, v97
	v_fmamk_f32 v135, v131, 0xbc800000, v95
	v_fmamk_f32 v132, v131, 0xbc800000, v96
	v_fmamk_f32 v134, v131, 0xbc800000, v94
	v_mul_f32_e32 v135, v135, v135
	v_mul_f32_e32 v133, v133, v133
	v_fmac_f32_e32 v135, v134, v134
	v_fmac_f32_e32 v133, v132, v132
	v_add_f32_e32 v132, v135, v133
	v_fmamk_f32 v134, v131, 0xbc800000, v93
	v_fmamk_f32 v136, v131, 0xbc800000, v91
	v_fmamk_f32 v133, v131, 0xbc800000, v92
	v_fmamk_f32 v135, v131, 0xbc800000, v90
	v_mul_f32_e32 v136, v136, v136
	v_mul_f32_e32 v134, v134, v134
	v_fmac_f32_e32 v136, v135, v135
	v_fmac_f32_e32 v134, v133, v133
	v_add_f32_e32 v133, v136, v134
	v_fmamk_f32 v134, v131, 0xbc800000, v89
	v_fmamk_f32 v136, v131, 0xbc800000, v87
	v_add_f32_e32 v132, v132, v133
	v_fmamk_f32 v133, v131, 0xbc800000, v88
	v_fmamk_f32 v135, v131, 0xbc800000, v86
	v_mul_f32_e32 v136, v136, v136
	v_mul_f32_e32 v134, v134, v134
	v_fmac_f32_e32 v136, v135, v135
	v_fmac_f32_e32 v134, v133, v133
	v_add_f32_e32 v133, v136, v134
	v_fmamk_f32 v134, v131, 0xbc800000, v85
	v_fmamk_f32 v136, v131, 0xbc800000, v83
	v_add_f32_e32 v132, v133, v132
	v_fmamk_f32 v133, v131, 0xbc800000, v84
	v_fmamk_f32 v135, v131, 0xbc800000, v82
	v_mul_f32_e32 v136, v136, v136
	v_mul_f32_e32 v134, v134, v134
	v_fmac_f32_e32 v136, v135, v135
	v_fmac_f32_e32 v134, v133, v133
	v_add_f32_e32 v133, v136, v134
	v_add_f32_e32 v132, v133, v132
	v_mov_b32_e32 v133, v132
	s_nop 1
	v_permlane16_swap_b32_e32 v132, v133
	s_waitcnt lgkmcnt(0)
	v_add_f32_e32 v132, v132, v133
	v_mov_b32_e32 v133, v132
	s_nop 1
	v_permlane32_swap_b32_e32 v132, v133
	s_and_saveexec_b64 s[0:1], s[6:7]
	s_cbranch_execz .LBB0_1457
	s_lshl_b32 s8, s33, 11
	s_add_i32 s8, s17, s8
	v_mul_f32_e32 v134, 0x3c800000, v131
	s_waitcnt lgkmcnt(0)
	v_add_f32_e32 v135, v132, v133
	v_lshl_add_u32 v131, v170, 5, s8
	ds_write_b64 v131, v[134:135] offset:1024
.LBB0_1457:
	s_or_b64 exec, exec, s[0:1]
	s_waitcnt lgkmcnt(0)
	v_add_f32_e32 v132, v79, v78
	v_add_f32_e32 v133, v80, v81
	v_add_f32_e32 v134, v75, v74
	v_add_f32_e32 v135, v76, v77
	v_add_f32_e32 v131, v132, v133
	v_add_f32_e32 v135, v134, v135
	v_add_f32_e32 v134, v134, v134
	v_add_f32_e32 v133, 0, v131
	v_add_f32_e32 v137, v70, v71
	v_add_f32_e32 v139, v72, v73
	v_mov_b32_e32 v138, v67
	v_mov_b32_e32 v134, v68
	v_add_f32_e32 v136, v66, v67
	v_add_f32_e32 v137, v137, v139
	v_add_f32_e32 v132, v68, v69
	v_add_f32_e32 v133, v135, v133
	v_add_f32_e32 v132, v136, v132
	v_add_f32_e32 v133, v137, v133
	v_add_f32_e32 v131, v132, v133
	v_mov_b32_e32 v132, v131
	s_nop 1
	v_permlane16_swap_b32_e32 v131, v132
	s_waitcnt lgkmcnt(0)
	v_add_f32_e32 v131, v131, v132
	v_mov_b32_e32 v132, v131
	s_nop 1
	v_permlane32_swap_b32_e32 v131, v132
	s_waitcnt lgkmcnt(0)
	v_add_f32_e32 v131, v131, v132
	v_fmamk_f32 v133, v131, 0xbc800000, v81
	v_fmamk_f32 v135, v131, 0xbc800000, v79
	v_fmamk_f32 v132, v131, 0xbc800000, v80
	v_fmamk_f32 v134, v131, 0xbc800000, v78
	v_mul_f32_e32 v135, v135, v135
	v_mul_f32_e32 v133, v133, v133
	v_fmac_f32_e32 v135, v134, v134
	v_fmac_f32_e32 v133, v132, v132
	v_add_f32_e32 v132, v135, v133
	v_fmamk_f32 v134, v131, 0xbc800000, v77
	v_fmamk_f32 v136, v131, 0xbc800000, v75
	v_fmamk_f32 v133, v131, 0xbc800000, v76
	v_fmamk_f32 v135, v131, 0xbc800000, v74
	v_mul_f32_e32 v136, v136, v136
	v_mul_f32_e32 v134, v134, v134
	v_fmac_f32_e32 v136, v135, v135
	v_fmac_f32_e32 v134, v133, v133
	v_add_f32_e32 v133, v136, v134
	v_fmamk_f32 v134, v131, 0xbc800000, v73
	v_fmamk_f32 v136, v131, 0xbc800000, v71
	v_add_f32_e32 v132, v132, v133
	v_fmamk_f32 v133, v131, 0xbc800000, v72
	v_fmamk_f32 v135, v131, 0xbc800000, v70
	v_mul_f32_e32 v136, v136, v136
	v_mul_f32_e32 v134, v134, v134
	v_fmac_f32_e32 v136, v135, v135
	v_fmac_f32_e32 v134, v133, v133
	v_add_f32_e32 v133, v136, v134
	v_fmamk_f32 v134, v131, 0xbc800000, v69
	v_fmamk_f32 v136, v131, 0xbc800000, v67
	v_add_f32_e32 v132, v133, v132
	v_fmamk_f32 v133, v131, 0xbc800000, v68
	v_fmamk_f32 v135, v131, 0xbc800000, v66
	v_mul_f32_e32 v136, v136, v136
	v_mul_f32_e32 v134, v134, v134
	v_fmac_f32_e32 v136, v135, v135
	v_fmac_f32_e32 v134, v133, v133
	v_add_f32_e32 v133, v136, v134
	v_add_f32_e32 v132, v133, v132
	v_mov_b32_e32 v133, v132
	s_nop 1
	v_permlane16_swap_b32_e32 v132, v133
	s_waitcnt lgkmcnt(0)
	v_add_f32_e32 v132, v132, v133
	v_mov_b32_e32 v133, v132
	s_nop 1
	v_permlane32_swap_b32_e32 v132, v133
	s_and_saveexec_b64 s[0:1], s[6:7]
	s_cbranch_execz .LBB0_1459
	s_lshl_b32 s8, s33, 11
	s_add_i32 s8, s17, s8
	v_mul_f32_e32 v134, 0x3c800000, v131
	s_waitcnt lgkmcnt(0)
	v_add_f32_e32 v135, v132, v133
	v_lshl_add_u32 v131, v170, 5, s8
	ds_write_b64 v131, v[134:135] offset:1536
.LBB0_1459:
	s_or_b64 exec, exec, s[0:1]
	s_waitcnt lgkmcnt(0)
	v_add_f32_e32 v132, v63, v62
	v_add_f32_e32 v133, v64, v65
	v_add_f32_e32 v134, v59, v58
	v_add_f32_e32 v135, v60, v61
	v_add_f32_e32 v131, v132, v133
	v_add_f32_e32 v135, v134, v135
	v_add_f32_e32 v134, v134, v134
	v_add_f32_e32 v133, 0, v131
	v_add_f32_e32 v137, v54, v55
	v_add_f32_e32 v139, v56, v57
	v_mov_b32_e32 v138, v51
	v_mov_b32_e32 v134, v52
	v_add_f32_e32 v136, v50, v51
	v_add_f32_e32 v137, v137, v139
	v_add_f32_e32 v132, v52, v53
	v_add_f32_e32 v133, v135, v133
	v_add_f32_e32 v132, v136, v132
	v_add_f32_e32 v133, v137, v133
	v_add_f32_e32 v131, v132, v133
	v_mov_b32_e32 v132, v131
	s_nop 1
	v_permlane16_swap_b32_e32 v131, v132
	s_waitcnt lgkmcnt(0)
	v_add_f32_e32 v131, v131, v132
	v_mov_b32_e32 v132, v131
	s_nop 1
	v_permlane32_swap_b32_e32 v131, v132
	s_waitcnt lgkmcnt(0)
	v_add_f32_e32 v131, v131, v132
	v_fmamk_f32 v133, v131, 0xbc800000, v65
	v_fmamk_f32 v135, v131, 0xbc800000, v63
	v_fmamk_f32 v132, v131, 0xbc800000, v64
	v_fmamk_f32 v134, v131, 0xbc800000, v62
	v_mul_f32_e32 v135, v135, v135
	v_mul_f32_e32 v133, v133, v133
	v_fmac_f32_e32 v135, v134, v134
	v_fmac_f32_e32 v133, v132, v132
	v_add_f32_e32 v132, v135, v133
	v_fmamk_f32 v134, v131, 0xbc800000, v61
	v_fmamk_f32 v136, v131, 0xbc800000, v59
	v_fmamk_f32 v133, v131, 0xbc800000, v60
	v_fmamk_f32 v135, v131, 0xbc800000, v58
	v_mul_f32_e32 v136, v136, v136
	v_mul_f32_e32 v134, v134, v134
	v_fmac_f32_e32 v136, v135, v135
	v_fmac_f32_e32 v134, v133, v133
	v_add_f32_e32 v133, v136, v134
	v_fmamk_f32 v134, v131, 0xbc800000, v57
	v_fmamk_f32 v136, v131, 0xbc800000, v55
	v_add_f32_e32 v132, v132, v133
	v_fmamk_f32 v133, v131, 0xbc800000, v56
	v_fmamk_f32 v135, v131, 0xbc800000, v54
	v_mul_f32_e32 v136, v136, v136
	v_mul_f32_e32 v134, v134, v134
	v_fmac_f32_e32 v136, v135, v135
	v_fmac_f32_e32 v134, v133, v133
	v_add_f32_e32 v133, v136, v134
	v_fmamk_f32 v134, v131, 0xbc800000, v53
	v_fmamk_f32 v136, v131, 0xbc800000, v51
	v_add_f32_e32 v132, v133, v132
	v_fmamk_f32 v133, v131, 0xbc800000, v52
	v_fmamk_f32 v135, v131, 0xbc800000, v50
	v_mul_f32_e32 v136, v136, v136
	v_mul_f32_e32 v134, v134, v134
	v_fmac_f32_e32 v136, v135, v135
	v_fmac_f32_e32 v134, v133, v133
	v_add_f32_e32 v133, v136, v134
	v_add_f32_e32 v132, v133, v132
	v_mov_b32_e32 v133, v132
	s_nop 1
	v_permlane16_swap_b32_e32 v132, v133
	s_waitcnt lgkmcnt(0)
	v_add_f32_e32 v132, v132, v133
	v_mov_b32_e32 v133, v132
	s_nop 1
	v_permlane32_swap_b32_e32 v132, v133
	s_and_saveexec_b64 s[0:1], s[6:7]
	s_cbranch_execz .LBB0_1461
	s_lshl_b32 s8, s33, 11
	s_add_i32 s8, s17, s8
	v_mul_f32_e32 v134, 0x3c800000, v131
	s_waitcnt lgkmcnt(0)
	v_add_f32_e32 v135, v132, v133
	v_lshl_add_u32 v131, v170, 5, s8
	ds_write_b64 v131, v[134:135] offset:4096
.LBB0_1461:
	s_or_b64 exec, exec, s[0:1]
	s_waitcnt lgkmcnt(0)
	v_add_f32_e32 v132, v47, v46
	v_add_f32_e32 v133, v48, v49
	v_add_f32_e32 v134, v43, v42
	v_add_f32_e32 v135, v44, v45
	v_add_f32_e32 v131, v132, v133
	v_add_f32_e32 v135, v134, v135
	v_add_f32_e32 v134, v134, v134
	v_add_f32_e32 v133, 0, v131
	v_add_f32_e32 v137, v38, v39
	v_add_f32_e32 v139, v40, v41
	v_mov_b32_e32 v138, v35
	v_mov_b32_e32 v134, v36
	v_add_f32_e32 v136, v34, v35
	v_add_f32_e32 v137, v137, v139
	v_add_f32_e32 v132, v36, v37
	v_add_f32_e32 v133, v135, v133
	v_add_f32_e32 v132, v136, v132
	v_add_f32_e32 v133, v137, v133
	v_add_f32_e32 v131, v132, v133
	v_mov_b32_e32 v132, v131
	s_nop 1
	v_permlane16_swap_b32_e32 v131, v132
	s_waitcnt lgkmcnt(0)
	v_add_f32_e32 v131, v131, v132
	v_mov_b32_e32 v132, v131
	s_nop 1
	v_permlane32_swap_b32_e32 v131, v132
	s_waitcnt lgkmcnt(0)
	v_add_f32_e32 v131, v131, v132
	v_fmamk_f32 v133, v131, 0xbc800000, v49
	v_fmamk_f32 v135, v131, 0xbc800000, v47
	v_fmamk_f32 v132, v131, 0xbc800000, v48
	v_fmamk_f32 v134, v131, 0xbc800000, v46
	v_mul_f32_e32 v135, v135, v135
	v_mul_f32_e32 v133, v133, v133
	v_fmac_f32_e32 v135, v134, v134
	v_fmac_f32_e32 v133, v132, v132
	v_add_f32_e32 v132, v135, v133
	v_fmamk_f32 v134, v131, 0xbc800000, v45
	v_fmamk_f32 v136, v131, 0xbc800000, v43
	v_fmamk_f32 v133, v131, 0xbc800000, v44
	v_fmamk_f32 v135, v131, 0xbc800000, v42
	v_mul_f32_e32 v136, v136, v136
	v_mul_f32_e32 v134, v134, v134
	v_fmac_f32_e32 v136, v135, v135
	v_fmac_f32_e32 v134, v133, v133
	v_add_f32_e32 v133, v136, v134
	v_fmamk_f32 v134, v131, 0xbc800000, v41
	v_fmamk_f32 v136, v131, 0xbc800000, v39
	v_add_f32_e32 v132, v132, v133
	v_fmamk_f32 v133, v131, 0xbc800000, v40
	v_fmamk_f32 v135, v131, 0xbc800000, v38
	v_mul_f32_e32 v136, v136, v136
	v_mul_f32_e32 v134, v134, v134
	v_fmac_f32_e32 v136, v135, v135
	v_fmac_f32_e32 v134, v133, v133
	v_add_f32_e32 v133, v136, v134
	v_fmamk_f32 v134, v131, 0xbc800000, v37
	v_fmamk_f32 v136, v131, 0xbc800000, v35
	v_add_f32_e32 v132, v133, v132
	v_fmamk_f32 v133, v131, 0xbc800000, v36
	v_fmamk_f32 v135, v131, 0xbc800000, v34
	v_mul_f32_e32 v136, v136, v136
	v_mul_f32_e32 v134, v134, v134
	v_fmac_f32_e32 v136, v135, v135
	v_fmac_f32_e32 v134, v133, v133
	v_add_f32_e32 v133, v136, v134
	v_add_f32_e32 v132, v133, v132
	v_mov_b32_e32 v133, v132
	s_nop 1
	v_permlane16_swap_b32_e32 v132, v133
	s_waitcnt lgkmcnt(0)
	v_add_f32_e32 v132, v132, v133
	v_mov_b32_e32 v133, v132
	s_nop 1
	v_permlane32_swap_b32_e32 v132, v133
	s_and_saveexec_b64 s[0:1], s[6:7]
	s_cbranch_execz .LBB0_1463
	s_lshl_b32 s8, s33, 11
	s_add_i32 s8, s17, s8
	v_mul_f32_e32 v134, 0x3c800000, v131
	s_waitcnt lgkmcnt(0)
	v_add_f32_e32 v135, v132, v133
	v_lshl_add_u32 v131, v170, 5, s8
	ds_write_b64 v131, v[134:135] offset:4608
.LBB0_1463:
	s_or_b64 exec, exec, s[0:1]
	s_waitcnt lgkmcnt(0)
	v_add_f32_e32 v132, v31, v30
	v_add_f32_e32 v133, v32, v33
	v_add_f32_e32 v134, v27, v26
	v_add_f32_e32 v135, v28, v29
	v_add_f32_e32 v131, v132, v133
	v_add_f32_e32 v135, v134, v135
	v_add_f32_e32 v134, v134, v134
	v_add_f32_e32 v133, 0, v131
	v_add_f32_e32 v137, v22, v23
	v_add_f32_e32 v139, v24, v25
	v_mov_b32_e32 v138, v19
	v_mov_b32_e32 v134, v20
	v_add_f32_e32 v136, v18, v19
	v_add_f32_e32 v137, v137, v139
	v_add_f32_e32 v132, v20, v21
	v_add_f32_e32 v133, v135, v133
	v_add_f32_e32 v132, v136, v132
	v_add_f32_e32 v133, v137, v133
	v_add_f32_e32 v131, v132, v133
	v_mov_b32_e32 v132, v131
	s_nop 1
	v_permlane16_swap_b32_e32 v131, v132
	s_waitcnt lgkmcnt(0)
	v_add_f32_e32 v131, v131, v132
	v_mov_b32_e32 v132, v131
	s_nop 1
	v_permlane32_swap_b32_e32 v131, v132
	s_waitcnt lgkmcnt(0)
	v_add_f32_e32 v131, v131, v132
	v_fmamk_f32 v133, v131, 0xbc800000, v33
	v_fmamk_f32 v135, v131, 0xbc800000, v31
	v_fmamk_f32 v132, v131, 0xbc800000, v32
	v_fmamk_f32 v134, v131, 0xbc800000, v30
	v_mul_f32_e32 v135, v135, v135
	v_mul_f32_e32 v133, v133, v133
	v_fmac_f32_e32 v135, v134, v134
	v_fmac_f32_e32 v133, v132, v132
	v_add_f32_e32 v132, v135, v133
	v_fmamk_f32 v134, v131, 0xbc800000, v29
	v_fmamk_f32 v136, v131, 0xbc800000, v27
	v_fmamk_f32 v133, v131, 0xbc800000, v28
	v_fmamk_f32 v135, v131, 0xbc800000, v26
	v_mul_f32_e32 v136, v136, v136
	v_mul_f32_e32 v134, v134, v134
	v_fmac_f32_e32 v136, v135, v135
	v_fmac_f32_e32 v134, v133, v133
	v_add_f32_e32 v133, v136, v134
	v_fmamk_f32 v134, v131, 0xbc800000, v25
	v_fmamk_f32 v136, v131, 0xbc800000, v23
	v_add_f32_e32 v132, v132, v133
	v_fmamk_f32 v133, v131, 0xbc800000, v24
	v_fmamk_f32 v135, v131, 0xbc800000, v22
	v_mul_f32_e32 v136, v136, v136
	v_mul_f32_e32 v134, v134, v134
	v_fmac_f32_e32 v136, v135, v135
	v_fmac_f32_e32 v134, v133, v133
	v_add_f32_e32 v133, v136, v134
	v_fmamk_f32 v134, v131, 0xbc800000, v21
	v_fmamk_f32 v136, v131, 0xbc800000, v19
	v_add_f32_e32 v132, v133, v132
	v_fmamk_f32 v133, v131, 0xbc800000, v20
	v_fmamk_f32 v135, v131, 0xbc800000, v18
	v_mul_f32_e32 v136, v136, v136
	v_mul_f32_e32 v134, v134, v134
	v_fmac_f32_e32 v136, v135, v135
	v_fmac_f32_e32 v134, v133, v133
	v_add_f32_e32 v133, v136, v134
	v_add_f32_e32 v132, v133, v132
	v_mov_b32_e32 v133, v132
	s_nop 1
	v_permlane16_swap_b32_e32 v132, v133
	s_waitcnt lgkmcnt(0)
	v_add_f32_e32 v132, v132, v133
	v_mov_b32_e32 v133, v132
	s_nop 1
	v_permlane32_swap_b32_e32 v132, v133
	s_and_saveexec_b64 s[0:1], s[6:7]
	s_cbranch_execz .LBB0_1465
	s_lshl_b32 s8, s33, 11
	s_add_i32 s8, s17, s8
	v_mul_f32_e32 v134, 0x3c800000, v131
	s_waitcnt lgkmcnt(0)
	v_add_f32_e32 v135, v132, v133
	v_lshl_add_u32 v131, v170, 5, s8
	ds_write_b64 v131, v[134:135] offset:5120
.LBB0_1465:
	s_or_b64 exec, exec, s[0:1]
	s_waitcnt lgkmcnt(0)
	v_add_f32_e32 v132, v15, v14
	v_add_f32_e32 v133, v16, v17
	v_add_f32_e32 v134, v11, v10
	v_add_f32_e32 v135, v12, v13
	v_add_f32_e32 v131, v132, v133
	v_add_f32_e32 v135, v134, v135
	v_add_f32_e32 v134, v134, v134
	v_add_f32_e32 v133, 0, v131
	v_add_f32_e32 v137, v6, v7
	v_add_f32_e32 v139, v8, v9
	v_mov_b32_e32 v138, v3
	v_mov_b32_e32 v134, v4
	v_add_f32_e32 v136, v2, v3
	v_add_f32_e32 v137, v137, v139
	v_add_f32_e32 v132, v4, v5
	v_add_f32_e32 v133, v135, v133
	v_add_f32_e32 v132, v136, v132
	v_add_f32_e32 v133, v137, v133
	v_add_f32_e32 v131, v132, v133
	v_mov_b32_e32 v132, v131
	s_nop 1
	v_permlane16_swap_b32_e32 v131, v132
	s_waitcnt lgkmcnt(0)
	v_add_f32_e32 v131, v131, v132
	v_mov_b32_e32 v132, v131
	s_nop 1
	v_permlane32_swap_b32_e32 v131, v132
	s_waitcnt lgkmcnt(0)
	v_add_f32_e32 v131, v131, v132
	v_fmamk_f32 v133, v131, 0xbc800000, v17
	v_fmamk_f32 v135, v131, 0xbc800000, v15
	v_fmamk_f32 v132, v131, 0xbc800000, v16
	v_fmamk_f32 v134, v131, 0xbc800000, v14
	v_mul_f32_e32 v135, v135, v135
	v_mul_f32_e32 v133, v133, v133
	v_fmac_f32_e32 v135, v134, v134
	v_fmac_f32_e32 v133, v132, v132
	v_add_f32_e32 v132, v135, v133
	v_fmamk_f32 v134, v131, 0xbc800000, v13
	v_fmamk_f32 v136, v131, 0xbc800000, v11
	v_fmamk_f32 v133, v131, 0xbc800000, v12
	v_fmamk_f32 v135, v131, 0xbc800000, v10
	v_mul_f32_e32 v136, v136, v136
	v_mul_f32_e32 v134, v134, v134
	v_fmac_f32_e32 v136, v135, v135
	v_fmac_f32_e32 v134, v133, v133
	v_add_f32_e32 v133, v136, v134
	v_fmamk_f32 v134, v131, 0xbc800000, v9
	v_fmamk_f32 v136, v131, 0xbc800000, v7
	v_add_f32_e32 v132, v132, v133
	v_fmamk_f32 v133, v131, 0xbc800000, v8
	v_fmamk_f32 v135, v131, 0xbc800000, v6
	v_mul_f32_e32 v136, v136, v136
	v_mul_f32_e32 v134, v134, v134
	v_fmac_f32_e32 v136, v135, v135
	v_fmac_f32_e32 v134, v133, v133
	v_add_f32_e32 v133, v136, v134
	v_fmamk_f32 v134, v131, 0xbc800000, v5
	v_fmamk_f32 v136, v131, 0xbc800000, v3
	v_add_f32_e32 v132, v133, v132
	v_fmamk_f32 v133, v131, 0xbc800000, v4
	v_fmamk_f32 v135, v131, 0xbc800000, v2
	v_mul_f32_e32 v136, v136, v136
	v_mul_f32_e32 v134, v134, v134
	v_fmac_f32_e32 v136, v135, v135
	v_fmac_f32_e32 v134, v133, v133
	v_add_f32_e32 v133, v136, v134
	v_add_f32_e32 v132, v133, v132
	v_mov_b32_e32 v133, v132
	s_nop 1
	v_permlane16_swap_b32_e32 v132, v133
	s_waitcnt lgkmcnt(0)
	v_add_f32_e32 v132, v132, v133
	v_mov_b32_e32 v133, v132
	s_nop 1
	v_permlane32_swap_b32_e32 v132, v133
	s_and_saveexec_b64 s[0:1], s[6:7]
	s_cbranch_execz .LBB0_1467
	s_lshl_b32 s8, s33, 11
	s_add_i32 s8, s17, s8
	v_mul_f32_e32 v134, 0x3c800000, v131
	s_waitcnt lgkmcnt(0)
	v_add_f32_e32 v135, v132, v133
	v_lshl_add_u32 v131, v170, 5, s8
	ds_write_b64 v131, v[134:135] offset:5632

.LBB0_1491:
	s_or_b64 exec, exec, s[22:23]
	s_lshl_b32 s0, s40, 5
	s_lshl_b32 s1, s18, 8
	s_or_b32 s0, s1, s0
	v_lshrrev_b32_e32 v130, 2, v148
	v_and_or_b32 v162, v130, 12, s0
	v_add_u32_e32 v150, s19, v152
	s_lshl_b32 s0, s16, 5
	v_ashrrev_i32_e32 v151, 31, v150
	s_and_b32 s0, s0, 0xfffffc00
	v_ashrrev_i32_e32 v163, 31, v162
	v_lshlrev_b64 v[130:131], 11, v[150:151]
	v_add_u32_e32 v132, s0, v162
	v_lshl_add_u64 v[130:131], s[94:95], 0, v[130:131]
	v_lshlrev_b64 v[168:169], 1, v[162:163]
	s_waitcnt lgkmcnt(0)
	v_ashrrev_i32_e32 v133, 31, v132
	s_waitcnt lgkmcnt(0)
	s_barrier
	v_lshl_add_u64 v[130:131], v[130:131], 0, v[168:169]
	v_lshl_add_u64 v[148:149], v[132:133], 2, s[34:35]
	s_mov_b32 s19, 0x10c000
	v_add_co_u32_e32 v130, vcc, s19, v148
	s_mov_b64 s[0:1], 0x10c000
	s_nop 0
	v_addc_co_u32_e32 v131, vcc, 0, v149, vcc
	global_load_dwordx4 v[138:141], v[130:131], off
	v_lshl_add_u64 v[130:131], v[148:149], 0, s[0:1]
	global_load_dwordx4 v[142:145], v[130:131], off offset:64
	global_load_dwordx4 v[134:137], v[130:131], off offset:512
	s_nop 0
	global_load_dwordx4 v[130:133], v[130:131], off offset:576
	v_lshl_add_u32 v246, v150, 11, v168
	global_load_dwordx2 v[216:217], v246, s[94:95]
	global_load_dwordx2 v[218:219], v246, s[94:95] offset:32
	global_load_dwordx2 v[220:221], v246, s[94:95] offset:256
	global_load_dwordx2 v[222:223], v246, s[94:95] offset:288
	v_add_u32_e32 v247, 0x8000, v246
	global_load_dwordx2 v[224:225], v247, s[94:95]
	global_load_dwordx2 v[232:233], v247, s[94:95] offset:32
	global_load_dwordx2 v[234:235], v247, s[94:95] offset:256
	global_load_dwordx2 v[236:237], v247, s[94:95] offset:288
	v_add_u32_e32 v247, 0x10000, v246
	global_load_dwordx2 v[238:239], v247, s[94:95]
	global_load_dwordx2 v[240:241], v247, s[94:95] offset:32
	global_load_dwordx2 v[242:243], v247, s[94:95] offset:256
	global_load_dwordx2 v[244:245], v247, s[94:95] offset:288
	v_lshl_add_u32 v183, v152, 3, 0
	ds_read_b64 v[164:165], v183 offset:8192
	v_add_u32_e32 v152, 16, v150
	v_ashrrev_i32_e32 v153, 31, v152
	v_lshlrev_b64 v[166:167], 11, v[152:153]
	v_lshl_add_u64 v[166:167], s[94:95], 0, v[166:167]
	s_waitcnt lgkmcnt(0)
	v_pk_mul_f32 v[128:129], v[128:129], v[164:165] op_sel:[0,1]
	v_pk_mul_f32 v[126:127], v[126:127], v[164:165] op_sel:[0,1]
	v_pk_mul_f32 v[122:123], v[122:123], v[164:165] op_sel:[0,1]
	v_pk_mul_f32 v[124:125], v[124:125], v[164:165] op_sel:[0,1]
	v_pk_mul_f32 v[172:173], v[118:119], v[164:165] op_sel:[0,1]
	v_pk_mul_f32 v[174:175], v[120:121], v[164:165] op_sel:[0,1]
	v_pk_mul_f32 v[114:115], v[114:115], v[164:165] op_sel:[0,1]
	v_pk_mul_f32 v[116:117], v[116:117], v[164:165] op_sel:[0,1]
	v_lshl_add_u64 v[166:167], v[166:167], 0, v[168:169]
	s_waitcnt vmcnt(11)
	v_lshlrev_b32_e32 v118, 16, v216
	v_and_b32_e32 v119, 0xffff0000, v216
	v_lshlrev_b32_e32 v120, 16, v217
	v_and_b32_e32 v121, 0xffff0000, v217
	s_waitcnt vmcnt(10)
	v_lshlrev_b32_e32 v154, 16, v218
	v_and_b32_e32 v155, 0xffff0000, v218
	v_lshlrev_b32_e32 v156, 16, v219
	v_and_b32_e32 v157, 0xffff0000, v219
	s_waitcnt vmcnt(9)
	v_lshlrev_b32_e32 v164, 16, v220
	v_and_b32_e32 v165, 0xffff0000, v220
	v_lshlrev_b32_e32 v158, 16, v221
	v_and_b32_e32 v159, 0xffff0000, v221
	s_waitcnt vmcnt(8)
	v_lshlrev_b32_e32 v176, 16, v222
	v_and_b32_e32 v177, 0xffff0000, v222
	v_lshlrev_b32_e32 v160, 16, v223
	v_and_b32_e32 v161, 0xffff0000, v223
	v_pk_fma_f32 v[118:119], v[138:139], v[126:127], v[118:119]
	v_pk_fma_f32 v[120:121], v[140:141], v[128:129], v[120:121]
	v_pk_fma_f32 v[124:125], v[144:145], v[124:125], v[156:157]
	v_pk_fma_f32 v[122:123], v[142:143], v[122:123], v[154:155]
	v_pk_fma_f32 v[128:129], v[136:137], v[174:175], v[158:159]
	v_pk_fma_f32 v[126:127], v[134:135], v[172:173], v[164:165]
	v_pk_fma_f32 v[116:117], v[132:133], v[116:117], v[160:161]
	v_pk_fma_f32 v[114:115], v[130:131], v[114:115], v[176:177]
	v_add_u32_e32 v154, 32, v150
	v_add_u32_e32 v247, 0x18000, v246
	global_load_dwordx2 v[216:217], v247, s[94:95]
	global_load_dwordx2 v[218:219], v247, s[94:95] offset:32
	global_load_dwordx2 v[220:221], v247, s[94:95] offset:256
	global_load_dwordx2 v[222:223], v247, s[94:95] offset:288
	ds_read_b64 v[166:167], v183 offset:8320
	v_ashrrev_i32_e32 v155, 31, v154
	v_lshlrev_b64 v[172:173], 11, v[154:155]
	v_lshl_add_u64 v[172:173], s[94:95], 0, v[172:173]
	v_lshl_add_u64 v[172:173], v[172:173], 0, v[168:169]
	s_waitcnt lgkmcnt(0)
	v_pk_mul_f32 v[110:111], v[110:111], v[166:167] op_sel:[0,1]
	v_pk_mul_f32 v[112:113], v[112:113], v[166:167] op_sel:[0,1]
	v_pk_mul_f32 v[106:107], v[106:107], v[166:167] op_sel:[0,1]
	v_pk_mul_f32 v[108:109], v[108:109], v[166:167] op_sel:[0,1]
	v_pk_mul_f32 v[102:103], v[102:103], v[166:167] op_sel:[0,1]
	v_pk_mul_f32 v[104:105], v[104:105], v[166:167] op_sel:[0,1]
	v_pk_mul_f32 v[98:99], v[98:99], v[166:167] op_sel:[0,1]
	v_pk_mul_f32 v[100:101], v[100:101], v[166:167] op_sel:[0,1]
	v_add_f32_e32 v193, v126, v127
	v_add_f32_e32 v197, v128, v129
	v_mov_b32_e32 v192, v114
	v_mov_b32_e32 v196, v115
	v_mov_b32_e32 v198, v117
	s_waitcnt vmcnt(11)
	v_lshlrev_b32_e32 v166, 16, v224
	v_and_b32_e32 v167, 0xffff0000, v224
	v_lshlrev_b32_e32 v156, 16, v225
	v_and_b32_e32 v157, 0xffff0000, v225
	s_waitcnt vmcnt(10)
	v_lshlrev_b32_e32 v174, 16, v232
	v_and_b32_e32 v175, 0xffff0000, v232
	v_lshlrev_b32_e32 v158, 16, v233
	v_and_b32_e32 v159, 0xffff0000, v233
	s_waitcnt vmcnt(9)
	v_lshlrev_b32_e32 v176, 16, v234
	v_and_b32_e32 v177, 0xffff0000, v234
	v_lshlrev_b32_e32 v160, 16, v235
	v_and_b32_e32 v161, 0xffff0000, v235
	s_waitcnt vmcnt(8)
	v_lshlrev_b32_e32 v178, 16, v236
	v_and_b32_e32 v179, 0xffff0000, v236
	v_lshlrev_b32_e32 v164, 16, v237
	v_and_b32_e32 v165, 0xffff0000, v237
	v_pk_fma_f32 v[112:113], v[140:141], v[112:113], v[156:157]
	v_pk_fma_f32 v[110:111], v[138:139], v[110:111], v[166:167]
	v_pk_fma_f32 v[108:109], v[144:145], v[108:109], v[158:159]
	v_pk_fma_f32 v[106:107], v[142:143], v[106:107], v[174:175]
	v_pk_fma_f32 v[104:105], v[136:137], v[104:105], v[160:161]
	v_pk_fma_f32 v[102:103], v[134:135], v[102:103], v[176:177]
	v_pk_fma_f32 v[100:101], v[132:133], v[100:101], v[164:165]
	v_pk_fma_f32 v[98:99], v[130:131], v[98:99], v[178:179]
	v_add_u32_e32 v156, 48, v150
	v_add_u32_e32 v247, 0x40000, v246
	global_load_dwordx2 v[224:225], v247, s[94:95]
	global_load_dwordx2 v[232:233], v247, s[94:95] offset:32
	global_load_dwordx2 v[234:235], v247, s[94:95] offset:256
	global_load_dwordx2 v[236:237], v247, s[94:95] offset:288
	ds_read_b64 v[172:173], v183 offset:8448
	v_ashrrev_i32_e32 v157, 31, v156
	v_lshlrev_b64 v[174:175], 11, v[156:157]
	v_lshl_add_u64 v[174:175], s[94:95], 0, v[174:175]
	v_lshl_add_u64 v[174:175], v[174:175], 0, v[168:169]
	s_waitcnt lgkmcnt(0)
	v_pk_mul_f32 v[94:95], v[94:95], v[172:173] op_sel:[0,1]
	v_pk_mul_f32 v[96:97], v[96:97], v[172:173] op_sel:[0,1]
	v_pk_mul_f32 v[90:91], v[90:91], v[172:173] op_sel:[0,1]
	v_pk_mul_f32 v[92:93], v[92:93], v[172:173] op_sel:[0,1]
	v_pk_mul_f32 v[86:87], v[86:87], v[172:173] op_sel:[0,1]
	v_pk_mul_f32 v[88:89], v[88:89], v[172:173] op_sel:[0,1]
	v_pk_mul_f32 v[82:83], v[82:83], v[172:173] op_sel:[0,1]
	v_pk_mul_f32 v[84:85], v[84:85], v[172:173] op_sel:[0,1]
	s_waitcnt vmcnt(11)
	v_lshlrev_b32_e32 v172, 16, v238
	v_and_b32_e32 v173, 0xffff0000, v238
	v_lshlrev_b32_e32 v158, 16, v239
	v_and_b32_e32 v159, 0xffff0000, v239
	s_waitcnt vmcnt(10)
	v_lshlrev_b32_e32 v176, 16, v240
	v_and_b32_e32 v177, 0xffff0000, v240
	v_lshlrev_b32_e32 v160, 16, v241
	v_and_b32_e32 v161, 0xffff0000, v241
	s_waitcnt vmcnt(9)
	v_lshlrev_b32_e32 v178, 16, v242
	v_and_b32_e32 v179, 0xffff0000, v242
	v_lshlrev_b32_e32 v164, 16, v243
	v_and_b32_e32 v165, 0xffff0000, v243
	s_waitcnt vmcnt(8)
	v_lshlrev_b32_e32 v180, 16, v244
	v_and_b32_e32 v181, 0xffff0000, v244
	v_lshlrev_b32_e32 v166, 16, v245
	v_and_b32_e32 v167, 0xffff0000, v245
	v_pk_fma_f32 v[96:97], v[140:141], v[96:97], v[158:159]
	v_pk_fma_f32 v[94:95], v[138:139], v[94:95], v[172:173]
	v_pk_fma_f32 v[92:93], v[144:145], v[92:93], v[160:161]
	v_pk_fma_f32 v[90:91], v[142:143], v[90:91], v[176:177]
	v_pk_fma_f32 v[88:89], v[136:137], v[88:89], v[164:165]
	v_pk_fma_f32 v[86:87], v[134:135], v[86:87], v[178:179]
	v_pk_fma_f32 v[84:85], v[132:133], v[84:85], v[166:167]
	v_pk_fma_f32 v[82:83], v[130:131], v[82:83], v[180:181]
	v_add_u32_e32 v158, 0x80, v150
	v_add_u32_e32 v247, 0x48000, v246
	global_load_dwordx2 v[238:239], v247, s[94:95]
	global_load_dwordx2 v[240:241], v247, s[94:95] offset:32
	global_load_dwordx2 v[242:243], v247, s[94:95] offset:256
	global_load_dwordx2 v[244:245], v247, s[94:95] offset:288
	ds_read_b64 v[174:175], v183 offset:8576
	v_ashrrev_i32_e32 v159, 31, v158
	v_lshlrev_b64 v[176:177], 11, v[158:159]
	v_lshl_add_u64 v[176:177], s[94:95], 0, v[176:177]
	v_lshl_add_u64 v[176:177], v[176:177], 0, v[168:169]
	s_waitcnt lgkmcnt(0)
	v_pk_mul_f32 v[78:79], v[78:79], v[174:175] op_sel:[0,1]
	v_pk_mul_f32 v[80:81], v[80:81], v[174:175] op_sel:[0,1]
	v_pk_mul_f32 v[74:75], v[74:75], v[174:175] op_sel:[0,1]
	v_pk_mul_f32 v[76:77], v[76:77], v[174:175] op_sel:[0,1]
	v_pk_mul_f32 v[70:71], v[70:71], v[174:175] op_sel:[0,1]
	v_pk_mul_f32 v[72:73], v[72:73], v[174:175] op_sel:[0,1]
	v_pk_mul_f32 v[66:67], v[66:67], v[174:175] op_sel:[0,1]
	v_pk_mul_f32 v[68:69], v[68:69], v[174:175] op_sel:[0,1]
	s_waitcnt vmcnt(11)
	v_lshlrev_b32_e32 v174, 16, v216
	v_and_b32_e32 v175, 0xffff0000, v216
	v_lshlrev_b32_e32 v160, 16, v217
	v_and_b32_e32 v161, 0xffff0000, v217
	s_waitcnt vmcnt(10)
	v_lshlrev_b32_e32 v178, 16, v218
	v_and_b32_e32 v179, 0xffff0000, v218
	v_lshlrev_b32_e32 v164, 16, v219
	v_and_b32_e32 v165, 0xffff0000, v219
	s_waitcnt vmcnt(9)
	v_lshlrev_b32_e32 v180, 16, v220
	v_and_b32_e32 v181, 0xffff0000, v220
	v_lshlrev_b32_e32 v166, 16, v221
	v_and_b32_e32 v167, 0xffff0000, v221
	s_waitcnt vmcnt(8)
	v_lshlrev_b32_e32 v186, 16, v222
	v_and_b32_e32 v187, 0xffff0000, v222
	v_lshlrev_b32_e32 v172, 16, v223
	v_and_b32_e32 v173, 0xffff0000, v223
	v_pk_fma_f32 v[80:81], v[140:141], v[80:81], v[160:161]
	v_pk_fma_f32 v[78:79], v[138:139], v[78:79], v[174:175]
	v_pk_fma_f32 v[76:77], v[144:145], v[76:77], v[164:165]
	v_pk_fma_f32 v[74:75], v[142:143], v[74:75], v[178:179]
	v_pk_fma_f32 v[72:73], v[136:137], v[72:73], v[166:167]
	v_pk_fma_f32 v[70:71], v[134:135], v[70:71], v[180:181]
	v_pk_fma_f32 v[68:69], v[132:133], v[68:69], v[172:173]
	v_pk_fma_f32 v[66:67], v[130:131], v[66:67], v[186:187]
	v_add_u32_e32 v160, 0x90, v150
	v_add_u32_e32 v247, 0x50000, v246
	global_load_dwordx2 v[216:217], v247, s[94:95]
	global_load_dwordx2 v[218:219], v247, s[94:95] offset:32
	global_load_dwordx2 v[220:221], v247, s[94:95] offset:256
	global_load_dwordx2 v[222:223], v247, s[94:95] offset:288
	ds_read_b64 v[176:177], v183 offset:9216
	v_ashrrev_i32_e32 v161, 31, v160
	v_lshlrev_b64 v[178:179], 11, v[160:161]
	v_lshl_add_u64 v[178:179], s[94:95], 0, v[178:179]
	v_lshl_add_u64 v[178:179], v[178:179], 0, v[168:169]
	s_waitcnt lgkmcnt(0)
	v_pk_mul_f32 v[62:63], v[62:63], v[176:177] op_sel:[0,1]
	v_pk_mul_f32 v[64:65], v[64:65], v[176:177] op_sel:[0,1]
	v_pk_mul_f32 v[58:59], v[58:59], v[176:177] op_sel:[0,1]
	v_pk_mul_f32 v[60:61], v[60:61], v[176:177] op_sel:[0,1]
	v_pk_mul_f32 v[54:55], v[54:55], v[176:177] op_sel:[0,1]
	v_pk_mul_f32 v[56:57], v[56:57], v[176:177] op_sel:[0,1]
	v_pk_mul_f32 v[50:51], v[50:51], v[176:177] op_sel:[0,1]
	v_pk_mul_f32 v[52:53], v[52:53], v[176:177] op_sel:[0,1]
	s_waitcnt vmcnt(11)
	v_lshlrev_b32_e32 v176, 16, v224
	v_and_b32_e32 v177, 0xffff0000, v224
	v_lshlrev_b32_e32 v164, 16, v225
	v_and_b32_e32 v165, 0xffff0000, v225
	s_waitcnt vmcnt(10)
	v_lshlrev_b32_e32 v180, 16, v232
	v_and_b32_e32 v181, 0xffff0000, v232
	v_lshlrev_b32_e32 v166, 16, v233
	v_and_b32_e32 v167, 0xffff0000, v233
	s_waitcnt vmcnt(9)
	v_lshlrev_b32_e32 v186, 16, v234
	v_and_b32_e32 v187, 0xffff0000, v234
	v_lshlrev_b32_e32 v172, 16, v235
	v_and_b32_e32 v173, 0xffff0000, v235
	s_waitcnt vmcnt(8)
	v_lshlrev_b32_e32 v188, 16, v236
	v_and_b32_e32 v189, 0xffff0000, v236
	v_lshlrev_b32_e32 v174, 16, v237
	v_and_b32_e32 v175, 0xffff0000, v237
	v_pk_fma_f32 v[64:65], v[140:141], v[64:65], v[164:165]
	v_pk_fma_f32 v[62:63], v[138:139], v[62:63], v[176:177]
	v_pk_fma_f32 v[60:61], v[144:145], v[60:61], v[166:167]
	v_pk_fma_f32 v[58:59], v[142:143], v[58:59], v[180:181]
	v_pk_fma_f32 v[56:57], v[136:137], v[56:57], v[172:173]
	v_pk_fma_f32 v[54:55], v[134:135], v[54:55], v[186:187]
	v_pk_fma_f32 v[52:53], v[132:133], v[52:53], v[174:175]
	v_pk_fma_f32 v[50:51], v[130:131], v[50:51], v[188:189]
	v_add_u32_e32 v164, 0xa0, v150
	v_add_u32_e32 v247, 0x58000, v246
	global_load_dwordx2 v[224:225], v247, s[94:95]
	global_load_dwordx2 v[232:233], v247, s[94:95] offset:32
	global_load_dwordx2 v[234:235], v247, s[94:95] offset:256
	global_load_dwordx2 v[236:237], v247, s[94:95] offset:288
	ds_read_b64 v[178:179], v183 offset:9344
	v_ashrrev_i32_e32 v165, 31, v164
	v_lshlrev_b64 v[180:181], 11, v[164:165]
	v_lshl_add_u64 v[180:181], s[94:95], 0, v[180:181]
	v_lshl_add_u64 v[180:181], v[180:181], 0, v[168:169]
	s_waitcnt lgkmcnt(0)
	v_pk_mul_f32 v[46:47], v[46:47], v[178:179] op_sel:[0,1]
	v_pk_mul_f32 v[48:49], v[48:49], v[178:179] op_sel:[0,1]
	v_pk_mul_f32 v[42:43], v[42:43], v[178:179] op_sel:[0,1]
	v_pk_mul_f32 v[44:45], v[44:45], v[178:179] op_sel:[0,1]
	v_pk_mul_f32 v[38:39], v[38:39], v[178:179] op_sel:[0,1]
	v_pk_mul_f32 v[40:41], v[40:41], v[178:179] op_sel:[0,1]
	v_pk_mul_f32 v[34:35], v[34:35], v[178:179] op_sel:[0,1]
	v_pk_mul_f32 v[36:37], v[36:37], v[178:179] op_sel:[0,1]
	s_waitcnt vmcnt(11)
	v_lshlrev_b32_e32 v178, 16, v238
	v_and_b32_e32 v179, 0xffff0000, v238
	v_lshlrev_b32_e32 v166, 16, v239
	v_and_b32_e32 v167, 0xffff0000, v239
	s_waitcnt vmcnt(10)
	v_lshlrev_b32_e32 v186, 16, v240
	v_and_b32_e32 v187, 0xffff0000, v240
	v_lshlrev_b32_e32 v172, 16, v241
	v_and_b32_e32 v173, 0xffff0000, v241
	s_waitcnt vmcnt(9)
	v_lshlrev_b32_e32 v188, 16, v242
	v_and_b32_e32 v189, 0xffff0000, v242
	v_lshlrev_b32_e32 v174, 16, v243
	v_and_b32_e32 v175, 0xffff0000, v243
	s_waitcnt vmcnt(8)
	v_lshlrev_b32_e32 v190, 16, v244
	v_and_b32_e32 v191, 0xffff0000, v244
	v_lshlrev_b32_e32 v176, 16, v245
	v_and_b32_e32 v177, 0xffff0000, v245
	v_pk_fma_f32 v[48:49], v[140:141], v[48:49], v[166:167]
	v_pk_fma_f32 v[46:47], v[138:139], v[46:47], v[178:179]
	v_pk_fma_f32 v[44:45], v[144:145], v[44:45], v[172:173]
	v_pk_fma_f32 v[42:43], v[142:143], v[42:43], v[186:187]
	v_pk_fma_f32 v[40:41], v[136:137], v[40:41], v[174:175]
	v_pk_fma_f32 v[38:39], v[134:135], v[38:39], v[188:189]
	v_pk_fma_f32 v[36:37], v[132:133], v[36:37], v[176:177]
	v_pk_fma_f32 v[34:35], v[130:131], v[34:35], v[190:191]
	v_add_u32_e32 v166, 0xb0, v150
	ds_read_b64 v[194:195], v183 offset:9472
	v_ashrrev_i32_e32 v167, 31, v166
	v_lshlrev_b64 v[180:181], 11, v[166:167]
	v_lshl_add_u64 v[180:181], s[94:95], 0, v[180:181]
	v_lshl_add_u64 v[168:169], v[180:181], 0, v[168:169]
	s_waitcnt lgkmcnt(0)
	v_mul_f32_e32 v30, v30, v195
	v_mul_f32_e32 v31, v31, v195
	v_mul_f32_e32 v32, v32, v195
	v_mul_f32_e32 v33, v33, v195
	v_mul_f32_e32 v26, v26, v195
	v_mul_f32_e32 v27, v27, v195
	v_mul_f32_e32 v28, v28, v195
	v_mul_f32_e32 v29, v29, v195
	v_mul_f32_e32 v22, v22, v195
	v_mul_f32_e32 v23, v23, v195
	v_mul_f32_e32 v24, v24, v195
	v_mul_f32_e32 v25, v25, v195
	v_mul_f32_e32 v18, v18, v195
	v_mul_f32_e32 v19, v19, v195
	v_mul_f32_e32 v20, v20, v195
	v_mul_f32_e32 v21, v21, v195
	s_waitcnt vmcnt(7)
	v_lshlrev_b32_e32 v194, 16, v216
	v_and_b32_e32 v195, 0xffff0000, v216
	v_lshlrev_b32_e32 v172, 16, v217
	v_and_b32_e32 v173, 0xffff0000, v217
	s_waitcnt vmcnt(5)
	v_lshlrev_b32_e32 v204, 16, v220
	v_and_b32_e32 v205, 0xffff0000, v220
	v_lshlrev_b32_e32 v176, 16, v221
	v_and_b32_e32 v177, 0xffff0000, v221
	v_pk_fma_f32 v[32:33], v[140:141], v[32:33], v[172:173]
	v_pk_fma_f32 v[24:25], v[136:137], v[24:25], v[176:177]
	v_add_f32_e32 v172, v119, v118
	v_add_f32_e32 v173, v120, v121
	v_add_f32_e32 v176, v123, v122
	v_add_f32_e32 v177, v124, v125
	v_add_f32_e32 v186, v172, v173
	v_add_f32_e32 v172, v176, v176
	v_add_f32_e32 v173, v176, v177
	s_waitcnt vmcnt(6)
	v_lshlrev_b32_e32 v200, 16, v218
	v_and_b32_e32 v201, 0xffff0000, v218
	v_lshlrev_b32_e32 v174, 16, v219
	v_and_b32_e32 v175, 0xffff0000, v219
	s_waitcnt vmcnt(4)
	v_lshlrev_b32_e32 v206, 16, v222
	v_and_b32_e32 v207, 0xffff0000, v222
	v_lshlrev_b32_e32 v178, 16, v223
	v_and_b32_e32 v179, 0xffff0000, v223
	v_add_f32_e32 v199, 0, v186
	v_pk_fma_f32 v[30:31], v[138:139], v[30:31], v[194:195]
	v_pk_fma_f32 v[28:29], v[144:145], v[28:29], v[174:175]
	v_pk_fma_f32 v[26:27], v[142:143], v[26:27], v[200:201]
	v_pk_fma_f32 v[22:23], v[134:135], v[22:23], v[204:205]
	v_pk_fma_f32 v[20:21], v[132:133], v[20:21], v[178:179]
	v_pk_fma_f32 v[18:19], v[130:131], v[18:19], v[206:207]
	v_add_f32_e32 v178, v192, v196
	v_add_f32_e32 v179, v193, v197
	v_add_f32_e32 v172, v116, v198
	v_add_f32_e32 v173, v173, v199
	v_add_f32_e32 v172, v178, v172
	v_add_f32_e32 v173, v179, v173
	v_add_f32_e32 v168, v172, v173
	v_mov_b32_e32 v169, v168
	s_nop 1
	v_permlane16_swap_b32_e32 v168, v169
	s_waitcnt lgkmcnt(0)
	v_add_f32_e32 v168, v168, v169
	v_mov_b32_e32 v169, v168
	s_nop 1
	v_permlane32_swap_b32_e32 v168, v169
	s_waitcnt lgkmcnt(0)
	v_add_f32_e32 v168, v168, v169
	v_fmamk_f32 v172, v168, 0xbc800000, v121
	v_fmamk_f32 v186, v168, 0xbc800000, v119
	v_fmamk_f32 v188, v168, 0xbc800000, v125
	v_fmamk_f32 v190, v168, 0xbc800000, v123
	v_fmamk_f32 v169, v168, 0xbc800000, v120
	v_fmamk_f32 v173, v168, 0xbc800000, v118
	v_fmamk_f32 v187, v168, 0xbc800000, v124
	v_fmamk_f32 v189, v168, 0xbc800000, v122
	v_fmamk_f32 v192, v168, 0xbc800000, v129
	v_fmamk_f32 v194, v168, 0xbc800000, v127
	v_mul_f32_e32 v186, v186, v186
	v_mul_f32_e32 v172, v172, v172
	v_mul_f32_e32 v190, v190, v190
	v_mul_f32_e32 v188, v188, v188
	v_fmamk_f32 v191, v168, 0xbc800000, v128
	v_fmamk_f32 v193, v168, 0xbc800000, v126
	v_fmamk_f32 v196, v168, 0xbc800000, v117
	v_fmamk_f32 v198, v168, 0xbc800000, v115
	v_mul_f32_e32 v194, v194, v194
	v_mul_f32_e32 v192, v192, v192
	v_fmac_f32_e32 v186, v173, v173
	v_fmac_f32_e32 v172, v169, v169
	v_fmac_f32_e32 v190, v189, v189
	v_fmac_f32_e32 v188, v187, v187
	v_fmamk_f32 v195, v168, 0xbc800000, v116
	v_fmamk_f32 v197, v168, 0xbc800000, v114
	v_mul_f32_e32 v198, v198, v198
	v_mul_f32_e32 v196, v196, v196
	v_fmac_f32_e32 v194, v193, v193
	v_fmac_f32_e32 v192, v191, v191
	v_add_f32_e32 v169, v186, v172
	v_add_f32_e32 v172, v190, v188
	v_fmac_f32_e32 v198, v197, v197
	v_fmac_f32_e32 v196, v195, v195
	v_add_f32_e32 v173, v194, v192
	v_add_f32_e32 v169, v169, v172
	v_add_f32_e32 v186, v198, v196
	v_add_f32_e32 v169, v173, v169
	v_add_f32_e32 v169, v186, v169
	v_mov_b32_e32 v172, v169
	s_nop 1
	v_permlane16_swap_b32_e32 v169, v172
	ds_read_b64 v[186:187], v183 offset:9600
	s_waitcnt lgkmcnt(1)
	v_add_f32_e32 v169, v169, v172
	ds_bpermute_b32 v172, v202, v169
	s_waitcnt lgkmcnt(1)
	v_mul_f32_e32 v14, v14, v187
	v_mul_f32_e32 v15, v15, v187
	v_mul_f32_e32 v16, v16, v187
	v_mul_f32_e32 v17, v17, v187
	v_mul_f32_e32 v10, v10, v187
	v_mul_f32_e32 v11, v11, v187
	v_mul_f32_e32 v12, v12, v187
	v_mul_f32_e32 v13, v13, v187
	v_mul_f32_e32 v6, v6, v187
	v_mul_f32_e32 v7, v7, v187
	v_mul_f32_e32 v8, v8, v187
	v_mul_f32_e32 v9, v9, v187
	v_mul_f32_e32 v2, v2, v187
	v_mul_f32_e32 v3, v3, v187
	v_mul_f32_e32 v4, v4, v187
	v_mul_f32_e32 v5, v5, v187
	s_waitcnt vmcnt(3)
	v_lshlrev_b32_e32 v186, 16, v224
	v_and_b32_e32 v187, 0xffff0000, v224
	v_lshlrev_b32_e32 v174, 16, v225
	v_and_b32_e32 v175, 0xffff0000, v225
	s_waitcnt vmcnt(2)
	v_lshlrev_b32_e32 v188, 16, v232
	v_and_b32_e32 v189, 0xffff0000, v232
	v_lshlrev_b32_e32 v180, 16, v233
	v_and_b32_e32 v181, 0xffff0000, v233
	s_waitcnt vmcnt(1)
	v_lshlrev_b32_e32 v190, 16, v234
	v_and_b32_e32 v191, 0xffff0000, v234
	v_lshlrev_b32_e32 v176, 16, v235
	v_and_b32_e32 v177, 0xffff0000, v235
	s_waitcnt vmcnt(0)
	v_lshlrev_b32_e32 v192, 16, v236
	v_and_b32_e32 v193, 0xffff0000, v236
	v_lshlrev_b32_e32 v178, 16, v237
	v_and_b32_e32 v179, 0xffff0000, v237
	v_pk_fma_f32 v[16:17], v[140:141], v[16:17], v[174:175]
	v_pk_fma_f32 v[14:15], v[138:139], v[14:15], v[186:187]
	v_pk_fma_f32 v[12:13], v[144:145], v[12:13], v[180:181]
	v_pk_fma_f32 v[10:11], v[142:143], v[10:11], v[188:189]
	v_pk_fma_f32 v[8:9], v[136:137], v[8:9], v[176:177]
	v_pk_fma_f32 v[6:7], v[134:135], v[6:7], v[190:191]
	v_pk_fma_f32 v[4:5], v[132:133], v[4:5], v[178:179]
	v_pk_fma_f32 v[2:3], v[130:131], v[2:3], v[192:193]
	s_nop 0
	s_and_saveexec_b64 s[0:1], s[6:7]
	s_cbranch_execz .LBB0_1493
	s_lshl_b32 s19, s33, 11
	s_add_i32 s19, s17, s19
	v_mul_f32_e32 v130, 0x3c800000, v168
	s_waitcnt lgkmcnt(0)
	v_add_f32_e32 v131, v169, v172
	v_lshl_add_u32 v132, v170, 5, s19
	ds_write_b64 v132, v[130:131]
.LBB0_1493:
	s_or_b64 exec, exec, s[0:1]
	v_add_f32_e32 v130, v111, v110
	v_add_f32_e32 v131, v112, v113
	v_add_f32_e32 v132, v107, v106
	v_add_f32_e32 v133, v108, v109
	v_add_f32_e32 v130, v130, v131
	v_add_f32_e32 v133, v132, v133
	v_add_f32_e32 v132, v132, v132
	v_add_f32_e32 v131, 0, v130
	v_add_f32_e32 v135, v102, v103
	v_add_f32_e32 v137, v104, v105
	v_mov_b32_e32 v136, v99
	v_add_f32_e32 v134, v98, v99
	v_add_f32_e32 v135, v135, v137
	v_add_f32_e32 v130, v100, v101
	v_add_f32_e32 v131, v133, v131
	s_nop 0
	v_add_f32_e32 v130, v134, v130
	v_add_f32_e32 v131, v135, v131
	s_nop 0
	v_add_f32_e32 v130, v130, v131
	v_mov_b32_e32 v131, v130
	s_nop 1
	v_permlane16_swap_b32_e32 v130, v131
	s_waitcnt lgkmcnt(0)
	v_add_f32_e32 v130, v130, v131
	v_mov_b32_e32 v131, v130
	s_nop 1
	v_permlane32_swap_b32_e32 v130, v131
	s_waitcnt lgkmcnt(0)
	v_add_f32_e32 v130, v130, v131
	v_fmamk_f32 v132, v130, 0xbc800000, v113
	v_fmamk_f32 v134, v130, 0xbc800000, v111
	v_fmamk_f32 v131, v130, 0xbc800000, v112
	v_fmamk_f32 v133, v130, 0xbc800000, v110
	v_mul_f32_e32 v134, v134, v134
	v_mul_f32_e32 v132, v132, v132
	v_fmac_f32_e32 v134, v133, v133
	v_fmac_f32_e32 v132, v131, v131
	v_fmamk_f32 v133, v130, 0xbc800000, v109
	v_fmamk_f32 v135, v130, 0xbc800000, v107
	v_add_f32_e32 v131, v134, v132
	v_fmamk_f32 v132, v130, 0xbc800000, v108
	v_fmamk_f32 v134, v130, 0xbc800000, v106
	v_mul_f32_e32 v135, v135, v135
	v_mul_f32_e32 v133, v133, v133
	v_fmac_f32_e32 v135, v134, v134
	v_fmac_f32_e32 v133, v132, v132
	v_add_f32_e32 v132, v135, v133
	v_fmamk_f32 v133, v130, 0xbc800000, v105
	v_fmamk_f32 v135, v130, 0xbc800000, v103
	v_add_f32_e32 v131, v131, v132
	v_fmamk_f32 v132, v130, 0xbc800000, v104
	v_fmamk_f32 v134, v130, 0xbc800000, v102
	v_mul_f32_e32 v135, v135, v135
	v_mul_f32_e32 v133, v133, v133
	v_fmac_f32_e32 v135, v134, v134
	v_fmac_f32_e32 v133, v132, v132
	v_add_f32_e32 v132, v135, v133
	v_fmamk_f32 v133, v130, 0xbc800000, v101
	v_fmamk_f32 v135, v130, 0xbc800000, v99
	v_add_f32_e32 v131, v132, v131
	v_fmamk_f32 v132, v130, 0xbc800000, v100
	v_fmamk_f32 v134, v130, 0xbc800000, v98
	v_mul_f32_e32 v135, v135, v135
	v_mul_f32_e32 v133, v133, v133
	v_fmac_f32_e32 v135, v134, v134
	v_fmac_f32_e32 v133, v132, v132
	v_add_f32_e32 v132, v135, v133
	v_add_f32_e32 v131, v132, v131
	v_mov_b32_e32 v132, v131
	s_nop 1
	v_permlane16_swap_b32_e32 v131, v132
	s_waitcnt lgkmcnt(0)
	v_add_f32_e32 v131, v131, v132
	v_mov_b32_e32 v132, v131
	s_nop 1
	v_permlane32_swap_b32_e32 v131, v132
	s_and_saveexec_b64 s[0:1], s[6:7]
	s_cbranch_execz .LBB0_1495
	s_lshl_b32 s19, s33, 11
	s_add_i32 s19, s17, s19
	v_mul_f32_e32 v130, 0x3c800000, v130
	s_waitcnt lgkmcnt(0)
	v_add_f32_e32 v131, v131, v132
	v_lshl_add_u32 v132, v170, 5, s19
	ds_write_b64 v132, v[130:131] offset:512
.LBB0_1495:
	s_or_b64 exec, exec, s[0:1]
	s_waitcnt lgkmcnt(0)
	v_add_f32_e32 v130, v95, v94
	v_add_f32_e32 v131, v96, v97
	v_add_f32_e32 v132, v91, v90
	v_add_f32_e32 v133, v92, v93
	v_add_f32_e32 v130, v130, v131
	v_add_f32_e32 v133, v132, v133
	v_add_f32_e32 v132, v132, v132
	v_add_f32_e32 v131, 0, v130
	v_add_f32_e32 v135, v86, v87
	v_add_f32_e32 v137, v88, v89
	v_mov_b32_e32 v136, v83
	v_add_f32_e32 v134, v82, v83
	v_add_f32_e32 v135, v135, v137
	v_add_f32_e32 v130, v84, v85
	v_add_f32_e32 v131, v133, v131
	s_nop 0
	v_add_f32_e32 v130, v134, v130
	v_add_f32_e32 v131, v135, v131
	s_nop 0
	v_add_f32_e32 v130, v130, v131
	v_mov_b32_e32 v131, v130
	s_nop 1
	v_permlane16_swap_b32_e32 v130, v131
	s_waitcnt lgkmcnt(0)
	v_add_f32_e32 v130, v130, v131
	v_mov_b32_e32 v131, v130
	s_nop 1
	v_permlane32_swap_b32_e32 v130, v131
	s_waitcnt lgkmcnt(0)
	v_add_f32_e32 v130, v130, v131
	v_fmamk_f32 v132, v130, 0xbc800000, v97
	v_fmamk_f32 v134, v130, 0xbc800000, v95
	v_fmamk_f32 v131, v130, 0xbc800000, v96
	v_fmamk_f32 v133, v130, 0xbc800000, v94
	v_mul_f32_e32 v134, v134, v134
	v_mul_f32_e32 v132, v132, v132
	v_fmac_f32_e32 v134, v133, v133
	v_fmac_f32_e32 v132, v131, v131
	v_fmamk_f32 v133, v130, 0xbc800000, v93
	v_fmamk_f32 v135, v130, 0xbc800000, v91
	v_add_f32_e32 v131, v134, v132
	v_fmamk_f32 v132, v130, 0xbc800000, v92
	v_fmamk_f32 v134, v130, 0xbc800000, v90
	v_mul_f32_e32 v135, v135, v135
	v_mul_f32_e32 v133, v133, v133
	v_fmac_f32_e32 v135, v134, v134
	v_fmac_f32_e32 v133, v132, v132
	v_add_f32_e32 v132, v135, v133
	v_fmamk_f32 v133, v130, 0xbc800000, v89
	v_fmamk_f32 v135, v130, 0xbc800000, v87
	v_add_f32_e32 v131, v131, v132
	v_fmamk_f32 v132, v130, 0xbc800000, v88
	v_fmamk_f32 v134, v130, 0xbc800000, v86
	v_mul_f32_e32 v135, v135, v135
	v_mul_f32_e32 v133, v133, v133
	v_fmac_f32_e32 v135, v134, v134
	v_fmac_f32_e32 v133, v132, v132
	v_add_f32_e32 v132, v135, v133
	v_fmamk_f32 v133, v130, 0xbc800000, v85
	v_fmamk_f32 v135, v130, 0xbc800000, v83
	v_add_f32_e32 v131, v132, v131
	v_fmamk_f32 v132, v130, 0xbc800000, v84
	v_fmamk_f32 v134, v130, 0xbc800000, v82
	v_mul_f32_e32 v135, v135, v135
	v_mul_f32_e32 v133, v133, v133
	v_fmac_f32_e32 v135, v134, v134
	v_fmac_f32_e32 v133, v132, v132
	v_add_f32_e32 v132, v135, v133
	v_add_f32_e32 v131, v132, v131
	v_mov_b32_e32 v132, v131
	s_nop 1
	v_permlane16_swap_b32_e32 v131, v132
	s_waitcnt lgkmcnt(0)
	v_add_f32_e32 v131, v131, v132
	v_mov_b32_e32 v132, v131
	s_nop 1
	v_permlane32_swap_b32_e32 v131, v132
	s_and_saveexec_b64 s[0:1], s[6:7]
	s_cbranch_execz .LBB0_1497
	s_lshl_b32 s19, s33, 11
	s_add_i32 s19, s17, s19
	v_mul_f32_e32 v130, 0x3c800000, v130
	s_waitcnt lgkmcnt(0)
	v_add_f32_e32 v131, v131, v132
	v_lshl_add_u32 v132, v170, 5, s19
	ds_write_b64 v132, v[130:131] offset:1024
.LBB0_1497:
	s_or_b64 exec, exec, s[0:1]
	s_waitcnt lgkmcnt(0)
	v_add_f32_e32 v130, v79, v78
	v_add_f32_e32 v131, v80, v81
	v_add_f32_e32 v132, v75, v74
	v_add_f32_e32 v133, v76, v77
	v_add_f32_e32 v130, v130, v131
	v_add_f32_e32 v133, v132, v133
	v_add_f32_e32 v132, v132, v132
	v_add_f32_e32 v131, 0, v130
	v_add_f32_e32 v135, v70, v71
	v_add_f32_e32 v137, v72, v73
	v_mov_b32_e32 v136, v67
	v_add_f32_e32 v134, v66, v67
	v_add_f32_e32 v135, v135, v137
	v_add_f32_e32 v130, v68, v69
	v_add_f32_e32 v131, v133, v131
	s_nop 0
	v_add_f32_e32 v130, v134, v130
	v_add_f32_e32 v131, v135, v131
	s_nop 0
	v_add_f32_e32 v130, v130, v131
	v_mov_b32_e32 v131, v130
	s_nop 1
	v_permlane16_swap_b32_e32 v130, v131
	s_waitcnt lgkmcnt(0)
	v_add_f32_e32 v130, v130, v131
	v_mov_b32_e32 v131, v130
	s_nop 1
	v_permlane32_swap_b32_e32 v130, v131
	s_waitcnt lgkmcnt(0)
	v_add_f32_e32 v130, v130, v131
	v_fmamk_f32 v132, v130, 0xbc800000, v81
	v_fmamk_f32 v134, v130, 0xbc800000, v79
	v_fmamk_f32 v131, v130, 0xbc800000, v80
	v_fmamk_f32 v133, v130, 0xbc800000, v78
	v_mul_f32_e32 v134, v134, v134
	v_mul_f32_e32 v132, v132, v132
	v_fmac_f32_e32 v134, v133, v133
	v_fmac_f32_e32 v132, v131, v131
	v_fmamk_f32 v133, v130, 0xbc800000, v77
	v_fmamk_f32 v135, v130, 0xbc800000, v75
	v_add_f32_e32 v131, v134, v132
	v_fmamk_f32 v132, v130, 0xbc800000, v76
	v_fmamk_f32 v134, v130, 0xbc800000, v74
	v_mul_f32_e32 v135, v135, v135
	v_mul_f32_e32 v133, v133, v133
	v_fmac_f32_e32 v135, v134, v134
	v_fmac_f32_e32 v133, v132, v132
	v_add_f32_e32 v132, v135, v133
	v_fmamk_f32 v133, v130, 0xbc800000, v73
	v_fmamk_f32 v135, v130, 0xbc800000, v71
	v_add_f32_e32 v131, v131, v132
	v_fmamk_f32 v132, v130, 0xbc800000, v72
	v_fmamk_f32 v134, v130, 0xbc800000, v70
	v_mul_f32_e32 v135, v135, v135
	v_mul_f32_e32 v133, v133, v133
	v_fmac_f32_e32 v135, v134, v134
	v_fmac_f32_e32 v133, v132, v132
	v_add_f32_e32 v132, v135, v133
	v_fmamk_f32 v133, v130, 0xbc800000, v69
	v_fmamk_f32 v135, v130, 0xbc800000, v67
	v_add_f32_e32 v131, v132, v131
	v_fmamk_f32 v132, v130, 0xbc800000, v68
	v_fmamk_f32 v134, v130, 0xbc800000, v66
	v_mul_f32_e32 v135, v135, v135
	v_mul_f32_e32 v133, v133, v133
	v_fmac_f32_e32 v135, v134, v134
	v_fmac_f32_e32 v133, v132, v132
	v_add_f32_e32 v132, v135, v133
	v_add_f32_e32 v131, v132, v131
	v_mov_b32_e32 v132, v131
	s_nop 1
	v_permlane16_swap_b32_e32 v131, v132
	s_waitcnt lgkmcnt(0)
	v_add_f32_e32 v131, v131, v132
	v_mov_b32_e32 v132, v131
	s_nop 1
	v_permlane32_swap_b32_e32 v131, v132
	s_and_saveexec_b64 s[0:1], s[6:7]
	s_cbranch_execz .LBB0_1499
	s_lshl_b32 s19, s33, 11
	s_add_i32 s19, s17, s19
	v_mul_f32_e32 v130, 0x3c800000, v130
	s_waitcnt lgkmcnt(0)
	v_add_f32_e32 v131, v131, v132
	v_lshl_add_u32 v132, v170, 5, s19
	ds_write_b64 v132, v[130:131] offset:1536
.LBB0_1499:
	s_or_b64 exec, exec, s[0:1]
	s_waitcnt lgkmcnt(0)
	v_add_f32_e32 v130, v63, v62
	v_add_f32_e32 v131, v64, v65
	v_add_f32_e32 v132, v59, v58
	v_add_f32_e32 v133, v60, v61
	v_add_f32_e32 v130, v130, v131
	v_add_f32_e32 v133, v132, v133
	v_add_f32_e32 v132, v132, v132
	v_add_f32_e32 v131, 0, v130
	v_add_f32_e32 v135, v54, v55
	v_add_f32_e32 v137, v56, v57
	v_mov_b32_e32 v136, v51
	v_add_f32_e32 v134, v50, v51
	v_add_f32_e32 v135, v135, v137
	v_add_f32_e32 v130, v52, v53
	v_add_f32_e32 v131, v133, v131
	s_nop 0
	v_add_f32_e32 v130, v134, v130
	v_add_f32_e32 v131, v135, v131
	s_nop 0
	v_add_f32_e32 v130, v130, v131
	v_mov_b32_e32 v131, v130
	s_nop 1
	v_permlane16_swap_b32_e32 v130, v131
	s_waitcnt lgkmcnt(0)
	v_add_f32_e32 v130, v130, v131
	v_mov_b32_e32 v131, v130
	s_nop 1
	v_permlane32_swap_b32_e32 v130, v131
	s_waitcnt lgkmcnt(0)
	v_add_f32_e32 v130, v130, v131
	v_fmamk_f32 v132, v130, 0xbc800000, v65
	v_fmamk_f32 v134, v130, 0xbc800000, v63
	v_fmamk_f32 v131, v130, 0xbc800000, v64
	v_fmamk_f32 v133, v130, 0xbc800000, v62
	v_mul_f32_e32 v134, v134, v134
	v_mul_f32_e32 v132, v132, v132
	v_fmac_f32_e32 v134, v133, v133
	v_fmac_f32_e32 v132, v131, v131
	v_fmamk_f32 v133, v130, 0xbc800000, v61
	v_fmamk_f32 v135, v130, 0xbc800000, v59
	v_add_f32_e32 v131, v134, v132
	v_fmamk_f32 v132, v130, 0xbc800000, v60
	v_fmamk_f32 v134, v130, 0xbc800000, v58
	v_mul_f32_e32 v135, v135, v135
	v_mul_f32_e32 v133, v133, v133
	v_fmac_f32_e32 v135, v134, v134
	v_fmac_f32_e32 v133, v132, v132
	v_add_f32_e32 v132, v135, v133
	v_fmamk_f32 v133, v130, 0xbc800000, v57
	v_fmamk_f32 v135, v130, 0xbc800000, v55
	v_add_f32_e32 v131, v131, v132
	v_fmamk_f32 v132, v130, 0xbc800000, v56
	v_fmamk_f32 v134, v130, 0xbc800000, v54
	v_mul_f32_e32 v135, v135, v135
	v_mul_f32_e32 v133, v133, v133
	v_fmac_f32_e32 v135, v134, v134
	v_fmac_f32_e32 v133, v132, v132
	v_add_f32_e32 v132, v135, v133
	v_fmamk_f32 v133, v130, 0xbc800000, v53
	v_fmamk_f32 v135, v130, 0xbc800000, v51
	v_add_f32_e32 v131, v132, v131
	v_fmamk_f32 v132, v130, 0xbc800000, v52
	v_fmamk_f32 v134, v130, 0xbc800000, v50
	v_mul_f32_e32 v135, v135, v135
	v_mul_f32_e32 v133, v133, v133
	v_fmac_f32_e32 v135, v134, v134
	v_fmac_f32_e32 v133, v132, v132
	v_add_f32_e32 v132, v135, v133
	v_add_f32_e32 v131, v132, v131
	v_mov_b32_e32 v132, v131
	s_nop 1
	v_permlane16_swap_b32_e32 v131, v132
	s_waitcnt lgkmcnt(0)
	v_add_f32_e32 v131, v131, v132
	v_mov_b32_e32 v132, v131
	s_nop 1
	v_permlane32_swap_b32_e32 v131, v132
	s_and_saveexec_b64 s[0:1], s[6:7]
	s_cbranch_execz .LBB0_1501
	s_lshl_b32 s19, s33, 11
	s_add_i32 s19, s17, s19
	v_mul_f32_e32 v130, 0x3c800000, v130
	s_waitcnt lgkmcnt(0)
	v_add_f32_e32 v131, v131, v132
	v_lshl_add_u32 v132, v170, 5, s19
	ds_write_b64 v132, v[130:131] offset:4096
.LBB0_1501:
	s_or_b64 exec, exec, s[0:1]
	s_waitcnt lgkmcnt(0)
	v_add_f32_e32 v130, v47, v46
	v_add_f32_e32 v131, v48, v49
	v_add_f32_e32 v132, v43, v42
	v_add_f32_e32 v133, v44, v45
	v_add_f32_e32 v130, v130, v131
	v_add_f32_e32 v133, v132, v133
	v_add_f32_e32 v132, v132, v132
	v_add_f32_e32 v131, 0, v130
	v_add_f32_e32 v135, v38, v39
	v_add_f32_e32 v137, v40, v41
	v_mov_b32_e32 v136, v35
	v_add_f32_e32 v134, v34, v35
	v_add_f32_e32 v135, v135, v137
	v_add_f32_e32 v130, v36, v37
	v_add_f32_e32 v131, v133, v131
	s_nop 0
	v_add_f32_e32 v130, v134, v130
	v_add_f32_e32 v131, v135, v131
	s_nop 0
	v_add_f32_e32 v130, v130, v131
	v_mov_b32_e32 v131, v130
	s_nop 1
	v_permlane16_swap_b32_e32 v130, v131
	s_waitcnt lgkmcnt(0)
	v_add_f32_e32 v130, v130, v131
	v_mov_b32_e32 v131, v130
	s_nop 1
	v_permlane32_swap_b32_e32 v130, v131
	s_waitcnt lgkmcnt(0)
	v_add_f32_e32 v130, v130, v131
	v_fmamk_f32 v132, v130, 0xbc800000, v49
	v_fmamk_f32 v134, v130, 0xbc800000, v47
	v_fmamk_f32 v131, v130, 0xbc800000, v48
	v_fmamk_f32 v133, v130, 0xbc800000, v46
	v_mul_f32_e32 v134, v134, v134
	v_mul_f32_e32 v132, v132, v132
	v_fmac_f32_e32 v134, v133, v133
	v_fmac_f32_e32 v132, v131, v131
	v_fmamk_f32 v133, v130, 0xbc800000, v45
	v_fmamk_f32 v135, v130, 0xbc800000, v43
	v_add_f32_e32 v131, v134, v132
	v_fmamk_f32 v132, v130, 0xbc800000, v44
	v_fmamk_f32 v134, v130, 0xbc800000, v42
	v_mul_f32_e32 v135, v135, v135
	v_mul_f32_e32 v133, v133, v133
	v_fmac_f32_e32 v135, v134, v134
	v_fmac_f32_e32 v133, v132, v132
	v_add_f32_e32 v132, v135, v133
	v_fmamk_f32 v133, v130, 0xbc800000, v41
	v_fmamk_f32 v135, v130, 0xbc800000, v39
	v_add_f32_e32 v131, v131, v132
	v_fmamk_f32 v132, v130, 0xbc800000, v40
	v_fmamk_f32 v134, v130, 0xbc800000, v38
	v_mul_f32_e32 v135, v135, v135
	v_mul_f32_e32 v133, v133, v133
	v_fmac_f32_e32 v135, v134, v134
	v_fmac_f32_e32 v133, v132, v132
	v_add_f32_e32 v132, v135, v133
	v_fmamk_f32 v133, v130, 0xbc800000, v37
	v_fmamk_f32 v135, v130, 0xbc800000, v35
	v_add_f32_e32 v131, v132, v131
	v_fmamk_f32 v132, v130, 0xbc800000, v36
	v_fmamk_f32 v134, v130, 0xbc800000, v34
	v_mul_f32_e32 v135, v135, v135
	v_mul_f32_e32 v133, v133, v133
	v_fmac_f32_e32 v135, v134, v134
	v_fmac_f32_e32 v133, v132, v132
	v_add_f32_e32 v132, v135, v133
	v_add_f32_e32 v131, v132, v131
	v_mov_b32_e32 v132, v131
	s_nop 1
	v_permlane16_swap_b32_e32 v131, v132
	s_waitcnt lgkmcnt(0)
	v_add_f32_e32 v131, v131, v132
	v_mov_b32_e32 v132, v131
	s_nop 1
	v_permlane32_swap_b32_e32 v131, v132
	s_and_saveexec_b64 s[0:1], s[6:7]
	s_cbranch_execz .LBB0_1503
	s_lshl_b32 s19, s33, 11
	s_add_i32 s19, s17, s19
	v_mul_f32_e32 v130, 0x3c800000, v130
	s_waitcnt lgkmcnt(0)
	v_add_f32_e32 v131, v131, v132
	v_lshl_add_u32 v132, v170, 5, s19
	ds_write_b64 v132, v[130:131] offset:4608
.LBB0_1503:
	s_or_b64 exec, exec, s[0:1]
	s_waitcnt lgkmcnt(0)
	v_add_f32_e32 v130, v31, v30
	v_add_f32_e32 v131, v32, v33
	v_add_f32_e32 v132, v27, v26
	v_add_f32_e32 v133, v28, v29
	v_add_f32_e32 v130, v130, v131
	v_add_f32_e32 v133, v132, v133
	v_add_f32_e32 v132, v132, v132
	v_add_f32_e32 v131, 0, v130
	v_add_f32_e32 v135, v22, v23
	v_add_f32_e32 v137, v24, v25
	v_mov_b32_e32 v136, v19
	v_add_f32_e32 v134, v18, v19
	v_add_f32_e32 v135, v135, v137
	v_add_f32_e32 v130, v20, v21
	v_add_f32_e32 v131, v133, v131
	s_nop 0
	v_add_f32_e32 v130, v134, v130
	v_add_f32_e32 v131, v135, v131
	s_nop 0
	v_add_f32_e32 v130, v130, v131
	v_mov_b32_e32 v131, v130
	s_nop 1
	v_permlane16_swap_b32_e32 v130, v131
	s_waitcnt lgkmcnt(0)
	v_add_f32_e32 v130, v130, v131
	v_mov_b32_e32 v131, v130
	s_nop 1
	v_permlane32_swap_b32_e32 v130, v131
	s_waitcnt lgkmcnt(0)
	v_add_f32_e32 v130, v130, v131
	v_fmamk_f32 v132, v130, 0xbc800000, v33
	v_fmamk_f32 v134, v130, 0xbc800000, v31
	v_fmamk_f32 v131, v130, 0xbc800000, v32
	v_fmamk_f32 v133, v130, 0xbc800000, v30
	v_mul_f32_e32 v134, v134, v134
	v_mul_f32_e32 v132, v132, v132
	v_fmac_f32_e32 v134, v133, v133
	v_fmac_f32_e32 v132, v131, v131
	v_fmamk_f32 v133, v130, 0xbc800000, v29
	v_fmamk_f32 v135, v130, 0xbc800000, v27
	v_add_f32_e32 v131, v134, v132
	v_fmamk_f32 v132, v130, 0xbc800000, v28
	v_fmamk_f32 v134, v130, 0xbc800000, v26
	v_mul_f32_e32 v135, v135, v135
	v_mul_f32_e32 v133, v133, v133
	v_fmac_f32_e32 v135, v134, v134
	v_fmac_f32_e32 v133, v132, v132
	v_add_f32_e32 v132, v135, v133
	v_fmamk_f32 v133, v130, 0xbc800000, v25
	v_fmamk_f32 v135, v130, 0xbc800000, v23
	v_add_f32_e32 v131, v131, v132
	v_fmamk_f32 v132, v130, 0xbc800000, v24
	v_fmamk_f32 v134, v130, 0xbc800000, v22
	v_mul_f32_e32 v135, v135, v135
	v_mul_f32_e32 v133, v133, v133
	v_fmac_f32_e32 v135, v134, v134
	v_fmac_f32_e32 v133, v132, v132
	v_add_f32_e32 v132, v135, v133
	v_fmamk_f32 v133, v130, 0xbc800000, v21
	v_fmamk_f32 v135, v130, 0xbc800000, v19
	v_add_f32_e32 v131, v132, v131
	v_fmamk_f32 v132, v130, 0xbc800000, v20
	v_fmamk_f32 v134, v130, 0xbc800000, v18
	v_mul_f32_e32 v135, v135, v135
	v_mul_f32_e32 v133, v133, v133
	v_fmac_f32_e32 v135, v134, v134
	v_fmac_f32_e32 v133, v132, v132
	v_add_f32_e32 v132, v135, v133
	v_add_f32_e32 v131, v132, v131
	v_mov_b32_e32 v132, v131
	s_nop 1
	v_permlane16_swap_b32_e32 v131, v132
	s_waitcnt lgkmcnt(0)
	v_add_f32_e32 v131, v131, v132
	v_mov_b32_e32 v132, v131
	s_nop 1
	v_permlane32_swap_b32_e32 v131, v132
	s_and_saveexec_b64 s[0:1], s[6:7]
	s_cbranch_execz .LBB0_1505
	s_lshl_b32 s19, s33, 11
	s_add_i32 s19, s17, s19
	v_mul_f32_e32 v130, 0x3c800000, v130
	s_waitcnt lgkmcnt(0)
	v_add_f32_e32 v131, v131, v132
	v_lshl_add_u32 v132, v170, 5, s19
	ds_write_b64 v132, v[130:131] offset:5120
.LBB0_1505:
	s_or_b64 exec, exec, s[0:1]
	s_waitcnt lgkmcnt(0)
	v_add_f32_e32 v130, v15, v14
	v_add_f32_e32 v131, v16, v17
	v_add_f32_e32 v132, v11, v10
	v_add_f32_e32 v133, v12, v13
	v_add_f32_e32 v130, v130, v131
	v_add_f32_e32 v133, v132, v133
	v_add_f32_e32 v132, v132, v132
	v_add_f32_e32 v131, 0, v130
	v_add_f32_e32 v135, v6, v7
	v_add_f32_e32 v137, v8, v9
	v_mov_b32_e32 v136, v3
	v_add_f32_e32 v134, v2, v3
	v_add_f32_e32 v135, v135, v137
	v_add_f32_e32 v130, v4, v5
	v_add_f32_e32 v131, v133, v131
	s_nop 0
	v_add_f32_e32 v130, v134, v130
	v_add_f32_e32 v131, v135, v131
	s_nop 0
	v_add_f32_e32 v130, v130, v131
	v_mov_b32_e32 v131, v130
	s_nop 1
	v_permlane16_swap_b32_e32 v130, v131
	s_waitcnt lgkmcnt(0)
	v_add_f32_e32 v130, v130, v131
	v_mov_b32_e32 v131, v130
	s_nop 1
	v_permlane32_swap_b32_e32 v130, v131
	s_waitcnt lgkmcnt(0)
	v_add_f32_e32 v130, v130, v131
	v_fmamk_f32 v132, v130, 0xbc800000, v17
	v_fmamk_f32 v134, v130, 0xbc800000, v15
	v_fmamk_f32 v131, v130, 0xbc800000, v16
	v_fmamk_f32 v133, v130, 0xbc800000, v14
	v_mul_f32_e32 v134, v134, v134
	v_mul_f32_e32 v132, v132, v132
	v_fmac_f32_e32 v134, v133, v133
	v_fmac_f32_e32 v132, v131, v131
	v_fmamk_f32 v133, v130, 0xbc800000, v13
	v_fmamk_f32 v135, v130, 0xbc800000, v11
	v_add_f32_e32 v131, v134, v132
	v_fmamk_f32 v132, v130, 0xbc800000, v12
	v_fmamk_f32 v134, v130, 0xbc800000, v10
	v_mul_f32_e32 v135, v135, v135
	v_mul_f32_e32 v133, v133, v133
	v_fmac_f32_e32 v135, v134, v134
	v_fmac_f32_e32 v133, v132, v132
	v_add_f32_e32 v132, v135, v133
	v_fmamk_f32 v133, v130, 0xbc800000, v9
	v_fmamk_f32 v135, v130, 0xbc800000, v7
	v_add_f32_e32 v131, v131, v132
	v_fmamk_f32 v132, v130, 0xbc800000, v8
	v_fmamk_f32 v134, v130, 0xbc800000, v6
	v_mul_f32_e32 v135, v135, v135
	v_mul_f32_e32 v133, v133, v133
	v_fmac_f32_e32 v135, v134, v134
	v_fmac_f32_e32 v133, v132, v132
	v_add_f32_e32 v132, v135, v133
	v_fmamk_f32 v133, v130, 0xbc800000, v5
	v_fmamk_f32 v135, v130, 0xbc800000, v3
	v_add_f32_e32 v131, v132, v131
	v_fmamk_f32 v132, v130, 0xbc800000, v4
	v_fmamk_f32 v134, v130, 0xbc800000, v2
	v_mul_f32_e32 v135, v135, v135
	v_mul_f32_e32 v133, v133, v133
	v_fmac_f32_e32 v135, v134, v134
	v_fmac_f32_e32 v133, v132, v132
	v_add_f32_e32 v132, v135, v133
	v_add_f32_e32 v131, v132, v131
	v_mov_b32_e32 v132, v131
	s_nop 1
	v_permlane16_swap_b32_e32 v131, v132
	s_waitcnt lgkmcnt(0)
	v_add_f32_e32 v131, v131, v132
	v_mov_b32_e32 v132, v131
	s_nop 1
	v_permlane32_swap_b32_e32 v131, v132
	s_and_saveexec_b64 s[0:1], s[6:7]
	s_cbranch_execz .LBB0_1507
	s_lshl_b32 s6, s33, 11
	s_add_i32 s17, s17, s6
	v_mul_f32_e32 v130, 0x3c800000, v130
	s_waitcnt lgkmcnt(0)
	v_add_f32_e32 v131, v131, v132
	v_lshl_add_u32 v132, v170, 5, s17
	ds_write_b64 v132, v[130:131] offset:5632

.LBB0_1678:
	s_lshl_b32 s16, s24, 8
	v_add_u32_e32 v249, s16, v149
	v_lshlrev_b32_e32 v249, 11, v249
	s_lshl_b32 s17, s8, 8
	s_lshl_b32 s18, s25, 5
	s_or_b32 s17, s17, s18
	v_lshrrev_b32_e32 v230, 2, v0
	v_and_or_b32 v230, v230, 12, s17
	v_lshl_add_u32 v248, v230, 1, v249
	s_lshl_b32 s19, s24, 5
	s_and_b32 s19, s19, 0xfffffc00
	s_lshl_b32 s19, s19, 2
	s_add_i32 s19, s19, 0x112000
	v_lshl_add_u32 v250, v230, 2, s19
	global_load_dwordx4 v[232:235], v250, s[34:35]
	global_load_dwordx4 v[236:239], v250, s[34:35] offset:64
	global_load_dwordx4 v[240:243], v250, s[34:35] offset:512
	global_load_dwordx4 v[244:247], v250, s[34:35] offset:576
	global_load_dwordx2 v[164:165], v248, s[56:57]
	global_load_dwordx2 v[166:167], v248, s[56:57] offset:32
	global_load_dwordx2 v[168:169], v248, s[56:57] offset:256
	global_load_dwordx2 v[170:171], v248, s[56:57] offset:288
	v_add_u32_e32 v249, 0x8000, v248
	global_load_dwordx2 v[172:173], v249, s[56:57]
	global_load_dwordx2 v[174:175], v249, s[56:57] offset:32
	global_load_dwordx2 v[176:177], v249, s[56:57] offset:256
	global_load_dwordx2 v[178:179], v249, s[56:57] offset:288
	v_add_u32_e32 v249, 0x10000, v248
	global_load_dwordx2 v[180:181], v249, s[56:57]
	global_load_dwordx2 v[182:183], v249, s[56:57] offset:32
	global_load_dwordx2 v[184:185], v249, s[56:57] offset:256
	global_load_dwordx2 v[186:187], v249, s[56:57] offset:288
	v_add_u32_e32 v249, 0x18000, v248
	global_load_dwordx2 v[188:189], v249, s[56:57]
	global_load_dwordx2 v[190:191], v249, s[56:57] offset:32
	global_load_dwordx2 v[192:193], v249, s[56:57] offset:256
	global_load_dwordx2 v[194:195], v249, s[56:57] offset:288
	v_add_u32_e32 v249, 0x40000, v248
	global_load_dwordx2 v[196:197], v249, s[56:57]
	global_load_dwordx2 v[198:199], v249, s[56:57] offset:32
	global_load_dwordx2 v[200:201], v249, s[56:57] offset:256
	global_load_dwordx2 v[204:205], v249, s[56:57] offset:288
	v_add_u32_e32 v249, 0x48000, v248
	global_load_dwordx2 v[206:207], v249, s[56:57]
	global_load_dwordx2 v[208:209], v249, s[56:57] offset:32
	global_load_dwordx2 v[210:211], v249, s[56:57] offset:256
	global_load_dwordx2 v[212:213], v249, s[56:57] offset:288
	v_add_u32_e32 v249, 0x50000, v248
	global_load_dwordx2 v[214:215], v249, s[56:57]
	global_load_dwordx2 v[216:217], v249, s[56:57] offset:32
	global_load_dwordx2 v[218:219], v249, s[56:57] offset:256
	global_load_dwordx2 v[220:221], v249, s[56:57] offset:288
	v_add_u32_e32 v249, 0x58000, v248
	global_load_dwordx2 v[222:223], v249, s[56:57]
	global_load_dwordx2 v[224:225], v249, s[56:57] offset:32
	global_load_dwordx2 v[226:227], v249, s[56:57] offset:256
	global_load_dwordx2 v[228:229], v249, s[56:57] offset:288
	v_add_f32_e32 v130, v127, v126
	v_add_f32_e32 v131, v128, v129
	v_add_f32_e32 v132, v123, v122
	v_add_f32_e32 v133, v124, v125
	v_add_f32_e32 v130, v130, v131
	v_add_f32_e32 v133, v132, v133
	v_add_f32_e32 v132, v132, v132
	v_add_f32_e32 v131, 0, v130
	v_add_f32_e32 v135, v118, v119
	v_add_f32_e32 v137, v120, v121
	v_mov_b32_e32 v136, v111
	v_add_f32_e32 v134, v110, v111
	v_add_f32_e32 v135, v135, v137
	v_add_f32_e32 v130, v112, v113
	v_add_f32_e32 v131, v133, v131
	v_add_f32_e32 v130, v134, v130
	v_add_f32_e32 v131, v135, v131
	v_add_f32_e32 v130, v130, v131
	v_mov_b32_e32 v131, v130
	s_nop 1
	v_permlane16_swap_b32_e32 v130, v131
	s_lshl_b32 s0, s25, 3
	s_add_i32 s2, s0, 0
	s_barrier
	s_waitcnt lgkmcnt(0)
	v_add_f32_e32 v130, v130, v131
	v_mov_b32_e32 v131, v130
	s_nop 1
	v_permlane32_swap_b32_e32 v130, v131
	s_waitcnt lgkmcnt(0)
	v_add_f32_e32 v131, v130, v131
	v_fmamk_f32 v132, v131, 0xbc800000, v129
	v_fmamk_f32 v134, v131, 0xbc800000, v127
	v_fmamk_f32 v130, v131, 0xbc800000, v128
	v_fmamk_f32 v133, v131, 0xbc800000, v126
	v_mul_f32_e32 v134, v134, v134
	v_mul_f32_e32 v132, v132, v132
	v_fmac_f32_e32 v134, v133, v133
	v_fmac_f32_e32 v132, v130, v130
	v_add_f32_e32 v130, v134, v132
	v_fmamk_f32 v133, v131, 0xbc800000, v125
	v_fmamk_f32 v135, v131, 0xbc800000, v123
	v_fmamk_f32 v132, v131, 0xbc800000, v124
	v_fmamk_f32 v134, v131, 0xbc800000, v122
	v_mul_f32_e32 v135, v135, v135
	v_mul_f32_e32 v133, v133, v133
	v_fmac_f32_e32 v135, v134, v134
	v_fmac_f32_e32 v133, v132, v132
	v_add_f32_e32 v132, v135, v133
	v_fmamk_f32 v133, v131, 0xbc800000, v121
	v_fmamk_f32 v135, v131, 0xbc800000, v119
	v_add_f32_e32 v130, v130, v132
	v_fmamk_f32 v132, v131, 0xbc800000, v120
	v_fmamk_f32 v134, v131, 0xbc800000, v118
	v_mul_f32_e32 v135, v135, v135
	v_mul_f32_e32 v133, v133, v133
	v_fmac_f32_e32 v135, v134, v134
	v_fmac_f32_e32 v133, v132, v132
	v_add_f32_e32 v132, v135, v133
	v_fmamk_f32 v133, v131, 0xbc800000, v113
	v_fmamk_f32 v135, v131, 0xbc800000, v111
	v_add_f32_e32 v130, v132, v130
	v_fmamk_f32 v132, v131, 0xbc800000, v112
	v_fmamk_f32 v134, v131, 0xbc800000, v110
	v_mul_f32_e32 v135, v135, v135
	v_mul_f32_e32 v133, v133, v133
	v_fmac_f32_e32 v135, v134, v134
	v_fmac_f32_e32 v133, v132, v132
	v_add_f32_e32 v132, v135, v133
	v_add_f32_e32 v132, v132, v130
	v_mov_b32_e32 v133, v132
	s_nop 1
	v_permlane16_swap_b32_e32 v132, v133
	v_and_b32_e32 v130, 63, v0
	v_cmp_gt_u32_e32 vcc, 16, v130
	s_waitcnt lgkmcnt(0)
	v_add_f32_e32 v132, v132, v133
	v_mov_b32_e32 v133, v132
	s_nop 1
	v_permlane32_swap_b32_e32 v132, v133
	s_and_saveexec_b64 s[0:1], vcc
	s_cbranch_execz .LBB0_1680
	s_lshl_b32 s3, s27, 11
	s_add_i32 s3, s2, s3
	v_mul_f32_e32 v134, 0x3c800000, v131
	s_waitcnt lgkmcnt(0)
	v_add_f32_e32 v135, v132, v133
	v_lshl_add_u32 v131, v146, 5, s3
	ds_write_b64 v131, v[134:135]
.LBB0_1680:
	s_or_b64 exec, exec, s[0:1]
	s_waitcnt lgkmcnt(0)
	v_add_f32_e32 v132, v115, v114
	v_add_f32_e32 v133, v116, v117
	v_add_f32_e32 v134, v107, v106
	v_add_f32_e32 v135, v108, v109
	v_add_f32_e32 v131, v132, v133
	v_add_f32_e32 v135, v134, v135
	v_add_f32_e32 v134, v134, v134
	v_add_f32_e32 v133, 0, v131
	v_add_f32_e32 v137, v102, v103
	v_add_f32_e32 v139, v104, v105
	v_mov_b32_e32 v138, v99
	v_mov_b32_e32 v134, v100
	v_add_f32_e32 v136, v98, v99
	v_add_f32_e32 v137, v137, v139
	v_add_f32_e32 v132, v100, v101
	v_add_f32_e32 v133, v135, v133
	v_add_f32_e32 v132, v136, v132
	v_add_f32_e32 v133, v137, v133
	v_add_f32_e32 v131, v132, v133
	v_mov_b32_e32 v132, v131
	s_nop 1
	v_permlane16_swap_b32_e32 v131, v132
	s_waitcnt lgkmcnt(0)
	v_add_f32_e32 v131, v131, v132
	v_mov_b32_e32 v132, v131
	s_nop 1
	v_permlane32_swap_b32_e32 v131, v132
	s_waitcnt lgkmcnt(0)
	v_add_f32_e32 v131, v131, v132
	v_fmamk_f32 v133, v131, 0xbc800000, v117
	v_fmamk_f32 v135, v131, 0xbc800000, v115
	v_fmamk_f32 v132, v131, 0xbc800000, v116
	v_fmamk_f32 v134, v131, 0xbc800000, v114
	v_mul_f32_e32 v135, v135, v135
	v_mul_f32_e32 v133, v133, v133
	v_fmac_f32_e32 v135, v134, v134
	v_fmac_f32_e32 v133, v132, v132
	v_add_f32_e32 v132, v135, v133
	v_fmamk_f32 v134, v131, 0xbc800000, v109
	v_fmamk_f32 v136, v131, 0xbc800000, v107
	v_fmamk_f32 v133, v131, 0xbc800000, v108
	v_fmamk_f32 v135, v131, 0xbc800000, v106
	v_mul_f32_e32 v136, v136, v136
	v_mul_f32_e32 v134, v134, v134
	v_fmac_f32_e32 v136, v135, v135
	v_fmac_f32_e32 v134, v133, v133
	v_add_f32_e32 v133, v136, v134
	v_fmamk_f32 v134, v131, 0xbc800000, v105
	v_fmamk_f32 v136, v131, 0xbc800000, v103
	v_add_f32_e32 v132, v132, v133
	v_fmamk_f32 v133, v131, 0xbc800000, v104
	v_fmamk_f32 v135, v131, 0xbc800000, v102
	v_mul_f32_e32 v136, v136, v136
	v_mul_f32_e32 v134, v134, v134
	v_fmac_f32_e32 v136, v135, v135
	v_fmac_f32_e32 v134, v133, v133
	v_add_f32_e32 v133, v136, v134
	v_fmamk_f32 v134, v131, 0xbc800000, v101
	v_fmamk_f32 v136, v131, 0xbc800000, v99
	v_add_f32_e32 v132, v133, v132
	v_fmamk_f32 v133, v131, 0xbc800000, v100
	v_fmamk_f32 v135, v131, 0xbc800000, v98
	v_mul_f32_e32 v136, v136, v136
	v_mul_f32_e32 v134, v134, v134
	v_fmac_f32_e32 v136, v135, v135
	v_fmac_f32_e32 v134, v133, v133
	v_add_f32_e32 v133, v136, v134
	v_add_f32_e32 v132, v133, v132
	v_mov_b32_e32 v133, v132
	s_nop 1
	v_permlane16_swap_b32_e32 v132, v133
	s_waitcnt lgkmcnt(0)
	v_add_f32_e32 v132, v132, v133
	v_mov_b32_e32 v133, v132
	s_nop 1
	v_permlane32_swap_b32_e32 v132, v133
	s_and_saveexec_b64 s[0:1], vcc
	s_cbranch_execz .LBB0_1682
	s_lshl_b32 s3, s27, 11
	s_add_i32 s3, s2, s3
	v_mul_f32_e32 v134, 0x3c800000, v131
	s_waitcnt lgkmcnt(0)
	v_add_f32_e32 v135, v132, v133
	v_lshl_add_u32 v131, v146, 5, s3
	ds_write_b64 v131, v[134:135] offset:512
.LBB0_1682:
	s_or_b64 exec, exec, s[0:1]
	s_waitcnt lgkmcnt(0)
	v_add_f32_e32 v132, v95, v94
	v_add_f32_e32 v133, v96, v97
	v_add_f32_e32 v134, v91, v90
	v_add_f32_e32 v135, v92, v93
	v_add_f32_e32 v131, v132, v133
	v_add_f32_e32 v135, v134, v135
	v_add_f32_e32 v134, v134, v134
	v_add_f32_e32 v133, 0, v131
	v_add_f32_e32 v137, v86, v87
	v_add_f32_e32 v139, v88, v89
	v_mov_b32_e32 v138, v83
	v_mov_b32_e32 v134, v84
	v_add_f32_e32 v136, v82, v83
	v_add_f32_e32 v137, v137, v139
	v_add_f32_e32 v132, v84, v85
	v_add_f32_e32 v133, v135, v133
	v_add_f32_e32 v132, v136, v132
	v_add_f32_e32 v133, v137, v133
	v_add_f32_e32 v131, v132, v133
	v_mov_b32_e32 v132, v131
	s_nop 1
	v_permlane16_swap_b32_e32 v131, v132
	s_waitcnt lgkmcnt(0)
	v_add_f32_e32 v131, v131, v132
	v_mov_b32_e32 v132, v131
	s_nop 1
	v_permlane32_swap_b32_e32 v131, v132
	s_waitcnt lgkmcnt(0)
	v_add_f32_e32 v131, v131, v132
	v_fmamk_f32 v133, v131, 0xbc800000, v97
	v_fmamk_f32 v135, v131, 0xbc800000, v95
	v_fmamk_f32 v132, v131, 0xbc800000, v96
	v_fmamk_f32 v134, v131, 0xbc800000, v94
	v_mul_f32_e32 v135, v135, v135
	v_mul_f32_e32 v133, v133, v133
	v_fmac_f32_e32 v135, v134, v134
	v_fmac_f32_e32 v133, v132, v132
	v_add_f32_e32 v132, v135, v133
	v_fmamk_f32 v134, v131, 0xbc800000, v93
	v_fmamk_f32 v136, v131, 0xbc800000, v91
	v_fmamk_f32 v133, v131, 0xbc800000, v92
	v_fmamk_f32 v135, v131, 0xbc800000, v90
	v_mul_f32_e32 v136, v136, v136
	v_mul_f32_e32 v134, v134, v134
	v_fmac_f32_e32 v136, v135, v135
	v_fmac_f32_e32 v134, v133, v133
	v_add_f32_e32 v133, v136, v134
	v_fmamk_f32 v134, v131, 0xbc800000, v89
	v_fmamk_f32 v136, v131, 0xbc800000, v87
	v_add_f32_e32 v132, v132, v133
	v_fmamk_f32 v133, v131, 0xbc800000, v88
	v_fmamk_f32 v135, v131, 0xbc800000, v86
	v_mul_f32_e32 v136, v136, v136
	v_mul_f32_e32 v134, v134, v134
	v_fmac_f32_e32 v136, v135, v135
	v_fmac_f32_e32 v134, v133, v133
	v_add_f32_e32 v133, v136, v134
	v_fmamk_f32 v134, v131, 0xbc800000, v85
	v_fmamk_f32 v136, v131, 0xbc800000, v83
	v_add_f32_e32 v132, v133, v132
	v_fmamk_f32 v133, v131, 0xbc800000, v84
	v_fmamk_f32 v135, v131, 0xbc800000, v82
	v_mul_f32_e32 v136, v136, v136
	v_mul_f32_e32 v134, v134, v134
	v_fmac_f32_e32 v136, v135, v135
	v_fmac_f32_e32 v134, v133, v133
	v_add_f32_e32 v133, v136, v134
	v_add_f32_e32 v132, v133, v132
	v_mov_b32_e32 v133, v132
	s_nop 1
	v_permlane16_swap_b32_e32 v132, v133
	s_waitcnt lgkmcnt(0)
	v_add_f32_e32 v132, v132, v133
	v_mov_b32_e32 v133, v132
	s_nop 1
	v_permlane32_swap_b32_e32 v132, v133
	s_and_saveexec_b64 s[0:1], vcc
	s_cbranch_execz .LBB0_1684
	s_lshl_b32 s3, s27, 11
	s_add_i32 s3, s2, s3
	v_mul_f32_e32 v134, 0x3c800000, v131
	s_waitcnt lgkmcnt(0)
	v_add_f32_e32 v135, v132, v133
	v_lshl_add_u32 v131, v146, 5, s3
	ds_write_b64 v131, v[134:135] offset:1024
.LBB0_1684:
	s_or_b64 exec, exec, s[0:1]
	s_waitcnt lgkmcnt(0)
	v_add_f32_e32 v132, v79, v78
	v_add_f32_e32 v133, v80, v81
	v_add_f32_e32 v134, v75, v74
	v_add_f32_e32 v135, v76, v77
	v_add_f32_e32 v131, v132, v133
	v_add_f32_e32 v135, v134, v135
	v_add_f32_e32 v134, v134, v134
	v_add_f32_e32 v133, 0, v131
	v_add_f32_e32 v137, v70, v71
	v_add_f32_e32 v139, v72, v73
	v_mov_b32_e32 v138, v67
	v_mov_b32_e32 v134, v68
	v_add_f32_e32 v136, v66, v67
	v_add_f32_e32 v137, v137, v139
	v_add_f32_e32 v132, v68, v69
	v_add_f32_e32 v133, v135, v133
	v_add_f32_e32 v132, v136, v132
	v_add_f32_e32 v133, v137, v133
	v_add_f32_e32 v131, v132, v133
	v_mov_b32_e32 v132, v131
	s_nop 1
	v_permlane16_swap_b32_e32 v131, v132
	s_waitcnt lgkmcnt(0)
	v_add_f32_e32 v131, v131, v132
	v_mov_b32_e32 v132, v131
	s_nop 1
	v_permlane32_swap_b32_e32 v131, v132
	s_waitcnt lgkmcnt(0)
	v_add_f32_e32 v131, v131, v132
	v_fmamk_f32 v133, v131, 0xbc800000, v81
	v_fmamk_f32 v135, v131, 0xbc800000, v79
	v_fmamk_f32 v132, v131, 0xbc800000, v80
	v_fmamk_f32 v134, v131, 0xbc800000, v78
	v_mul_f32_e32 v135, v135, v135
	v_mul_f32_e32 v133, v133, v133
	v_fmac_f32_e32 v135, v134, v134
	v_fmac_f32_e32 v133, v132, v132
	v_add_f32_e32 v132, v135, v133
	v_fmamk_f32 v134, v131, 0xbc800000, v77
	v_fmamk_f32 v136, v131, 0xbc800000, v75
	v_fmamk_f32 v133, v131, 0xbc800000, v76
	v_fmamk_f32 v135, v131, 0xbc800000, v74
	v_mul_f32_e32 v136, v136, v136
	v_mul_f32_e32 v134, v134, v134
	v_fmac_f32_e32 v136, v135, v135
	v_fmac_f32_e32 v134, v133, v133
	v_add_f32_e32 v133, v136, v134
	v_fmamk_f32 v134, v131, 0xbc800000, v73
	v_fmamk_f32 v136, v131, 0xbc800000, v71
	v_add_f32_e32 v132, v132, v133
	v_fmamk_f32 v133, v131, 0xbc800000, v72
	v_fmamk_f32 v135, v131, 0xbc800000, v70
	v_mul_f32_e32 v136, v136, v136
	v_mul_f32_e32 v134, v134, v134
	v_fmac_f32_e32 v136, v135, v135
	v_fmac_f32_e32 v134, v133, v133
	v_add_f32_e32 v133, v136, v134
	v_fmamk_f32 v134, v131, 0xbc800000, v69
	v_fmamk_f32 v136, v131, 0xbc800000, v67
	v_add_f32_e32 v132, v133, v132
	v_fmamk_f32 v133, v131, 0xbc800000, v68
	v_fmamk_f32 v135, v131, 0xbc800000, v66
	v_mul_f32_e32 v136, v136, v136
	v_mul_f32_e32 v134, v134, v134
	v_fmac_f32_e32 v136, v135, v135
	v_fmac_f32_e32 v134, v133, v133
	v_add_f32_e32 v133, v136, v134
	v_add_f32_e32 v132, v133, v132
	v_mov_b32_e32 v133, v132
	s_nop 1
	v_permlane16_swap_b32_e32 v132, v133
	s_waitcnt lgkmcnt(0)
	v_add_f32_e32 v132, v132, v133
	v_mov_b32_e32 v133, v132
	s_nop 1
	v_permlane32_swap_b32_e32 v132, v133
	s_and_saveexec_b64 s[0:1], vcc
	s_cbranch_execz .LBB0_1686
	s_lshl_b32 s3, s27, 11
	s_add_i32 s3, s2, s3
	v_mul_f32_e32 v134, 0x3c800000, v131
	s_waitcnt lgkmcnt(0)
	v_add_f32_e32 v135, v132, v133
	v_lshl_add_u32 v131, v146, 5, s3
	ds_write_b64 v131, v[134:135] offset:1536
.LBB0_1686:
	s_or_b64 exec, exec, s[0:1]
	s_waitcnt lgkmcnt(0)
	v_add_f32_e32 v132, v63, v62
	v_add_f32_e32 v133, v64, v65
	v_add_f32_e32 v134, v59, v58
	v_add_f32_e32 v135, v60, v61
	v_add_f32_e32 v131, v132, v133
	v_add_f32_e32 v135, v134, v135
	v_add_f32_e32 v134, v134, v134
	v_add_f32_e32 v133, 0, v131
	v_add_f32_e32 v137, v54, v55
	v_add_f32_e32 v139, v56, v57
	v_mov_b32_e32 v138, v51
	v_mov_b32_e32 v134, v52
	v_add_f32_e32 v136, v50, v51
	v_add_f32_e32 v137, v137, v139
	v_add_f32_e32 v132, v52, v53
	v_add_f32_e32 v133, v135, v133
	v_add_f32_e32 v132, v136, v132
	v_add_f32_e32 v133, v137, v133
	v_add_f32_e32 v131, v132, v133
	v_mov_b32_e32 v132, v131
	s_nop 1
	v_permlane16_swap_b32_e32 v131, v132
	s_waitcnt lgkmcnt(0)
	v_add_f32_e32 v131, v131, v132
	v_mov_b32_e32 v132, v131
	s_nop 1
	v_permlane32_swap_b32_e32 v131, v132
	s_waitcnt lgkmcnt(0)
	v_add_f32_e32 v131, v131, v132
	v_fmamk_f32 v133, v131, 0xbc800000, v65
	v_fmamk_f32 v135, v131, 0xbc800000, v63
	v_fmamk_f32 v132, v131, 0xbc800000, v64
	v_fmamk_f32 v134, v131, 0xbc800000, v62
	v_mul_f32_e32 v135, v135, v135
	v_mul_f32_e32 v133, v133, v133
	v_fmac_f32_e32 v135, v134, v134
	v_fmac_f32_e32 v133, v132, v132
	v_add_f32_e32 v132, v135, v133
	v_fmamk_f32 v134, v131, 0xbc800000, v61
	v_fmamk_f32 v136, v131, 0xbc800000, v59
	v_fmamk_f32 v133, v131, 0xbc800000, v60
	v_fmamk_f32 v135, v131, 0xbc800000, v58
	v_mul_f32_e32 v136, v136, v136
	v_mul_f32_e32 v134, v134, v134
	v_fmac_f32_e32 v136, v135, v135
	v_fmac_f32_e32 v134, v133, v133
	v_add_f32_e32 v133, v136, v134
	v_fmamk_f32 v134, v131, 0xbc800000, v57
	v_fmamk_f32 v136, v131, 0xbc800000, v55
	v_add_f32_e32 v132, v132, v133
	v_fmamk_f32 v133, v131, 0xbc800000, v56
	v_fmamk_f32 v135, v131, 0xbc800000, v54
	v_mul_f32_e32 v136, v136, v136
	v_mul_f32_e32 v134, v134, v134
	v_fmac_f32_e32 v136, v135, v135
	v_fmac_f32_e32 v134, v133, v133
	v_add_f32_e32 v133, v136, v134
	v_fmamk_f32 v134, v131, 0xbc800000, v53
	v_fmamk_f32 v136, v131, 0xbc800000, v51
	v_add_f32_e32 v132, v133, v132
	v_fmamk_f32 v133, v131, 0xbc800000, v52
	v_fmamk_f32 v135, v131, 0xbc800000, v50
	v_mul_f32_e32 v136, v136, v136
	v_mul_f32_e32 v134, v134, v134
	v_fmac_f32_e32 v136, v135, v135
	v_fmac_f32_e32 v134, v133, v133
	v_add_f32_e32 v133, v136, v134
	v_add_f32_e32 v132, v133, v132
	v_mov_b32_e32 v133, v132
	s_nop 1
	v_permlane16_swap_b32_e32 v132, v133
	s_waitcnt lgkmcnt(0)
	v_add_f32_e32 v132, v132, v133
	v_mov_b32_e32 v133, v132
	s_nop 1
	v_permlane32_swap_b32_e32 v132, v133
	s_and_saveexec_b64 s[0:1], vcc
	s_cbranch_execz .LBB0_1688
	s_lshl_b32 s3, s27, 11
	s_add_i32 s3, s2, s3
	v_mul_f32_e32 v134, 0x3c800000, v131
	s_waitcnt lgkmcnt(0)
	v_add_f32_e32 v135, v132, v133
	v_lshl_add_u32 v131, v146, 5, s3
	ds_write_b64 v131, v[134:135] offset:4096
.LBB0_1688:
	s_or_b64 exec, exec, s[0:1]
	s_waitcnt lgkmcnt(0)
	v_add_f32_e32 v132, v47, v46
	v_add_f32_e32 v133, v48, v49
	v_add_f32_e32 v134, v43, v42
	v_add_f32_e32 v135, v44, v45
	v_add_f32_e32 v131, v132, v133
	v_add_f32_e32 v135, v134, v135
	v_add_f32_e32 v134, v134, v134
	v_add_f32_e32 v133, 0, v131
	v_add_f32_e32 v137, v38, v39
	v_add_f32_e32 v139, v40, v41
	v_mov_b32_e32 v138, v35
	v_mov_b32_e32 v134, v36
	v_add_f32_e32 v136, v34, v35
	v_add_f32_e32 v137, v137, v139
	v_add_f32_e32 v132, v36, v37
	v_add_f32_e32 v133, v135, v133
	v_add_f32_e32 v132, v136, v132
	v_add_f32_e32 v133, v137, v133
	v_add_f32_e32 v131, v132, v133
	v_mov_b32_e32 v132, v131
	s_nop 1
	v_permlane16_swap_b32_e32 v131, v132
	s_waitcnt lgkmcnt(0)
	v_add_f32_e32 v131, v131, v132
	v_mov_b32_e32 v132, v131
	s_nop 1
	v_permlane32_swap_b32_e32 v131, v132
	s_waitcnt lgkmcnt(0)
	v_add_f32_e32 v131, v131, v132
	v_fmamk_f32 v133, v131, 0xbc800000, v49
	v_fmamk_f32 v135, v131, 0xbc800000, v47
	v_fmamk_f32 v132, v131, 0xbc800000, v48
	v_fmamk_f32 v134, v131, 0xbc800000, v46
	v_mul_f32_e32 v135, v135, v135
	v_mul_f32_e32 v133, v133, v133
	v_fmac_f32_e32 v135, v134, v134
	v_fmac_f32_e32 v133, v132, v132
	v_add_f32_e32 v132, v135, v133
	v_fmamk_f32 v134, v131, 0xbc800000, v45
	v_fmamk_f32 v136, v131, 0xbc800000, v43
	v_fmamk_f32 v133, v131, 0xbc800000, v44
	v_fmamk_f32 v135, v131, 0xbc800000, v42
	v_mul_f32_e32 v136, v136, v136
	v_mul_f32_e32 v134, v134, v134
	v_fmac_f32_e32 v136, v135, v135
	v_fmac_f32_e32 v134, v133, v133
	v_add_f32_e32 v133, v136, v134
	v_fmamk_f32 v134, v131, 0xbc800000, v41
	v_fmamk_f32 v136, v131, 0xbc800000, v39
	v_add_f32_e32 v132, v132, v133
	v_fmamk_f32 v133, v131, 0xbc800000, v40
	v_fmamk_f32 v135, v131, 0xbc800000, v38
	v_mul_f32_e32 v136, v136, v136
	v_mul_f32_e32 v134, v134, v134
	v_fmac_f32_e32 v136, v135, v135
	v_fmac_f32_e32 v134, v133, v133
	v_add_f32_e32 v133, v136, v134
	v_fmamk_f32 v134, v131, 0xbc800000, v37
	v_fmamk_f32 v136, v131, 0xbc800000, v35
	v_add_f32_e32 v132, v133, v132
	v_fmamk_f32 v133, v131, 0xbc800000, v36
	v_fmamk_f32 v135, v131, 0xbc800000, v34
	v_mul_f32_e32 v136, v136, v136
	v_mul_f32_e32 v134, v134, v134
	v_fmac_f32_e32 v136, v135, v135
	v_fmac_f32_e32 v134, v133, v133
	v_add_f32_e32 v133, v136, v134
	v_add_f32_e32 v132, v133, v132
	v_mov_b32_e32 v133, v132
	s_nop 1
	v_permlane16_swap_b32_e32 v132, v133
	s_waitcnt lgkmcnt(0)
	v_add_f32_e32 v132, v132, v133
	v_mov_b32_e32 v133, v132
	s_nop 1
	v_permlane32_swap_b32_e32 v132, v133
	s_and_saveexec_b64 s[0:1], vcc
	s_cbranch_execz .LBB0_1690
	s_lshl_b32 s3, s27, 11
	s_add_i32 s3, s2, s3
	v_mul_f32_e32 v134, 0x3c800000, v131
	s_waitcnt lgkmcnt(0)
	v_add_f32_e32 v135, v132, v133
	v_lshl_add_u32 v131, v146, 5, s3
	ds_write_b64 v131, v[134:135] offset:4608
.LBB0_1690:
	s_or_b64 exec, exec, s[0:1]
	s_waitcnt lgkmcnt(0)
	v_add_f32_e32 v132, v31, v30
	v_add_f32_e32 v133, v32, v33
	v_add_f32_e32 v134, v27, v26
	v_add_f32_e32 v135, v28, v29
	v_add_f32_e32 v131, v132, v133
	v_add_f32_e32 v135, v134, v135
	v_add_f32_e32 v134, v134, v134
	v_add_f32_e32 v133, 0, v131
	v_add_f32_e32 v137, v22, v23
	v_add_f32_e32 v139, v24, v25
	v_mov_b32_e32 v138, v19
	v_mov_b32_e32 v134, v20
	v_add_f32_e32 v136, v18, v19
	v_add_f32_e32 v137, v137, v139
	v_add_f32_e32 v132, v20, v21
	v_add_f32_e32 v133, v135, v133
	v_add_f32_e32 v132, v136, v132
	v_add_f32_e32 v133, v137, v133
	v_add_f32_e32 v131, v132, v133
	v_mov_b32_e32 v132, v131
	s_nop 1
	v_permlane16_swap_b32_e32 v131, v132
	s_waitcnt lgkmcnt(0)
	v_add_f32_e32 v131, v131, v132
	v_mov_b32_e32 v132, v131
	s_nop 1
	v_permlane32_swap_b32_e32 v131, v132
	s_waitcnt lgkmcnt(0)
	v_add_f32_e32 v131, v131, v132
	v_fmamk_f32 v133, v131, 0xbc800000, v33
	v_fmamk_f32 v135, v131, 0xbc800000, v31
	v_fmamk_f32 v132, v131, 0xbc800000, v32
	v_fmamk_f32 v134, v131, 0xbc800000, v30
	v_mul_f32_e32 v135, v135, v135
	v_mul_f32_e32 v133, v133, v133
	v_fmac_f32_e32 v135, v134, v134
	v_fmac_f32_e32 v133, v132, v132
	v_add_f32_e32 v132, v135, v133
	v_fmamk_f32 v134, v131, 0xbc800000, v29
	v_fmamk_f32 v136, v131, 0xbc800000, v27
	v_fmamk_f32 v133, v131, 0xbc800000, v28
	v_fmamk_f32 v135, v131, 0xbc800000, v26
	v_mul_f32_e32 v136, v136, v136
	v_mul_f32_e32 v134, v134, v134
	v_fmac_f32_e32 v136, v135, v135
	v_fmac_f32_e32 v134, v133, v133
	v_add_f32_e32 v133, v136, v134
	v_fmamk_f32 v134, v131, 0xbc800000, v25
	v_fmamk_f32 v136, v131, 0xbc800000, v23
	v_add_f32_e32 v132, v132, v133
	v_fmamk_f32 v133, v131, 0xbc800000, v24
	v_fmamk_f32 v135, v131, 0xbc800000, v22
	v_mul_f32_e32 v136, v136, v136
	v_mul_f32_e32 v134, v134, v134
	v_fmac_f32_e32 v136, v135, v135
	v_fmac_f32_e32 v134, v133, v133
	v_add_f32_e32 v133, v136, v134
	v_fmamk_f32 v134, v131, 0xbc800000, v21
	v_fmamk_f32 v136, v131, 0xbc800000, v19
	v_add_f32_e32 v132, v133, v132
	v_fmamk_f32 v133, v131, 0xbc800000, v20
	v_fmamk_f32 v135, v131, 0xbc800000, v18
	v_mul_f32_e32 v136, v136, v136
	v_mul_f32_e32 v134, v134, v134
	v_fmac_f32_e32 v136, v135, v135
	v_fmac_f32_e32 v134, v133, v133
	v_add_f32_e32 v133, v136, v134
	v_add_f32_e32 v132, v133, v132
	v_mov_b32_e32 v133, v132
	s_nop 1
	v_permlane16_swap_b32_e32 v132, v133
	s_waitcnt lgkmcnt(0)
	v_add_f32_e32 v132, v132, v133
	v_mov_b32_e32 v133, v132
	s_nop 1
	v_permlane32_swap_b32_e32 v132, v133
	s_and_saveexec_b64 s[0:1], vcc
	s_cbranch_execz .LBB0_1692
	s_lshl_b32 s3, s27, 11
	s_add_i32 s3, s2, s3
	v_mul_f32_e32 v134, 0x3c800000, v131
	s_waitcnt lgkmcnt(0)
	v_add_f32_e32 v135, v132, v133
	v_lshl_add_u32 v131, v146, 5, s3
	ds_write_b64 v131, v[134:135] offset:5120
.LBB0_1692:
	s_or_b64 exec, exec, s[0:1]
	s_waitcnt lgkmcnt(0)
	v_add_f32_e32 v132, v15, v14
	v_add_f32_e32 v133, v16, v17
	v_add_f32_e32 v134, v11, v10
	v_add_f32_e32 v135, v12, v13
	v_add_f32_e32 v131, v132, v133
	v_add_f32_e32 v135, v134, v135
	v_add_f32_e32 v134, v134, v134
	v_add_f32_e32 v133, 0, v131
	v_add_f32_e32 v137, v6, v7
	v_add_f32_e32 v139, v8, v9
	v_mov_b32_e32 v138, v3
	v_mov_b32_e32 v134, v4
	v_add_f32_e32 v136, v2, v3
	v_add_f32_e32 v137, v137, v139
	v_add_f32_e32 v132, v4, v5
	v_add_f32_e32 v133, v135, v133
	v_add_f32_e32 v132, v136, v132
	v_add_f32_e32 v133, v137, v133
	v_add_f32_e32 v131, v132, v133
	v_mov_b32_e32 v132, v131
	s_nop 1
	v_permlane16_swap_b32_e32 v131, v132
	s_waitcnt lgkmcnt(0)
	v_add_f32_e32 v131, v131, v132
	v_mov_b32_e32 v132, v131
	s_nop 1
	v_permlane32_swap_b32_e32 v131, v132
	s_waitcnt lgkmcnt(0)
	v_add_f32_e32 v131, v131, v132
	v_fmamk_f32 v133, v131, 0xbc800000, v17
	v_fmamk_f32 v135, v131, 0xbc800000, v15
	v_fmamk_f32 v132, v131, 0xbc800000, v16
	v_fmamk_f32 v134, v131, 0xbc800000, v14
	v_mul_f32_e32 v135, v135, v135
	v_mul_f32_e32 v133, v133, v133
	v_fmac_f32_e32 v135, v134, v134
	v_fmac_f32_e32 v133, v132, v132
	v_add_f32_e32 v132, v135, v133
	v_fmamk_f32 v134, v131, 0xbc800000, v13
	v_fmamk_f32 v136, v131, 0xbc800000, v11
	v_fmamk_f32 v133, v131, 0xbc800000, v12
	v_fmamk_f32 v135, v131, 0xbc800000, v10
	v_mul_f32_e32 v136, v136, v136
	v_mul_f32_e32 v134, v134, v134
	v_fmac_f32_e32 v136, v135, v135
	v_fmac_f32_e32 v134, v133, v133
	v_add_f32_e32 v133, v136, v134
	v_fmamk_f32 v134, v131, 0xbc800000, v9
	v_fmamk_f32 v136, v131, 0xbc800000, v7
	v_add_f32_e32 v132, v132, v133
	v_fmamk_f32 v133, v131, 0xbc800000, v8
	v_fmamk_f32 v135, v131, 0xbc800000, v6
	v_mul_f32_e32 v136, v136, v136
	v_mul_f32_e32 v134, v134, v134
	v_fmac_f32_e32 v136, v135, v135
	v_fmac_f32_e32 v134, v133, v133
	v_add_f32_e32 v133, v136, v134
	v_fmamk_f32 v134, v131, 0xbc800000, v5
	v_fmamk_f32 v136, v131, 0xbc800000, v3
	v_add_f32_e32 v132, v133, v132
	v_fmamk_f32 v133, v131, 0xbc800000, v4
	v_fmamk_f32 v135, v131, 0xbc800000, v2
	v_mul_f32_e32 v136, v136, v136
	v_mul_f32_e32 v134, v134, v134
	v_fmac_f32_e32 v136, v135, v135
	v_fmac_f32_e32 v134, v133, v133
	v_add_f32_e32 v133, v136, v134
	v_add_f32_e32 v132, v133, v132
	v_mov_b32_e32 v1, v132
	s_nop 1
	v_permlane16_swap_b32_e32 v132, v1
	s_waitcnt lgkmcnt(0)
	v_add_f32_e32 v1, v132, v1
	v_mov_b32_e32 v132, v1
	s_nop 1
	v_permlane32_swap_b32_e32 v1, v132
	s_and_saveexec_b64 s[0:1], vcc
	s_cbranch_execz .LBB0_1694
	s_lshl_b32 s3, s27, 11
	s_add_i32 s2, s2, s3
	v_mul_f32_e32 v134, 0x3c800000, v131
	s_waitcnt lgkmcnt(0)
	v_add_f32_e32 v135, v1, v132
	v_lshl_add_u32 v1, v146, 5, s2
	ds_write_b64 v1, v[134:135] offset:5632
